# MLP-up epilogue: removed/fused canonicalizing v_max x,x before relu (316 VALU), on top of v17
# baseline (speedup 1.0000x reference)
; DI u32x4 pack_v8(f32x4 v0, f32x4 v1) { u32x4 w; w.x = pk2(v0[0], v0[1]); w.y = pk2(v0[2], v0[3]); w.z = pk2(v1[0], v1[1]); w.w = pk2(v1[2], v1[3]); return w; }
; DI float rstd16(const float* ssq, int row) { const f32x4* p = (const f32x4*)(ssq + (size_t)row * 16); const f32x4 a = p[0], b = p[1], c = p[2], d = p[3];
;   return __builtin_amdgcn_rsqf((((a[0] + a[1]) + (a[2] + a[3])) + ((b[0] + b[1]) + (b[2] + b[3])) + ((c[0] + c[1]) + (c[2] + c[3])) + ((d[0] + d[1]) + (d[2] + d[3]))) * (1.0f / 1024.0f) + EPS); }
;   DI void operator()(AccRef acc, const Unit& u, int wr, int wc, int fr, int fq) const {
;     ...
;       for (int m = 0; m < 4; ++m) { const int row = rowb + ai * 128 + m * 16; const float rs = rstd16(SSQH, row);
; #pragma unroll
;         for (int bj = 0; bj < 2; ++bj) { f32x4 v0 = acc[ai][bj][m][0], v1 = acc[ai][bj][m][1];
; #pragma unroll
;           for (int j = 0; j < 4; ++j) { const float a = fmaxf(v0[j], 0.f) * rs, b = fmaxf(v1[j], 0.f) * rs; v0[j] = a * a; v1[j] = b * b; }
;           *(u32x4*)(A2 + (size_t)row * DFF + cb + bj * 128) = pack_v8(v0, v1); } }
.LBB0_899:
	s_lshl_b32 s15, s24, 8
	v_mov_b32_e32 v151, v224
	s_add_i32 s15, s15, s42
	v_and_or_b32 v144, v151, 15, s15
	v_ashrrev_i32_e32 v145, 31, v144
	v_lshlrev_b64 v[152:153], 6, v[144:145]
	v_lshl_add_u64 v[164:165], s[60:61], 0, v[152:153]
	global_load_dwordx4 v[152:155], v[164:165], off
	global_load_dwordx4 v[156:159], v[164:165], off offset:16
	global_load_dwordx4 v[160:163], v[164:165], off offset:32
	s_nop 0
	global_load_dwordx4 v[164:167], v[164:165], off offset:48
	v_max_f32_e32 v169, v117, v117
	v_max_f32_e32 v172, v119, v119
	v_max_f32_e32 v117, 0, v121
	v_max_f32_e32 v119, 0, v127
	v_max_f32_e32 v121, 0, v123
	v_max_f32_e32 v123, 0, v169
	v_max_f32_e32 v127, 0, v172
	v_max_f32_e32 v169, 0, v115
	v_lshlrev_b64 v[172:173], 13, v[144:145]
	s_lshl_b32 s15, s64, 8
	v_max_f32_e32 v171, v114, v114
	v_max_f32_e32 v114, 0, v124
	v_max_f32_e32 v124, 0, v112
	v_lshrrev_b32_e32 v112, 1, v151
	v_and_or_b32 v112, v112, 24, s15
	v_max_f32_e32 v168, v116, v116
	v_max_f32_e32 v170, v118, v118
	v_max_f32_e32 v116, 0, v120
	v_max_f32_e32 v115, 0, v125
	v_max_f32_e32 v118, 0, v126
	v_max_f32_e32 v120, 0, v122
	v_or_b32_e32 v112, s43, v112
	v_max_f32_e32 v122, 0, v168
	v_max_f32_e32 v125, 0, v113
	v_max_f32_e32 v126, 0, v170
	v_max_f32_e32 v168, 0, v171
	v_ashrrev_i32_e32 v113, 31, v112
	v_or_b32_e32 v170, 16, v144
	v_lshlrev_b64 v[112:113], 1, v[112:113]
	v_ashrrev_i32_e32 v171, 31, v170
	v_max_f32_e32 v151, v97, v97
	v_max_f32_e32 v97, 0, v109
	s_waitcnt vmcnt(0) lgkmcnt(0)
	v_mov_b32_e32 v174, v153
	v_mov_b32_e32 v175, v154
	v_mov_b32_e32 v153, v155
	v_mov_b32_e32 v154, v157
	v_mov_b32_e32 v155, v158
	v_mov_b32_e32 v157, v159
	v_pk_add_f32 v[152:153], v[174:175], v[152:153]
	v_pk_add_f32 v[154:155], v[154:155], v[156:157]
	v_pk_add_f32 v[152:153], v[152:153], v[152:153] op_sel:[0,1] op_sel_hi:[1,0]
	v_pk_add_f32 v[154:155], v[154:155], v[154:155] op_sel:[0,1] op_sel_hi:[1,0]
	v_add_f32_e32 v158, v160, v161
	v_add_f32_e32 v160, v162, v163
	v_mov_b32_e32 v159, v166
	v_mov_b32_e32 v161, v167
	v_mov_b32_e32 v153, v164
	v_mov_b32_e32 v155, v165
	v_pk_add_f32 v[156:157], v[158:159], v[160:161]
	v_pk_add_f32 v[152:153], v[152:153], v[154:155]
	v_lshl_add_u64 v[154:155], s[52:53], 0, v[172:173]
	v_pk_add_f32 v[152:153], v[152:153], v[156:157]
	v_lshl_add_u64 v[154:155], v[154:155], 0, v[112:113]
	v_add_f32_e32 v145, v152, v153
	v_fmamk_f32 v145, v145, 0x3a800000, v150
	v_rsq_f32_e32 v152, v145
	v_max_f32_e32 v145, v101, v101
	v_max_f32_e32 v156, v102, v102
	v_max_f32_e32 v157, v98, v98
	v_pk_mul_f32 v[114:115], v[114:115], v[152:153] op_sel_hi:[1,0]
	v_pk_mul_f32 v[116:117], v[116:117], v[152:153] op_sel_hi:[1,0]
	v_pk_mul_f32 v[118:119], v[118:119], v[152:153] op_sel_hi:[1,0]
	v_pk_mul_f32 v[120:121], v[120:121], v[152:153] op_sel_hi:[1,0]
	v_pk_mul_f32 v[122:123], v[122:123], v[152:153] op_sel_hi:[1,0]
	v_pk_mul_f32 v[124:125], v[124:125], v[152:153] op_sel_hi:[1,0]
	v_pk_mul_f32 v[126:127], v[126:127], v[152:153] op_sel_hi:[1,0]
	v_pk_mul_f32 v[152:153], v[168:169], v[152:153] op_sel_hi:[1,0]
	v_pk_mul_f32 v[114:115], v[114:115], v[114:115]
	v_pk_mul_f32 v[116:117], v[116:117], v[116:117]
	v_pk_mul_f32 v[118:119], v[118:119], v[118:119]
	v_pk_mul_f32 v[120:121], v[120:121], v[120:121]
	v_pk_mul_f32 v[122:123], v[122:123], v[122:123]
	v_pk_mul_f32 v[124:125], v[124:125], v[124:125]
	v_pk_mul_f32 v[126:127], v[126:127], v[126:127]
	v_pk_mul_f32 v[152:153], v[152:153], v[152:153]
	v_cvt_pk_bf16_f32 v114, v114, v115
	v_cvt_pk_bf16_f32 v115, v118, v119
	v_cvt_pk_bf16_f32 v116, v116, v117
	v_cvt_pk_bf16_f32 v117, v120, v121
	v_cvt_pk_bf16_f32 v118, v122, v123
	v_cvt_pk_bf16_f32 v119, v126, v127
	v_cvt_pk_bf16_f32 v120, v124, v125
	v_cvt_pk_bf16_f32 v121, v152, v153
	global_store_dwordx4 v[154:155], v[114:117], off
	global_store_dwordx4 v[154:155], v[118:121], off offset:256
	v_max_f32_e32 v158, v103, v103
	v_lshlrev_b64 v[114:115], 6, v[170:171]
	v_lshl_add_u64 v[126:127], s[60:61], 0, v[114:115]
	global_load_dwordx4 v[114:117], v[126:127], off
	global_load_dwordx4 v[118:121], v[126:127], off offset:16
	global_load_dwordx4 v[122:125], v[126:127], off offset:32
	global_load_dwordx4 v[152:155], v[126:127], off offset:48
	v_max_f32_e32 v126, v100, v100
	v_max_f32_e32 v127, v96, v96
	v_max_f32_e32 v159, v99, v99
	v_max_f32_e32 v96, 0, v108
	v_max_f32_e32 v98, 0, v104
	v_max_f32_e32 v99, 0, v105
	v_max_f32_e32 v100, 0, v110
	v_max_f32_e32 v102, 0, v106
	v_max_f32_e32 v101, 0, v111
	v_max_f32_e32 v103, 0, v107
	v_max_f32_e32 v104, 0, v126
	v_max_f32_e32 v106, 0, v127
	v_max_f32_e32 v105, 0, v145
	v_max_f32_e32 v107, 0, v151
	v_max_f32_e32 v108, 0, v156
	v_max_f32_e32 v110, 0, v157
	v_max_f32_e32 v109, 0, v158
	v_max_f32_e32 v111, 0, v159
	v_or_b32_e32 v126, 32, v144
	v_lshlrev_b64 v[156:157], 13, v[170:171]
	v_ashrrev_i32_e32 v127, 31, v126
	v_lshlrev_b64 v[158:159], 6, v[126:127]
	s_andn2_b64 vcc, exec, s[4:5]
	s_mov_b64 s[4:5], -1
	s_waitcnt vmcnt(0) lgkmcnt(0)
; DI u32x4 pack_v8(f32x4 v0, f32x4 v1) { u32x4 w; w.x = pk2(v0[0], v0[1]); w.y = pk2(v0[2], v0[3]); w.z = pk2(v1[0], v1[1]); w.w = pk2(v1[2], v1[3]); return w; }
; DI float rstd16(const float* ssq, int row) { const f32x4* p = (const f32x4*)(ssq + (size_t)row * 16); const f32x4 a = p[0], b = p[1], c = p[2], d = p[3];
;   return __builtin_amdgcn_rsqf((((a[0] + a[1]) + (a[2] + a[3])) + ((b[0] + b[1]) + (b[2] + b[3])) + ((c[0] + c[1]) + (c[2] + c[3])) + ((d[0] + d[1]) + (d[2] + d[3]))) * (1.0f / 1024.0f) + EPS); }
;   DI void operator()(AccRef acc, const Unit& u, int wr, int wc, int fr, int fq) const {
;     ...
;       for (int m = 0; m < 4; ++m) { const int row = rowb + ai * 128 + m * 16; const float rs = rstd16(SSQH, row);
; #pragma unroll
;         for (int bj = 0; bj < 2; ++bj) { f32x4 v0 = acc[ai][bj][m][0], v1 = acc[ai][bj][m][1];
; #pragma unroll
;           for (int j = 0; j < 4; ++j) { const float a = fmaxf(v0[j], 0.f) * rs, b = fmaxf(v1[j], 0.f) * rs; v0[j] = a * a; v1[j] = b * b; }
;           *(u32x4*)(A2 + (size_t)row * DFF + cb + bj * 128) = pack_v8(v0, v1); } }
	v_mov_b32_e32 v160, v115
	v_mov_b32_e32 v161, v116
	v_mov_b32_e32 v115, v117
	v_mov_b32_e32 v116, v119
	v_mov_b32_e32 v117, v120
	v_mov_b32_e32 v119, v121
	v_pk_add_f32 v[114:115], v[160:161], v[114:115]
	v_pk_add_f32 v[116:117], v[116:117], v[118:119]
	v_pk_add_f32 v[114:115], v[114:115], v[114:115] op_sel:[0,1] op_sel_hi:[1,0]
	v_pk_add_f32 v[116:117], v[116:117], v[116:117] op_sel:[0,1] op_sel_hi:[1,0]
	v_add_f32_e32 v120, v122, v123
	v_add_f32_e32 v122, v124, v125
	v_mov_b32_e32 v121, v154
	v_mov_b32_e32 v123, v155
	v_mov_b32_e32 v115, v152
	v_mov_b32_e32 v117, v153
	v_pk_add_f32 v[118:119], v[120:121], v[122:123]
	v_pk_add_f32 v[114:115], v[114:115], v[116:117]
	v_lshl_add_u64 v[116:117], s[52:53], 0, v[156:157]
	v_pk_add_f32 v[114:115], v[114:115], v[118:119]
	v_lshl_add_u64 v[116:117], v[116:117], 0, v[112:113]
	v_add_f32_e32 v114, v114, v115
	v_fmamk_f32 v114, v114, 0x3a800000, v150
	v_rsq_f32_e32 v114, v114
	v_lshl_add_u64 v[118:119], s[60:61], 0, v[158:159]
	v_pk_mul_f32 v[96:97], v[96:97], v[114:115] op_sel_hi:[1,0]
	v_pk_mul_f32 v[98:99], v[98:99], v[114:115] op_sel_hi:[1,0]
	v_pk_mul_f32 v[100:101], v[100:101], v[114:115] op_sel_hi:[1,0]
	v_pk_mul_f32 v[102:103], v[102:103], v[114:115] op_sel_hi:[1,0]
	v_pk_mul_f32 v[104:105], v[104:105], v[114:115] op_sel_hi:[1,0]
	v_pk_mul_f32 v[106:107], v[106:107], v[114:115] op_sel_hi:[1,0]
	v_pk_mul_f32 v[108:109], v[108:109], v[114:115] op_sel_hi:[1,0]
	v_pk_mul_f32 v[110:111], v[110:111], v[114:115] op_sel_hi:[1,0]
	v_pk_mul_f32 v[96:97], v[96:97], v[96:97]
	v_pk_mul_f32 v[98:99], v[98:99], v[98:99]
	v_pk_mul_f32 v[100:101], v[100:101], v[100:101]
	v_pk_mul_f32 v[102:103], v[102:103], v[102:103]
	v_pk_mul_f32 v[104:105], v[104:105], v[104:105]
	v_pk_mul_f32 v[106:107], v[106:107], v[106:107]
	v_pk_mul_f32 v[108:109], v[108:109], v[108:109]
	v_pk_mul_f32 v[110:111], v[110:111], v[110:111]
	v_cvt_pk_bf16_f32 v96, v96, v97
	v_cvt_pk_bf16_f32 v97, v100, v101
	v_cvt_pk_bf16_f32 v98, v98, v99
	v_cvt_pk_bf16_f32 v99, v102, v103
	v_cvt_pk_bf16_f32 v100, v104, v105
	v_cvt_pk_bf16_f32 v101, v108, v109
	v_cvt_pk_bf16_f32 v102, v106, v107
	v_cvt_pk_bf16_f32 v103, v110, v111
	global_store_dwordx4 v[116:117], v[96:99], off
	s_nop 0
	global_store_dwordx4 v[116:117], v[100:103], off offset:256
	global_load_dwordx4 v[96:99], v[118:119], off
	s_nop 0
	global_load_dwordx4 v[100:103], v[118:119], off offset:16
	global_load_dwordx4 v[104:107], v[118:119], off offset:32
	global_load_dwordx4 v[108:111], v[118:119], off offset:48
	v_max_f32_e32 v116, v85, v85
	v_max_f32_e32 v117, v81, v81
	v_max_f32_e32 v81, 0, v93
	v_max_f32_e32 v85, 0, v95
	v_max_f32_e32 v93, 0, v87
	v_max_f32_e32 v95, 0, v83
	v_max_f32_e32 v114, v84, v84
	v_max_f32_e32 v115, v80, v80
	v_max_f32_e32 v118, v86, v86
	v_max_f32_e32 v119, v82, v82
	v_max_f32_e32 v80, 0, v92
	v_max_f32_e32 v82, 0, v88
	v_max_f32_e32 v83, 0, v89
	v_max_f32_e32 v84, 0, v94
	v_max_f32_e32 v86, 0, v90
	v_max_f32_e32 v87, 0, v91
	v_max_f32_e32 v88, 0, v114
	v_max_f32_e32 v90, 0, v115
	v_max_f32_e32 v89, 0, v116
	v_max_f32_e32 v91, 0, v117
	v_max_f32_e32 v92, 0, v118
	v_max_f32_e32 v94, 0, v119
	v_or_b32_e32 v114, 48, v144
	v_lshlrev_b64 v[116:117], 13, v[126:127]
	v_ashrrev_i32_e32 v115, 31, v114
	v_lshlrev_b64 v[118:119], 6, v[114:115]
	s_waitcnt vmcnt(0) lgkmcnt(0)
	v_mov_b32_e32 v120, v97
	v_mov_b32_e32 v121, v98
	v_mov_b32_e32 v97, v99
	v_mov_b32_e32 v98, v101
	v_mov_b32_e32 v99, v102
	v_mov_b32_e32 v101, v103
	v_pk_add_f32 v[96:97], v[120:121], v[96:97]
	v_pk_add_f32 v[98:99], v[98:99], v[100:101]
	v_pk_add_f32 v[96:97], v[96:97], v[96:97] op_sel:[0,1] op_sel_hi:[1,0]
	v_pk_add_f32 v[98:99], v[98:99], v[98:99] op_sel:[0,1] op_sel_hi:[1,0]
	v_add_f32_e32 v102, v104, v105
	v_add_f32_e32 v104, v106, v107
	v_mov_b32_e32 v103, v110
	v_mov_b32_e32 v105, v111
	v_mov_b32_e32 v97, v108
	v_mov_b32_e32 v99, v109
	v_pk_add_f32 v[100:101], v[102:103], v[104:105]
	v_pk_add_f32 v[96:97], v[96:97], v[98:99]
	v_lshl_add_u64 v[98:99], s[52:53], 0, v[116:117]
	v_pk_add_f32 v[96:97], v[96:97], v[100:101]
	v_lshl_add_u64 v[98:99], v[98:99], 0, v[112:113]
	v_add_f32_e32 v96, v96, v97
	v_fmamk_f32 v96, v96, 0x3a800000, v150
	v_rsq_f32_e32 v96, v96
	v_lshl_add_u64 v[100:101], s[60:61], 0, v[118:119]
	v_pk_mul_f32 v[80:81], v[80:81], v[96:97] op_sel_hi:[1,0]
	v_pk_mul_f32 v[82:83], v[82:83], v[96:97] op_sel_hi:[1,0]
	v_pk_mul_f32 v[84:85], v[84:85], v[96:97] op_sel_hi:[1,0]
	v_pk_mul_f32 v[86:87], v[86:87], v[96:97] op_sel_hi:[1,0]
	v_pk_mul_f32 v[88:89], v[88:89], v[96:97] op_sel_hi:[1,0]
	v_pk_mul_f32 v[90:91], v[90:91], v[96:97] op_sel_hi:[1,0]
	v_pk_mul_f32 v[92:93], v[92:93], v[96:97] op_sel_hi:[1,0]
	v_pk_mul_f32 v[94:95], v[94:95], v[96:97] op_sel_hi:[1,0]
	v_pk_mul_f32 v[80:81], v[80:81], v[80:81]
	v_pk_mul_f32 v[82:83], v[82:83], v[82:83]
	v_pk_mul_f32 v[84:85], v[84:85], v[84:85]
	v_pk_mul_f32 v[86:87], v[86:87], v[86:87]
	v_pk_mul_f32 v[88:89], v[88:89], v[88:89]
	v_pk_mul_f32 v[90:91], v[90:91], v[90:91]
	v_pk_mul_f32 v[92:93], v[92:93], v[92:93]
	v_pk_mul_f32 v[94:95], v[94:95], v[94:95]
	v_cvt_pk_bf16_f32 v80, v80, v81
	v_cvt_pk_bf16_f32 v81, v84, v85
	v_cvt_pk_bf16_f32 v82, v82, v83
	v_cvt_pk_bf16_f32 v83, v86, v87
	v_cvt_pk_bf16_f32 v84, v88, v89
	v_cvt_pk_bf16_f32 v85, v92, v93
	v_cvt_pk_bf16_f32 v86, v90, v91
	v_cvt_pk_bf16_f32 v87, v94, v95
	global_store_dwordx4 v[98:99], v[80:83], off
	s_nop 0
	global_store_dwordx4 v[98:99], v[84:87], off offset:256
	global_load_dwordx4 v[80:83], v[100:101], off
	s_nop 0
	global_load_dwordx4 v[84:87], v[100:101], off offset:16
	global_load_dwordx4 v[88:91], v[100:101], off offset:32
	global_load_dwordx4 v[92:95], v[100:101], off offset:48
	v_max_f32_e32 v98, v69, v69
	v_max_f32_e32 v99, v65, v65
	v_max_f32_e32 v65, 0, v77
	v_max_f32_e32 v69, 0, v79
	v_max_f32_e32 v77, 0, v71
	v_max_f32_e32 v79, 0, v67
	v_max_f32_e32 v96, v68, v68
	v_max_f32_e32 v97, v64, v64
	v_max_f32_e32 v100, v70, v70
	v_max_f32_e32 v101, v66, v66
	v_max_f32_e32 v64, 0, v76
	v_max_f32_e32 v66, 0, v72
	v_max_f32_e32 v67, 0, v73
	v_max_f32_e32 v68, 0, v78
	v_max_f32_e32 v70, 0, v74
	v_max_f32_e32 v71, 0, v75
	v_max_f32_e32 v72, 0, v96
	v_max_f32_e32 v74, 0, v97
	v_max_f32_e32 v73, 0, v98
	v_max_f32_e32 v75, 0, v99
	v_max_f32_e32 v76, 0, v100
	v_max_f32_e32 v78, 0, v101
	v_add_u32_e32 v96, 0x80, v144
	v_lshlrev_b64 v[98:99], 13, v[114:115]
	v_ashrrev_i32_e32 v97, 31, v96
	v_lshlrev_b64 v[100:101], 6, v[96:97]
	s_waitcnt vmcnt(0) lgkmcnt(0)
; DI u32x4 pack_v8(f32x4 v0, f32x4 v1) { u32x4 w; w.x = pk2(v0[0], v0[1]); w.y = pk2(v0[2], v0[3]); w.z = pk2(v1[0], v1[1]); w.w = pk2(v1[2], v1[3]); return w; }
; DI float rstd16(const float* ssq, int row) { const f32x4* p = (const f32x4*)(ssq + (size_t)row * 16); const f32x4 a = p[0], b = p[1], c = p[2], d = p[3];
;   return __builtin_amdgcn_rsqf((((a[0] + a[1]) + (a[2] + a[3])) + ((b[0] + b[1]) + (b[2] + b[3])) + ((c[0] + c[1]) + (c[2] + c[3])) + ((d[0] + d[1]) + (d[2] + d[3]))) * (1.0f / 1024.0f) + EPS); }
;   DI void operator()(AccRef acc, const Unit& u, int wr, int wc, int fr, int fq) const {
;     ...
;       for (int m = 0; m < 4; ++m) { const int row = rowb + ai * 128 + m * 16; const float rs = rstd16(SSQH, row);
; #pragma unroll
;         for (int bj = 0; bj < 2; ++bj) { f32x4 v0 = acc[ai][bj][m][0], v1 = acc[ai][bj][m][1];
; #pragma unroll
;           for (int j = 0; j < 4; ++j) { const float a = fmaxf(v0[j], 0.f) * rs, b = fmaxf(v1[j], 0.f) * rs; v0[j] = a * a; v1[j] = b * b; }
;           *(u32x4*)(A2 + (size_t)row * DFF + cb + bj * 128) = pack_v8(v0, v1); } }
	v_mov_b32_e32 v102, v81
	v_mov_b32_e32 v103, v82
	v_mov_b32_e32 v81, v83
	v_mov_b32_e32 v82, v85
	v_mov_b32_e32 v83, v86
	v_mov_b32_e32 v85, v87
	v_pk_add_f32 v[80:81], v[102:103], v[80:81]
	v_pk_add_f32 v[82:83], v[82:83], v[84:85]
	v_pk_add_f32 v[80:81], v[80:81], v[80:81] op_sel:[0,1] op_sel_hi:[1,0]
	v_pk_add_f32 v[82:83], v[82:83], v[82:83] op_sel:[0,1] op_sel_hi:[1,0]
	v_add_f32_e32 v86, v88, v89
	v_add_f32_e32 v88, v90, v91
	v_mov_b32_e32 v87, v94
	v_mov_b32_e32 v89, v95
	v_mov_b32_e32 v81, v92
	v_mov_b32_e32 v83, v93
	v_pk_add_f32 v[84:85], v[86:87], v[88:89]
	v_pk_add_f32 v[80:81], v[80:81], v[82:83]
	v_lshl_add_u64 v[82:83], s[52:53], 0, v[98:99]
	v_pk_add_f32 v[80:81], v[80:81], v[84:85]
	v_lshl_add_u64 v[82:83], v[82:83], 0, v[112:113]
	v_add_f32_e32 v80, v80, v81
	v_fmamk_f32 v80, v80, 0x3a800000, v150
	v_rsq_f32_e32 v80, v80
	v_lshl_add_u64 v[84:85], s[60:61], 0, v[100:101]
	v_pk_mul_f32 v[64:65], v[64:65], v[80:81] op_sel_hi:[1,0]
	v_pk_mul_f32 v[66:67], v[66:67], v[80:81] op_sel_hi:[1,0]
	v_pk_mul_f32 v[68:69], v[68:69], v[80:81] op_sel_hi:[1,0]
	v_pk_mul_f32 v[70:71], v[70:71], v[80:81] op_sel_hi:[1,0]
	v_pk_mul_f32 v[72:73], v[72:73], v[80:81] op_sel_hi:[1,0]
	v_pk_mul_f32 v[74:75], v[74:75], v[80:81] op_sel_hi:[1,0]
	v_pk_mul_f32 v[76:77], v[76:77], v[80:81] op_sel_hi:[1,0]
	v_pk_mul_f32 v[78:79], v[78:79], v[80:81] op_sel_hi:[1,0]
	v_pk_mul_f32 v[64:65], v[64:65], v[64:65]
	v_pk_mul_f32 v[66:67], v[66:67], v[66:67]
	v_pk_mul_f32 v[68:69], v[68:69], v[68:69]
	v_pk_mul_f32 v[70:71], v[70:71], v[70:71]
	v_pk_mul_f32 v[72:73], v[72:73], v[72:73]
	v_pk_mul_f32 v[74:75], v[74:75], v[74:75]
	v_pk_mul_f32 v[76:77], v[76:77], v[76:77]
	v_pk_mul_f32 v[78:79], v[78:79], v[78:79]
	v_cvt_pk_bf16_f32 v64, v64, v65
	v_cvt_pk_bf16_f32 v65, v68, v69
	v_cvt_pk_bf16_f32 v66, v66, v67
	v_cvt_pk_bf16_f32 v67, v70, v71
	v_cvt_pk_bf16_f32 v68, v72, v73
	v_cvt_pk_bf16_f32 v69, v76, v77
	v_cvt_pk_bf16_f32 v70, v74, v75
	v_cvt_pk_bf16_f32 v71, v78, v79
	global_store_dwordx4 v[82:83], v[64:67], off
	s_nop 0
	global_store_dwordx4 v[82:83], v[68:71], off offset:256
	global_load_dwordx4 v[64:67], v[84:85], off
	s_nop 0
	global_load_dwordx4 v[68:71], v[84:85], off offset:16
	global_load_dwordx4 v[72:75], v[84:85], off offset:32
	global_load_dwordx4 v[76:79], v[84:85], off offset:48
	v_max_f32_e32 v82, v53, v53
	v_max_f32_e32 v83, v49, v49
	v_max_f32_e32 v49, 0, v61
	v_max_f32_e32 v53, 0, v63
	v_max_f32_e32 v61, 0, v55
	v_max_f32_e32 v63, 0, v51
	v_max_f32_e32 v80, v52, v52
	v_max_f32_e32 v81, v48, v48
	v_max_f32_e32 v84, v54, v54
	v_max_f32_e32 v85, v50, v50
	v_max_f32_e32 v48, 0, v60
	v_max_f32_e32 v50, 0, v56
	v_max_f32_e32 v51, 0, v57
	v_max_f32_e32 v52, 0, v62
	v_max_f32_e32 v54, 0, v58
	v_max_f32_e32 v55, 0, v59
	v_max_f32_e32 v56, 0, v80
	v_max_f32_e32 v58, 0, v81
	v_max_f32_e32 v57, 0, v82
	v_max_f32_e32 v59, 0, v83
	v_max_f32_e32 v60, 0, v84
	v_max_f32_e32 v62, 0, v85
	v_add_u32_e32 v80, 0x90, v144
	v_lshlrev_b64 v[82:83], 13, v[96:97]
	v_ashrrev_i32_e32 v81, 31, v80
	v_lshlrev_b64 v[84:85], 6, v[80:81]
	s_waitcnt vmcnt(0) lgkmcnt(0)
	v_mov_b32_e32 v86, v65
	v_mov_b32_e32 v87, v66
	v_mov_b32_e32 v65, v67
	v_mov_b32_e32 v66, v69
	v_mov_b32_e32 v67, v70
	v_mov_b32_e32 v69, v71
	v_pk_add_f32 v[64:65], v[86:87], v[64:65]
	v_pk_add_f32 v[66:67], v[66:67], v[68:69]
	v_pk_add_f32 v[64:65], v[64:65], v[64:65] op_sel:[0,1] op_sel_hi:[1,0]
	v_pk_add_f32 v[66:67], v[66:67], v[66:67] op_sel:[0,1] op_sel_hi:[1,0]
	v_add_f32_e32 v70, v72, v73
	v_add_f32_e32 v72, v74, v75
	v_mov_b32_e32 v71, v78
	v_mov_b32_e32 v73, v79
	v_mov_b32_e32 v65, v76
	v_mov_b32_e32 v67, v77
	v_pk_add_f32 v[68:69], v[70:71], v[72:73]
	v_pk_add_f32 v[64:65], v[64:65], v[66:67]
	v_lshl_add_u64 v[66:67], s[52:53], 0, v[82:83]
	v_pk_add_f32 v[64:65], v[64:65], v[68:69]
	v_lshl_add_u64 v[66:67], v[66:67], 0, v[112:113]
	v_add_f32_e32 v64, v64, v65
	v_fmamk_f32 v64, v64, 0x3a800000, v150
	v_rsq_f32_e32 v64, v64
	v_lshl_add_u64 v[68:69], s[60:61], 0, v[84:85]
	v_pk_mul_f32 v[48:49], v[48:49], v[64:65] op_sel_hi:[1,0]
	v_pk_mul_f32 v[50:51], v[50:51], v[64:65] op_sel_hi:[1,0]
	v_pk_mul_f32 v[52:53], v[52:53], v[64:65] op_sel_hi:[1,0]
	v_pk_mul_f32 v[54:55], v[54:55], v[64:65] op_sel_hi:[1,0]
	v_pk_mul_f32 v[56:57], v[56:57], v[64:65] op_sel_hi:[1,0]
	v_pk_mul_f32 v[58:59], v[58:59], v[64:65] op_sel_hi:[1,0]
	v_pk_mul_f32 v[60:61], v[60:61], v[64:65] op_sel_hi:[1,0]
	v_pk_mul_f32 v[62:63], v[62:63], v[64:65] op_sel_hi:[1,0]
	v_pk_mul_f32 v[48:49], v[48:49], v[48:49]
	v_pk_mul_f32 v[50:51], v[50:51], v[50:51]
	v_pk_mul_f32 v[52:53], v[52:53], v[52:53]
	v_pk_mul_f32 v[54:55], v[54:55], v[54:55]
	v_pk_mul_f32 v[56:57], v[56:57], v[56:57]
	v_pk_mul_f32 v[58:59], v[58:59], v[58:59]
	v_pk_mul_f32 v[60:61], v[60:61], v[60:61]
	v_pk_mul_f32 v[62:63], v[62:63], v[62:63]
	v_cvt_pk_bf16_f32 v48, v48, v49
	v_cvt_pk_bf16_f32 v49, v52, v53
	v_cvt_pk_bf16_f32 v50, v50, v51
	v_cvt_pk_bf16_f32 v51, v54, v55
	v_cvt_pk_bf16_f32 v52, v56, v57
	v_cvt_pk_bf16_f32 v53, v60, v61
	v_cvt_pk_bf16_f32 v54, v58, v59
	v_cvt_pk_bf16_f32 v55, v62, v63
	global_store_dwordx4 v[66:67], v[48:51], off
	s_nop 0
	global_store_dwordx4 v[66:67], v[52:55], off offset:256
	global_load_dwordx4 v[48:51], v[68:69], off
	s_nop 0
	global_load_dwordx4 v[52:55], v[68:69], off offset:16
	global_load_dwordx4 v[56:59], v[68:69], off offset:32
	global_load_dwordx4 v[60:63], v[68:69], off offset:48
	v_max_f32_e32 v66, v37, v37
	v_max_f32_e32 v67, v33, v33
	v_max_f32_e32 v33, 0, v45
	v_max_f32_e32 v37, 0, v47
	v_max_f32_e32 v45, 0, v39
	v_max_f32_e32 v47, 0, v35
	v_max_f32_e32 v64, v36, v36
	v_max_f32_e32 v65, v32, v32
	v_max_f32_e32 v68, v38, v38
	v_max_f32_e32 v69, v34, v34
	v_max_f32_e32 v32, 0, v44
	v_max_f32_e32 v34, 0, v40
	v_max_f32_e32 v35, 0, v41
	v_max_f32_e32 v36, 0, v46
	v_max_f32_e32 v38, 0, v42
	v_max_f32_e32 v39, 0, v43
	v_max_f32_e32 v40, 0, v64
	v_max_f32_e32 v42, 0, v65
	v_max_f32_e32 v41, 0, v66
	v_max_f32_e32 v43, 0, v67
	v_max_f32_e32 v44, 0, v68
	v_max_f32_e32 v46, 0, v69
	v_add_u32_e32 v64, 0xa0, v144
	v_lshlrev_b64 v[66:67], 13, v[80:81]
	v_ashrrev_i32_e32 v65, 31, v64
	v_lshlrev_b64 v[68:69], 6, v[64:65]
	s_waitcnt vmcnt(0) lgkmcnt(0)
; DI u32x4 pack_v8(f32x4 v0, f32x4 v1) { u32x4 w; w.x = pk2(v0[0], v0[1]); w.y = pk2(v0[2], v0[3]); w.z = pk2(v1[0], v1[1]); w.w = pk2(v1[2], v1[3]); return w; }
; DI float rstd16(const float* ssq, int row) { const f32x4* p = (const f32x4*)(ssq + (size_t)row * 16); const f32x4 a = p[0], b = p[1], c = p[2], d = p[3];
;   return __builtin_amdgcn_rsqf((((a[0] + a[1]) + (a[2] + a[3])) + ((b[0] + b[1]) + (b[2] + b[3])) + ((c[0] + c[1]) + (c[2] + c[3])) + ((d[0] + d[1]) + (d[2] + d[3]))) * (1.0f / 1024.0f) + EPS); }
;   DI void operator()(AccRef acc, const Unit& u, int wr, int wc, int fr, int fq) const {
;     ...
;       for (int m = 0; m < 4; ++m) { const int row = rowb + ai * 128 + m * 16; const float rs = rstd16(SSQH, row);
; #pragma unroll
;         for (int bj = 0; bj < 2; ++bj) { f32x4 v0 = acc[ai][bj][m][0], v1 = acc[ai][bj][m][1];
; #pragma unroll
;           for (int j = 0; j < 4; ++j) { const float a = fmaxf(v0[j], 0.f) * rs, b = fmaxf(v1[j], 0.f) * rs; v0[j] = a * a; v1[j] = b * b; }
;           *(u32x4*)(A2 + (size_t)row * DFF + cb + bj * 128) = pack_v8(v0, v1); } }
	v_mov_b32_e32 v70, v49
	v_mov_b32_e32 v71, v50
	v_mov_b32_e32 v49, v51
	v_mov_b32_e32 v50, v53
	v_mov_b32_e32 v51, v54
	v_mov_b32_e32 v53, v55
	v_pk_add_f32 v[48:49], v[70:71], v[48:49]
	v_pk_add_f32 v[50:51], v[50:51], v[52:53]
	v_pk_add_f32 v[48:49], v[48:49], v[48:49] op_sel:[0,1] op_sel_hi:[1,0]
	v_pk_add_f32 v[50:51], v[50:51], v[50:51] op_sel:[0,1] op_sel_hi:[1,0]
	v_add_f32_e32 v54, v56, v57
	v_add_f32_e32 v56, v58, v59
	v_mov_b32_e32 v55, v62
	v_mov_b32_e32 v57, v63
	v_mov_b32_e32 v49, v60
	v_mov_b32_e32 v51, v61
	v_pk_add_f32 v[52:53], v[54:55], v[56:57]
	v_pk_add_f32 v[48:49], v[48:49], v[50:51]
	v_lshl_add_u64 v[50:51], s[52:53], 0, v[66:67]
	v_pk_add_f32 v[48:49], v[48:49], v[52:53]
	v_lshl_add_u64 v[50:51], v[50:51], 0, v[112:113]
	v_add_f32_e32 v48, v48, v49
	v_fmamk_f32 v48, v48, 0x3a800000, v150
	v_rsq_f32_e32 v48, v48
	v_lshl_add_u64 v[52:53], s[60:61], 0, v[68:69]
	v_pk_mul_f32 v[32:33], v[32:33], v[48:49] op_sel_hi:[1,0]
	v_pk_mul_f32 v[34:35], v[34:35], v[48:49] op_sel_hi:[1,0]
	v_pk_mul_f32 v[36:37], v[36:37], v[48:49] op_sel_hi:[1,0]
	v_pk_mul_f32 v[38:39], v[38:39], v[48:49] op_sel_hi:[1,0]
	v_pk_mul_f32 v[40:41], v[40:41], v[48:49] op_sel_hi:[1,0]
	v_pk_mul_f32 v[42:43], v[42:43], v[48:49] op_sel_hi:[1,0]
	v_pk_mul_f32 v[44:45], v[44:45], v[48:49] op_sel_hi:[1,0]
	v_pk_mul_f32 v[46:47], v[46:47], v[48:49] op_sel_hi:[1,0]
	v_pk_mul_f32 v[32:33], v[32:33], v[32:33]
	v_pk_mul_f32 v[34:35], v[34:35], v[34:35]
	v_pk_mul_f32 v[36:37], v[36:37], v[36:37]
	v_pk_mul_f32 v[38:39], v[38:39], v[38:39]
	v_pk_mul_f32 v[40:41], v[40:41], v[40:41]
	v_pk_mul_f32 v[42:43], v[42:43], v[42:43]
	v_pk_mul_f32 v[44:45], v[44:45], v[44:45]
	v_pk_mul_f32 v[46:47], v[46:47], v[46:47]
	v_cvt_pk_bf16_f32 v32, v32, v33
	v_cvt_pk_bf16_f32 v33, v36, v37
	v_cvt_pk_bf16_f32 v34, v34, v35
	v_cvt_pk_bf16_f32 v35, v38, v39
	v_cvt_pk_bf16_f32 v36, v40, v41
	v_cvt_pk_bf16_f32 v37, v44, v45
	v_cvt_pk_bf16_f32 v38, v42, v43
	v_cvt_pk_bf16_f32 v39, v46, v47
	global_store_dwordx4 v[50:51], v[32:35], off
	s_nop 0
	global_store_dwordx4 v[50:51], v[36:39], off offset:256
	global_load_dwordx4 v[32:35], v[52:53], off
	s_nop 0
	global_load_dwordx4 v[36:39], v[52:53], off offset:16
	global_load_dwordx4 v[40:43], v[52:53], off offset:32
	global_load_dwordx4 v[44:47], v[52:53], off offset:48
	v_max_f32_e32 v50, v21, v21
	v_max_f32_e32 v51, v17, v17
	v_max_f32_e32 v17, 0, v29
	v_max_f32_e32 v21, 0, v31
	v_max_f32_e32 v29, 0, v23
	v_max_f32_e32 v31, 0, v19
	v_max_f32_e32 v48, v20, v20
	v_max_f32_e32 v49, v16, v16
	v_max_f32_e32 v52, v22, v22
	v_max_f32_e32 v53, v18, v18
	v_max_f32_e32 v16, 0, v28
	v_max_f32_e32 v18, 0, v24
	v_max_f32_e32 v19, 0, v25
	v_max_f32_e32 v20, 0, v30
	v_max_f32_e32 v22, 0, v26
	v_max_f32_e32 v23, 0, v27
	v_max_f32_e32 v24, 0, v48
	v_max_f32_e32 v26, 0, v49
	v_max_f32_e32 v25, 0, v50
	v_max_f32_e32 v27, 0, v51
	v_max_f32_e32 v28, 0, v52
	v_max_f32_e32 v30, 0, v53
	v_add_u32_e32 v48, 0xb0, v144
	v_lshlrev_b64 v[50:51], 13, v[64:65]
	v_ashrrev_i32_e32 v49, 31, v48
	v_lshlrev_b64 v[52:53], 6, v[48:49]
	s_waitcnt vmcnt(0) lgkmcnt(0)
; DI float ozero() { float z = 0.f; asm volatile("" : "+v"(z)); return z; }
; DI int otid() { int t = threadIdx.x; asm volatile("" : "+v"(t)); return t; }
; #define PG8_BAR __builtin_amdgcn_s_barrier()
; DI u32x4 pack_v8(f32x4 v0, f32x4 v1) { u32x4 w; w.x = pk2(v0[0], v0[1]); w.y = pk2(v0[2], v0[3]); w.z = pk2(v1[0], v1[1]); w.w = pk2(v1[2], v1[3]); return w; }
; template <class Epi, class Sched>
; DI void gemm_phase(LAS unsigned char* lds, const Gemm g, const Sched& S, const Epi& E) {
;     ...
;     if (wr == 0) PG8_BAR;
;     { const int l2 = otid() & 63; E(acc, cur, wr, wc, l2 & 15, l2 >> 4); }
;     if (!has_next) break;
;     { const float z0 = ozero();
; #pragma unroll
;     for (int a = 0; a < 2; ++a)
; #pragma unroll
;       for (int b = 0; b < 2; ++b)
; #pragma unroll
;         for (int m = 0; m < 4; ++m)
; #pragma unroll
;           for (int n = 0; n < 2; ++n) acc[a][b][m][n] = (f32x4){z0, z0, z0, z0}; }
;     cur = nxt; cA = nA; cB = nB; ++ui;
;     if (wr == 1) PG8_BAR;
;   DI void operator()(AccRef acc, const Unit& u, int wr, int wc, int fr, int fq) const {
;     ...
;       for (int m = 0; m < 4; ++m) { const int row = rowb + ai * 128 + m * 16; const float rs = rstd16(SSQH, row);
; #pragma unroll
;         for (int bj = 0; bj < 2; ++bj) { f32x4 v0 = acc[ai][bj][m][0], v1 = acc[ai][bj][m][1];
; #pragma unroll
;           for (int j = 0; j < 4; ++j) { const float a = fmaxf(v0[j], 0.f) * rs, b = fmaxf(v1[j], 0.f) * rs; v0[j] = a * a; v1[j] = b * b; }
;           *(u32x4*)(A2 + (size_t)row * DFF + cb + bj * 128) = pack_v8(v0, v1); } }
	v_mov_b32_e32 v54, v33
	v_mov_b32_e32 v55, v34
	v_mov_b32_e32 v33, v35
	v_mov_b32_e32 v34, v37
	v_mov_b32_e32 v35, v38
	v_mov_b32_e32 v37, v39
	v_pk_add_f32 v[32:33], v[54:55], v[32:33]
	v_pk_add_f32 v[34:35], v[34:35], v[36:37]
	v_pk_add_f32 v[32:33], v[32:33], v[32:33] op_sel:[0,1] op_sel_hi:[1,0]
	v_pk_add_f32 v[34:35], v[34:35], v[34:35] op_sel:[0,1] op_sel_hi:[1,0]
	v_add_f32_e32 v38, v40, v41
	v_add_f32_e32 v40, v42, v43
	v_mov_b32_e32 v39, v46
	v_mov_b32_e32 v41, v47
	v_mov_b32_e32 v33, v44
	v_mov_b32_e32 v35, v45
	v_pk_add_f32 v[36:37], v[38:39], v[40:41]
	v_pk_add_f32 v[32:33], v[32:33], v[34:35]
	v_lshl_add_u64 v[34:35], s[52:53], 0, v[50:51]
	v_pk_add_f32 v[32:33], v[32:33], v[36:37]
	v_lshl_add_u64 v[34:35], v[34:35], 0, v[112:113]
	v_add_f32_e32 v32, v32, v33
	v_fmamk_f32 v32, v32, 0x3a800000, v150
	v_rsq_f32_e32 v32, v32
	v_lshl_add_u64 v[36:37], s[60:61], 0, v[52:53]
	v_max_f32_e32 v38, v7, v7
	v_max_f32_e32 v39, v3, v3
	v_pk_mul_f32 v[16:17], v[16:17], v[32:33] op_sel_hi:[1,0]
	v_pk_mul_f32 v[18:19], v[18:19], v[32:33] op_sel_hi:[1,0]
	v_pk_mul_f32 v[20:21], v[20:21], v[32:33] op_sel_hi:[1,0]
	v_pk_mul_f32 v[22:23], v[22:23], v[32:33] op_sel_hi:[1,0]
	v_pk_mul_f32 v[24:25], v[24:25], v[32:33] op_sel_hi:[1,0]
	v_pk_mul_f32 v[26:27], v[26:27], v[32:33] op_sel_hi:[1,0]
	v_pk_mul_f32 v[28:29], v[28:29], v[32:33] op_sel_hi:[1,0]
	v_pk_mul_f32 v[30:31], v[30:31], v[32:33] op_sel_hi:[1,0]
	v_pk_mul_f32 v[16:17], v[16:17], v[16:17]
	v_pk_mul_f32 v[18:19], v[18:19], v[18:19]
	v_pk_mul_f32 v[20:21], v[20:21], v[20:21]
	v_pk_mul_f32 v[22:23], v[22:23], v[22:23]
	v_pk_mul_f32 v[24:25], v[24:25], v[24:25]
	v_pk_mul_f32 v[26:27], v[26:27], v[26:27]
	v_pk_mul_f32 v[28:29], v[28:29], v[28:29]
	v_pk_mul_f32 v[30:31], v[30:31], v[30:31]
	v_cvt_pk_bf16_f32 v16, v16, v17
	v_cvt_pk_bf16_f32 v17, v20, v21
	v_cvt_pk_bf16_f32 v18, v18, v19
	v_cvt_pk_bf16_f32 v19, v22, v23
	v_cvt_pk_bf16_f32 v20, v24, v25
	v_cvt_pk_bf16_f32 v21, v28, v29
	v_cvt_pk_bf16_f32 v22, v26, v27
	v_cvt_pk_bf16_f32 v23, v30, v31
	global_store_dwordx4 v[34:35], v[16:19], off
	s_nop 0
	global_store_dwordx4 v[34:35], v[20:23], off offset:256
	global_load_dwordx4 v[16:19], v[36:37], off
	s_nop 0
	global_load_dwordx4 v[20:23], v[36:37], off offset:16
	global_load_dwordx4 v[24:27], v[36:37], off offset:32
	global_load_dwordx4 v[28:31], v[36:37], off offset:48
	v_max_f32_e32 v36, v6, v6
	v_max_f32_e32 v37, v2, v2
	v_max_f32_e32 v2, 0, v8
	v_max_f32_e32 v6, 0, v10
	v_max_f32_e32 v8, 0, v4
	v_max_f32_e32 v10, 0, v0
	v_max_f32_e32 v34, v5, v5
	v_max_f32_e32 v35, v1, v1
	v_max_f32_e32 v0, 0, v12
	v_max_f32_e32 v1, 0, v13
	v_max_f32_e32 v3, 0, v9
	v_max_f32_e32 v4, 0, v14
	v_max_f32_e32 v5, 0, v15
	v_max_f32_e32 v7, 0, v11
	v_max_f32_e32 v9, 0, v34
	v_max_f32_e32 v11, 0, v35
	v_max_f32_e32 v12, 0, v36
	v_max_f32_e32 v14, 0, v37
	v_max_f32_e32 v13, 0, v38
	v_max_f32_e32 v15, 0, v39
	s_waitcnt vmcnt(0) lgkmcnt(0)
	v_mov_b32_e32 v32, v17
	v_mov_b32_e32 v33, v18
	v_mov_b32_e32 v17, v19
	v_mov_b32_e32 v18, v21
	v_mov_b32_e32 v19, v22
	v_mov_b32_e32 v21, v23
	v_pk_add_f32 v[16:17], v[32:33], v[16:17]
	v_pk_add_f32 v[18:19], v[18:19], v[20:21]
	v_pk_add_f32 v[16:17], v[16:17], v[16:17] op_sel:[0,1] op_sel_hi:[1,0]
	v_pk_add_f32 v[18:19], v[18:19], v[18:19] op_sel:[0,1] op_sel_hi:[1,0]
	v_add_f32_e32 v22, v24, v25
	v_add_f32_e32 v24, v26, v27
	v_mov_b32_e32 v23, v30
	v_mov_b32_e32 v25, v31
	v_mov_b32_e32 v17, v28
	v_mov_b32_e32 v19, v29
	v_pk_add_f32 v[20:21], v[22:23], v[24:25]
	v_pk_add_f32 v[16:17], v[16:17], v[18:19]
	v_lshlrev_b64 v[18:19], 13, v[48:49]
	v_pk_add_f32 v[16:17], v[16:17], v[20:21]
	v_lshl_add_u64 v[18:19], s[52:53], 0, v[18:19]
	v_add_f32_e32 v16, v16, v17
	v_fmamk_f32 v16, v16, 0x3a800000, v150
	v_rsq_f32_e32 v16, v16
	v_lshl_add_u64 v[18:19], v[18:19], 0, v[112:113]
	v_pk_mul_f32 v[0:1], v[0:1], v[16:17] op_sel_hi:[1,0]
	v_pk_mul_f32 v[2:3], v[2:3], v[16:17] op_sel_hi:[1,0]
	v_pk_mul_f32 v[4:5], v[4:5], v[16:17] op_sel_hi:[1,0]
	v_pk_mul_f32 v[6:7], v[6:7], v[16:17] op_sel_hi:[1,0]
	v_pk_mul_f32 v[8:9], v[8:9], v[16:17] op_sel_hi:[1,0]
	v_pk_mul_f32 v[10:11], v[10:11], v[16:17] op_sel_hi:[1,0]
	v_pk_mul_f32 v[12:13], v[12:13], v[16:17] op_sel_hi:[1,0]
	v_pk_mul_f32 v[14:15], v[14:15], v[16:17] op_sel_hi:[1,0]
	v_pk_mul_f32 v[0:1], v[0:1], v[0:1]
	v_pk_mul_f32 v[2:3], v[2:3], v[2:3]
	v_pk_mul_f32 v[4:5], v[4:5], v[4:5]
	v_pk_mul_f32 v[6:7], v[6:7], v[6:7]
	v_pk_mul_f32 v[8:9], v[8:9], v[8:9]
	v_pk_mul_f32 v[10:11], v[10:11], v[10:11]
	v_pk_mul_f32 v[12:13], v[12:13], v[12:13]
	v_pk_mul_f32 v[14:15], v[14:15], v[14:15]
	v_cvt_pk_bf16_f32 v0, v0, v1
	v_cvt_pk_bf16_f32 v1, v4, v5
	v_cvt_pk_bf16_f32 v2, v2, v3
	v_cvt_pk_bf16_f32 v3, v6, v7
	v_cvt_pk_bf16_f32 v4, v8, v9
	v_cvt_pk_bf16_f32 v5, v12, v13
	v_cvt_pk_bf16_f32 v6, v10, v11
	v_cvt_pk_bf16_f32 v7, v14, v15
	global_store_dwordx4 v[18:19], v[0:3], off
	global_store_dwordx4 v[18:19], v[4:7], off offset:256
	s_cbranch_vccnz .LBB0_892
	v_mov_b32_e32 v0, 0
	s_andn2_b64 vcc, exec, s[6:7]
	s_cbranch_vccnz .LBB0_891
	s_barrier
	s_branch .LBB0_891

; DI u32x4 pack_v8(f32x4 v0, f32x4 v1) { u32x4 w; w.x = pk2(v0[0], v0[1]); w.y = pk2(v0[2], v0[3]); w.z = pk2(v1[0], v1[1]); w.w = pk2(v1[2], v1[3]); return w; }
; DI float rstd16(const float* ssq, int row) { const f32x4* p = (const f32x4*)(ssq + (size_t)row * 16); const f32x4 a = p[0], b = p[1], c = p[2], d = p[3];
;   return __builtin_amdgcn_rsqf((((a[0] + a[1]) + (a[2] + a[3])) + ((b[0] + b[1]) + (b[2] + b[3])) + ((c[0] + c[1]) + (c[2] + c[3])) + ((d[0] + d[1]) + (d[2] + d[3]))) * (1.0f / 1024.0f) + EPS); }
;   DI void operator()(AccRef acc, const Unit& u, int wr, int wc, int fr, int fq) const {
;     const int rowb = u.pm * 256 + wr * 64 + fr; const int cb = u.pn * 256 + wc * 32 + 8 * fq;
; #pragma unroll
;     for (int ai = 0; ai < 2; ++ai)
; #pragma unroll
;       for (int m = 0; m < 4; ++m) { const int row = rowb + ai * 128 + m * 16; const float rs = rstd16(SSQH, row);
; #pragma unroll
;         for (int bj = 0; bj < 2; ++bj) { f32x4 v0 = acc[ai][bj][m][0], v1 = acc[ai][bj][m][1];
; #pragma unroll
;           for (int j = 0; j < 4; ++j) { const float a = fmaxf(v0[j], 0.f) * rs, b = fmaxf(v1[j], 0.f) * rs; v0[j] = a * a; v1[j] = b * b; }
;           *(u32x4*)(A2 + (size_t)row * DFF + cb + bj * 128) = pack_v8(v0, v1); } }
.LBB0_1683:
	s_lshl_b32 s13, s22, 8
	v_mov_b32_e32 v151, v224
	s_add_i32 s13, s13, s36
	v_and_or_b32 v144, v151, 15, s13
	v_ashrrev_i32_e32 v145, 31, v144
	v_lshlrev_b64 v[152:153], 6, v[144:145]
	v_lshl_add_u64 v[164:165], s[58:59], 0, v[152:153]
	global_load_dwordx4 v[152:155], v[164:165], off
	global_load_dwordx4 v[156:159], v[164:165], off offset:16
	global_load_dwordx4 v[160:163], v[164:165], off offset:32
	s_nop 0
	global_load_dwordx4 v[164:167], v[164:165], off offset:48
	v_max_f32_e32 v169, v117, v117
	v_max_f32_e32 v172, v119, v119
	v_max_f32_e32 v117, 0, v121
	v_max_f32_e32 v119, 0, v127
	v_max_f32_e32 v121, 0, v123
	v_max_f32_e32 v123, 0, v169
	v_max_f32_e32 v127, 0, v172
	v_max_f32_e32 v169, 0, v115
	v_lshlrev_b64 v[172:173], 13, v[144:145]
	s_lshl_b32 s13, s66, 8
	v_max_f32_e32 v171, v114, v114
	v_max_f32_e32 v114, 0, v124
	v_max_f32_e32 v124, 0, v112
	v_lshrrev_b32_e32 v112, 1, v151
	v_and_or_b32 v112, v112, 24, s13
	v_max_f32_e32 v168, v116, v116
	v_max_f32_e32 v170, v118, v118
	v_max_f32_e32 v116, 0, v120
	v_max_f32_e32 v115, 0, v125
	v_max_f32_e32 v118, 0, v126
	v_max_f32_e32 v120, 0, v122
	v_or_b32_e32 v112, s37, v112
	v_max_f32_e32 v122, 0, v168
	v_max_f32_e32 v125, 0, v113
	v_max_f32_e32 v126, 0, v170
	v_max_f32_e32 v168, 0, v171
	v_ashrrev_i32_e32 v113, 31, v112
	v_or_b32_e32 v170, 16, v144
	v_lshlrev_b64 v[112:113], 1, v[112:113]
	v_ashrrev_i32_e32 v171, 31, v170
	v_max_f32_e32 v151, v97, v97
	v_max_f32_e32 v97, 0, v109
	s_waitcnt vmcnt(0) lgkmcnt(0)
	v_mov_b32_e32 v174, v153
	v_mov_b32_e32 v175, v154
	v_mov_b32_e32 v153, v155
	v_mov_b32_e32 v154, v157
	v_mov_b32_e32 v155, v158
	v_mov_b32_e32 v157, v159
	v_pk_add_f32 v[152:153], v[174:175], v[152:153]
	v_pk_add_f32 v[154:155], v[154:155], v[156:157]
	v_pk_add_f32 v[152:153], v[152:153], v[152:153] op_sel:[0,1] op_sel_hi:[1,0]
	v_pk_add_f32 v[154:155], v[154:155], v[154:155] op_sel:[0,1] op_sel_hi:[1,0]
	v_add_f32_e32 v158, v160, v161
	v_add_f32_e32 v160, v162, v163
	v_mov_b32_e32 v159, v166
	v_mov_b32_e32 v161, v167
	v_mov_b32_e32 v153, v164
	v_mov_b32_e32 v155, v165
	v_pk_add_f32 v[156:157], v[158:159], v[160:161]
	v_pk_add_f32 v[152:153], v[152:153], v[154:155]
	v_lshl_add_u64 v[154:155], s[54:55], 0, v[172:173]
	v_pk_add_f32 v[152:153], v[152:153], v[156:157]
	v_lshl_add_u64 v[154:155], v[154:155], 0, v[112:113]
	v_add_f32_e32 v145, v152, v153
	v_fmamk_f32 v145, v145, 0x3a800000, v150
	v_rsq_f32_e32 v152, v145
	v_max_f32_e32 v145, v101, v101
	v_max_f32_e32 v156, v102, v102
	v_max_f32_e32 v157, v98, v98
	v_pk_mul_f32 v[114:115], v[114:115], v[152:153] op_sel_hi:[1,0]
	v_pk_mul_f32 v[116:117], v[116:117], v[152:153] op_sel_hi:[1,0]
	v_pk_mul_f32 v[118:119], v[118:119], v[152:153] op_sel_hi:[1,0]
	v_pk_mul_f32 v[120:121], v[120:121], v[152:153] op_sel_hi:[1,0]
	v_pk_mul_f32 v[122:123], v[122:123], v[152:153] op_sel_hi:[1,0]
	v_pk_mul_f32 v[124:125], v[124:125], v[152:153] op_sel_hi:[1,0]
	v_pk_mul_f32 v[126:127], v[126:127], v[152:153] op_sel_hi:[1,0]
	v_pk_mul_f32 v[152:153], v[168:169], v[152:153] op_sel_hi:[1,0]
	v_pk_mul_f32 v[114:115], v[114:115], v[114:115]
	v_pk_mul_f32 v[116:117], v[116:117], v[116:117]
	v_pk_mul_f32 v[118:119], v[118:119], v[118:119]
	v_pk_mul_f32 v[120:121], v[120:121], v[120:121]
	v_pk_mul_f32 v[122:123], v[122:123], v[122:123]
	v_pk_mul_f32 v[124:125], v[124:125], v[124:125]
	v_pk_mul_f32 v[126:127], v[126:127], v[126:127]
	v_pk_mul_f32 v[152:153], v[152:153], v[152:153]
	v_cvt_pk_bf16_f32 v114, v114, v115
	v_cvt_pk_bf16_f32 v115, v118, v119
	v_cvt_pk_bf16_f32 v116, v116, v117
	v_cvt_pk_bf16_f32 v117, v120, v121
	v_cvt_pk_bf16_f32 v118, v122, v123
	v_cvt_pk_bf16_f32 v119, v126, v127
	v_cvt_pk_bf16_f32 v120, v124, v125
	v_cvt_pk_bf16_f32 v121, v152, v153
	global_store_dwordx4 v[154:155], v[114:117], off
	global_store_dwordx4 v[154:155], v[118:121], off offset:256
	v_max_f32_e32 v158, v103, v103
	v_lshlrev_b64 v[114:115], 6, v[170:171]
	v_lshl_add_u64 v[126:127], s[58:59], 0, v[114:115]
	global_load_dwordx4 v[114:117], v[126:127], off
	global_load_dwordx4 v[118:121], v[126:127], off offset:16
	global_load_dwordx4 v[122:125], v[126:127], off offset:32
	global_load_dwordx4 v[152:155], v[126:127], off offset:48
	v_max_f32_e32 v126, v100, v100
	v_max_f32_e32 v127, v96, v96
	v_max_f32_e32 v159, v99, v99
	v_max_f32_e32 v96, 0, v108
	v_max_f32_e32 v98, 0, v104
	v_max_f32_e32 v99, 0, v105
	v_max_f32_e32 v100, 0, v110
	v_max_f32_e32 v102, 0, v106
	v_max_f32_e32 v101, 0, v111
	v_max_f32_e32 v103, 0, v107
	v_max_f32_e32 v104, 0, v126
	v_max_f32_e32 v106, 0, v127
	v_max_f32_e32 v105, 0, v145
	v_max_f32_e32 v107, 0, v151
	v_max_f32_e32 v108, 0, v156
	v_max_f32_e32 v110, 0, v157
	v_max_f32_e32 v109, 0, v158
	v_max_f32_e32 v111, 0, v159
	v_or_b32_e32 v126, 32, v144
	v_lshlrev_b64 v[156:157], 13, v[170:171]
	v_ashrrev_i32_e32 v127, 31, v126
	v_lshlrev_b64 v[158:159], 6, v[126:127]
	s_andn2_b64 vcc, exec, s[4:5]
	s_mov_b64 s[4:5], -1
	s_waitcnt vmcnt(0) lgkmcnt(0)
; DI u32x4 pack_v8(f32x4 v0, f32x4 v1) { u32x4 w; w.x = pk2(v0[0], v0[1]); w.y = pk2(v0[2], v0[3]); w.z = pk2(v1[0], v1[1]); w.w = pk2(v1[2], v1[3]); return w; }
; DI float rstd16(const float* ssq, int row) { const f32x4* p = (const f32x4*)(ssq + (size_t)row * 16); const f32x4 a = p[0], b = p[1], c = p[2], d = p[3];
;   return __builtin_amdgcn_rsqf((((a[0] + a[1]) + (a[2] + a[3])) + ((b[0] + b[1]) + (b[2] + b[3])) + ((c[0] + c[1]) + (c[2] + c[3])) + ((d[0] + d[1]) + (d[2] + d[3]))) * (1.0f / 1024.0f) + EPS); }
;   DI void operator()(AccRef acc, const Unit& u, int wr, int wc, int fr, int fq) const {
;     ...
;       for (int m = 0; m < 4; ++m) { const int row = rowb + ai * 128 + m * 16; const float rs = rstd16(SSQH, row);
; #pragma unroll
;         for (int bj = 0; bj < 2; ++bj) { f32x4 v0 = acc[ai][bj][m][0], v1 = acc[ai][bj][m][1];
; #pragma unroll
;           for (int j = 0; j < 4; ++j) { const float a = fmaxf(v0[j], 0.f) * rs, b = fmaxf(v1[j], 0.f) * rs; v0[j] = a * a; v1[j] = b * b; }
;           *(u32x4*)(A2 + (size_t)row * DFF + cb + bj * 128) = pack_v8(v0, v1); } }
	v_mov_b32_e32 v160, v115
	v_mov_b32_e32 v161, v116
	v_mov_b32_e32 v115, v117
	v_mov_b32_e32 v116, v119
	v_mov_b32_e32 v117, v120
	v_mov_b32_e32 v119, v121
	v_pk_add_f32 v[114:115], v[160:161], v[114:115]
	v_pk_add_f32 v[116:117], v[116:117], v[118:119]
	v_pk_add_f32 v[114:115], v[114:115], v[114:115] op_sel:[0,1] op_sel_hi:[1,0]
	v_pk_add_f32 v[116:117], v[116:117], v[116:117] op_sel:[0,1] op_sel_hi:[1,0]
	v_add_f32_e32 v120, v122, v123
	v_add_f32_e32 v122, v124, v125
	v_mov_b32_e32 v121, v154
	v_mov_b32_e32 v123, v155
	v_mov_b32_e32 v115, v152
	v_mov_b32_e32 v117, v153
	v_pk_add_f32 v[118:119], v[120:121], v[122:123]
	v_pk_add_f32 v[114:115], v[114:115], v[116:117]
	v_lshl_add_u64 v[116:117], s[54:55], 0, v[156:157]
	v_pk_add_f32 v[114:115], v[114:115], v[118:119]
	v_lshl_add_u64 v[116:117], v[116:117], 0, v[112:113]
	v_add_f32_e32 v114, v114, v115
	v_fmamk_f32 v114, v114, 0x3a800000, v150
	v_rsq_f32_e32 v114, v114
	v_lshl_add_u64 v[118:119], s[58:59], 0, v[158:159]
	v_pk_mul_f32 v[96:97], v[96:97], v[114:115] op_sel_hi:[1,0]
	v_pk_mul_f32 v[98:99], v[98:99], v[114:115] op_sel_hi:[1,0]
	v_pk_mul_f32 v[100:101], v[100:101], v[114:115] op_sel_hi:[1,0]
	v_pk_mul_f32 v[102:103], v[102:103], v[114:115] op_sel_hi:[1,0]
	v_pk_mul_f32 v[104:105], v[104:105], v[114:115] op_sel_hi:[1,0]
	v_pk_mul_f32 v[106:107], v[106:107], v[114:115] op_sel_hi:[1,0]
	v_pk_mul_f32 v[108:109], v[108:109], v[114:115] op_sel_hi:[1,0]
	v_pk_mul_f32 v[110:111], v[110:111], v[114:115] op_sel_hi:[1,0]
	v_pk_mul_f32 v[96:97], v[96:97], v[96:97]
	v_pk_mul_f32 v[98:99], v[98:99], v[98:99]
	v_pk_mul_f32 v[100:101], v[100:101], v[100:101]
	v_pk_mul_f32 v[102:103], v[102:103], v[102:103]
	v_pk_mul_f32 v[104:105], v[104:105], v[104:105]
	v_pk_mul_f32 v[106:107], v[106:107], v[106:107]
	v_pk_mul_f32 v[108:109], v[108:109], v[108:109]
	v_pk_mul_f32 v[110:111], v[110:111], v[110:111]
	v_cvt_pk_bf16_f32 v96, v96, v97
	v_cvt_pk_bf16_f32 v97, v100, v101
	v_cvt_pk_bf16_f32 v98, v98, v99
	v_cvt_pk_bf16_f32 v99, v102, v103
	v_cvt_pk_bf16_f32 v100, v104, v105
	v_cvt_pk_bf16_f32 v101, v108, v109
	v_cvt_pk_bf16_f32 v102, v106, v107
	v_cvt_pk_bf16_f32 v103, v110, v111
	global_store_dwordx4 v[116:117], v[96:99], off
	s_nop 0
	global_store_dwordx4 v[116:117], v[100:103], off offset:256
	global_load_dwordx4 v[96:99], v[118:119], off
	s_nop 0
	global_load_dwordx4 v[100:103], v[118:119], off offset:16
	global_load_dwordx4 v[104:107], v[118:119], off offset:32
	global_load_dwordx4 v[108:111], v[118:119], off offset:48
	v_max_f32_e32 v116, v85, v85
	v_max_f32_e32 v117, v81, v81
	v_max_f32_e32 v81, 0, v93
	v_max_f32_e32 v85, 0, v95
	v_max_f32_e32 v93, 0, v87
	v_max_f32_e32 v95, 0, v83
	v_max_f32_e32 v114, v84, v84
	v_max_f32_e32 v115, v80, v80
	v_max_f32_e32 v118, v86, v86
	v_max_f32_e32 v119, v82, v82
	v_max_f32_e32 v80, 0, v92
	v_max_f32_e32 v82, 0, v88
	v_max_f32_e32 v83, 0, v89
	v_max_f32_e32 v84, 0, v94
	v_max_f32_e32 v86, 0, v90
	v_max_f32_e32 v87, 0, v91
	v_max_f32_e32 v88, 0, v114
	v_max_f32_e32 v90, 0, v115
	v_max_f32_e32 v89, 0, v116
	v_max_f32_e32 v91, 0, v117
	v_max_f32_e32 v92, 0, v118
	v_max_f32_e32 v94, 0, v119
	v_or_b32_e32 v114, 48, v144
	v_lshlrev_b64 v[116:117], 13, v[126:127]
	v_ashrrev_i32_e32 v115, 31, v114
	v_lshlrev_b64 v[118:119], 6, v[114:115]
	s_waitcnt vmcnt(0) lgkmcnt(0)
	v_mov_b32_e32 v120, v97
	v_mov_b32_e32 v121, v98
	v_mov_b32_e32 v97, v99
	v_mov_b32_e32 v98, v101
	v_mov_b32_e32 v99, v102
	v_mov_b32_e32 v101, v103
	v_pk_add_f32 v[96:97], v[120:121], v[96:97]
	v_pk_add_f32 v[98:99], v[98:99], v[100:101]
	v_pk_add_f32 v[96:97], v[96:97], v[96:97] op_sel:[0,1] op_sel_hi:[1,0]
	v_pk_add_f32 v[98:99], v[98:99], v[98:99] op_sel:[0,1] op_sel_hi:[1,0]
	v_add_f32_e32 v102, v104, v105
	v_add_f32_e32 v104, v106, v107
	v_mov_b32_e32 v103, v110
	v_mov_b32_e32 v105, v111
	v_mov_b32_e32 v97, v108
	v_mov_b32_e32 v99, v109
	v_pk_add_f32 v[100:101], v[102:103], v[104:105]
	v_pk_add_f32 v[96:97], v[96:97], v[98:99]
	v_lshl_add_u64 v[98:99], s[54:55], 0, v[116:117]
	v_pk_add_f32 v[96:97], v[96:97], v[100:101]
	v_lshl_add_u64 v[98:99], v[98:99], 0, v[112:113]
	v_add_f32_e32 v96, v96, v97
	v_fmamk_f32 v96, v96, 0x3a800000, v150
	v_rsq_f32_e32 v96, v96
	v_lshl_add_u64 v[100:101], s[58:59], 0, v[118:119]
	v_pk_mul_f32 v[80:81], v[80:81], v[96:97] op_sel_hi:[1,0]
	v_pk_mul_f32 v[82:83], v[82:83], v[96:97] op_sel_hi:[1,0]
	v_pk_mul_f32 v[84:85], v[84:85], v[96:97] op_sel_hi:[1,0]
	v_pk_mul_f32 v[86:87], v[86:87], v[96:97] op_sel_hi:[1,0]
	v_pk_mul_f32 v[88:89], v[88:89], v[96:97] op_sel_hi:[1,0]
	v_pk_mul_f32 v[90:91], v[90:91], v[96:97] op_sel_hi:[1,0]
	v_pk_mul_f32 v[92:93], v[92:93], v[96:97] op_sel_hi:[1,0]
	v_pk_mul_f32 v[94:95], v[94:95], v[96:97] op_sel_hi:[1,0]
	v_pk_mul_f32 v[80:81], v[80:81], v[80:81]
	v_pk_mul_f32 v[82:83], v[82:83], v[82:83]
	v_pk_mul_f32 v[84:85], v[84:85], v[84:85]
	v_pk_mul_f32 v[86:87], v[86:87], v[86:87]
	v_pk_mul_f32 v[88:89], v[88:89], v[88:89]
	v_pk_mul_f32 v[90:91], v[90:91], v[90:91]
	v_pk_mul_f32 v[92:93], v[92:93], v[92:93]
	v_pk_mul_f32 v[94:95], v[94:95], v[94:95]
	v_cvt_pk_bf16_f32 v80, v80, v81
	v_cvt_pk_bf16_f32 v81, v84, v85
	v_cvt_pk_bf16_f32 v82, v82, v83
	v_cvt_pk_bf16_f32 v83, v86, v87
	v_cvt_pk_bf16_f32 v84, v88, v89
	v_cvt_pk_bf16_f32 v85, v92, v93
	v_cvt_pk_bf16_f32 v86, v90, v91
	v_cvt_pk_bf16_f32 v87, v94, v95
	global_store_dwordx4 v[98:99], v[80:83], off
	s_nop 0
	global_store_dwordx4 v[98:99], v[84:87], off offset:256
	global_load_dwordx4 v[80:83], v[100:101], off
	s_nop 0
	global_load_dwordx4 v[84:87], v[100:101], off offset:16
	global_load_dwordx4 v[88:91], v[100:101], off offset:32
	global_load_dwordx4 v[92:95], v[100:101], off offset:48
	v_max_f32_e32 v98, v69, v69
	v_max_f32_e32 v99, v65, v65
	v_max_f32_e32 v65, 0, v77
	v_max_f32_e32 v69, 0, v79
	v_max_f32_e32 v77, 0, v71
	v_max_f32_e32 v79, 0, v67
	v_max_f32_e32 v96, v68, v68
	v_max_f32_e32 v97, v64, v64
	v_max_f32_e32 v100, v70, v70
	v_max_f32_e32 v101, v66, v66
	v_max_f32_e32 v64, 0, v76
	v_max_f32_e32 v66, 0, v72
	v_max_f32_e32 v67, 0, v73
	v_max_f32_e32 v68, 0, v78
	v_max_f32_e32 v70, 0, v74
	v_max_f32_e32 v71, 0, v75
	v_max_f32_e32 v72, 0, v96
	v_max_f32_e32 v74, 0, v97
	v_max_f32_e32 v73, 0, v98
	v_max_f32_e32 v75, 0, v99
	v_max_f32_e32 v76, 0, v100
	v_max_f32_e32 v78, 0, v101
	v_add_u32_e32 v96, 0x80, v144
	v_lshlrev_b64 v[98:99], 13, v[114:115]
	v_ashrrev_i32_e32 v97, 31, v96
	v_lshlrev_b64 v[100:101], 6, v[96:97]
	s_waitcnt vmcnt(0) lgkmcnt(0)
; DI u32x4 pack_v8(f32x4 v0, f32x4 v1) { u32x4 w; w.x = pk2(v0[0], v0[1]); w.y = pk2(v0[2], v0[3]); w.z = pk2(v1[0], v1[1]); w.w = pk2(v1[2], v1[3]); return w; }
; DI float rstd16(const float* ssq, int row) { const f32x4* p = (const f32x4*)(ssq + (size_t)row * 16); const f32x4 a = p[0], b = p[1], c = p[2], d = p[3];
;   return __builtin_amdgcn_rsqf((((a[0] + a[1]) + (a[2] + a[3])) + ((b[0] + b[1]) + (b[2] + b[3])) + ((c[0] + c[1]) + (c[2] + c[3])) + ((d[0] + d[1]) + (d[2] + d[3]))) * (1.0f / 1024.0f) + EPS); }
;   DI void operator()(AccRef acc, const Unit& u, int wr, int wc, int fr, int fq) const {
;     ...
;       for (int m = 0; m < 4; ++m) { const int row = rowb + ai * 128 + m * 16; const float rs = rstd16(SSQH, row);
; #pragma unroll
;         for (int bj = 0; bj < 2; ++bj) { f32x4 v0 = acc[ai][bj][m][0], v1 = acc[ai][bj][m][1];
; #pragma unroll
;           for (int j = 0; j < 4; ++j) { const float a = fmaxf(v0[j], 0.f) * rs, b = fmaxf(v1[j], 0.f) * rs; v0[j] = a * a; v1[j] = b * b; }
;           *(u32x4*)(A2 + (size_t)row * DFF + cb + bj * 128) = pack_v8(v0, v1); } }
	v_mov_b32_e32 v102, v81
	v_mov_b32_e32 v103, v82
	v_mov_b32_e32 v81, v83
	v_mov_b32_e32 v82, v85
	v_mov_b32_e32 v83, v86
	v_mov_b32_e32 v85, v87
	v_pk_add_f32 v[80:81], v[102:103], v[80:81]
	v_pk_add_f32 v[82:83], v[82:83], v[84:85]
	v_pk_add_f32 v[80:81], v[80:81], v[80:81] op_sel:[0,1] op_sel_hi:[1,0]
	v_pk_add_f32 v[82:83], v[82:83], v[82:83] op_sel:[0,1] op_sel_hi:[1,0]
	v_add_f32_e32 v86, v88, v89
	v_add_f32_e32 v88, v90, v91
	v_mov_b32_e32 v87, v94
	v_mov_b32_e32 v89, v95
	v_mov_b32_e32 v81, v92
	v_mov_b32_e32 v83, v93
	v_pk_add_f32 v[84:85], v[86:87], v[88:89]
	v_pk_add_f32 v[80:81], v[80:81], v[82:83]
	v_lshl_add_u64 v[82:83], s[54:55], 0, v[98:99]
	v_pk_add_f32 v[80:81], v[80:81], v[84:85]
	v_lshl_add_u64 v[82:83], v[82:83], 0, v[112:113]
	v_add_f32_e32 v80, v80, v81
	v_fmamk_f32 v80, v80, 0x3a800000, v150
	v_rsq_f32_e32 v80, v80
	v_lshl_add_u64 v[84:85], s[58:59], 0, v[100:101]
	v_pk_mul_f32 v[64:65], v[64:65], v[80:81] op_sel_hi:[1,0]
	v_pk_mul_f32 v[66:67], v[66:67], v[80:81] op_sel_hi:[1,0]
	v_pk_mul_f32 v[68:69], v[68:69], v[80:81] op_sel_hi:[1,0]
	v_pk_mul_f32 v[70:71], v[70:71], v[80:81] op_sel_hi:[1,0]
	v_pk_mul_f32 v[72:73], v[72:73], v[80:81] op_sel_hi:[1,0]
	v_pk_mul_f32 v[74:75], v[74:75], v[80:81] op_sel_hi:[1,0]
	v_pk_mul_f32 v[76:77], v[76:77], v[80:81] op_sel_hi:[1,0]
	v_pk_mul_f32 v[78:79], v[78:79], v[80:81] op_sel_hi:[1,0]
	v_pk_mul_f32 v[64:65], v[64:65], v[64:65]
	v_pk_mul_f32 v[66:67], v[66:67], v[66:67]
	v_pk_mul_f32 v[68:69], v[68:69], v[68:69]
	v_pk_mul_f32 v[70:71], v[70:71], v[70:71]
	v_pk_mul_f32 v[72:73], v[72:73], v[72:73]
	v_pk_mul_f32 v[74:75], v[74:75], v[74:75]
	v_pk_mul_f32 v[76:77], v[76:77], v[76:77]
	v_pk_mul_f32 v[78:79], v[78:79], v[78:79]
	v_cvt_pk_bf16_f32 v64, v64, v65
	v_cvt_pk_bf16_f32 v65, v68, v69
	v_cvt_pk_bf16_f32 v66, v66, v67
	v_cvt_pk_bf16_f32 v67, v70, v71
	v_cvt_pk_bf16_f32 v68, v72, v73
	v_cvt_pk_bf16_f32 v69, v76, v77
	v_cvt_pk_bf16_f32 v70, v74, v75
	v_cvt_pk_bf16_f32 v71, v78, v79
	global_store_dwordx4 v[82:83], v[64:67], off
	s_nop 0
	global_store_dwordx4 v[82:83], v[68:71], off offset:256
	global_load_dwordx4 v[64:67], v[84:85], off
	s_nop 0
	global_load_dwordx4 v[68:71], v[84:85], off offset:16
	global_load_dwordx4 v[72:75], v[84:85], off offset:32
	global_load_dwordx4 v[76:79], v[84:85], off offset:48
	v_max_f32_e32 v82, v53, v53
	v_max_f32_e32 v83, v49, v49
	v_max_f32_e32 v49, 0, v61
	v_max_f32_e32 v53, 0, v63
	v_max_f32_e32 v61, 0, v55
	v_max_f32_e32 v63, 0, v51
	v_max_f32_e32 v80, v52, v52
	v_max_f32_e32 v81, v48, v48
	v_max_f32_e32 v84, v54, v54
	v_max_f32_e32 v85, v50, v50
	v_max_f32_e32 v48, 0, v60
	v_max_f32_e32 v50, 0, v56
	v_max_f32_e32 v51, 0, v57
	v_max_f32_e32 v52, 0, v62
	v_max_f32_e32 v54, 0, v58
	v_max_f32_e32 v55, 0, v59
	v_max_f32_e32 v56, 0, v80
	v_max_f32_e32 v58, 0, v81
	v_max_f32_e32 v57, 0, v82
	v_max_f32_e32 v59, 0, v83
	v_max_f32_e32 v60, 0, v84
	v_max_f32_e32 v62, 0, v85
	v_add_u32_e32 v80, 0x90, v144
	v_lshlrev_b64 v[82:83], 13, v[96:97]
	v_ashrrev_i32_e32 v81, 31, v80
	v_lshlrev_b64 v[84:85], 6, v[80:81]
	s_waitcnt vmcnt(0) lgkmcnt(0)
	v_mov_b32_e32 v86, v65
	v_mov_b32_e32 v87, v66
	v_mov_b32_e32 v65, v67
	v_mov_b32_e32 v66, v69
	v_mov_b32_e32 v67, v70
	v_mov_b32_e32 v69, v71
	v_pk_add_f32 v[64:65], v[86:87], v[64:65]
	v_pk_add_f32 v[66:67], v[66:67], v[68:69]
	v_pk_add_f32 v[64:65], v[64:65], v[64:65] op_sel:[0,1] op_sel_hi:[1,0]
	v_pk_add_f32 v[66:67], v[66:67], v[66:67] op_sel:[0,1] op_sel_hi:[1,0]
	v_add_f32_e32 v70, v72, v73
	v_add_f32_e32 v72, v74, v75
	v_mov_b32_e32 v71, v78
	v_mov_b32_e32 v73, v79
	v_mov_b32_e32 v65, v76
	v_mov_b32_e32 v67, v77
	v_pk_add_f32 v[68:69], v[70:71], v[72:73]
	v_pk_add_f32 v[64:65], v[64:65], v[66:67]
	v_lshl_add_u64 v[66:67], s[54:55], 0, v[82:83]
	v_pk_add_f32 v[64:65], v[64:65], v[68:69]
	v_lshl_add_u64 v[66:67], v[66:67], 0, v[112:113]
	v_add_f32_e32 v64, v64, v65
	v_fmamk_f32 v64, v64, 0x3a800000, v150
	v_rsq_f32_e32 v64, v64
	v_lshl_add_u64 v[68:69], s[58:59], 0, v[84:85]
	v_pk_mul_f32 v[48:49], v[48:49], v[64:65] op_sel_hi:[1,0]
	v_pk_mul_f32 v[50:51], v[50:51], v[64:65] op_sel_hi:[1,0]
	v_pk_mul_f32 v[52:53], v[52:53], v[64:65] op_sel_hi:[1,0]
	v_pk_mul_f32 v[54:55], v[54:55], v[64:65] op_sel_hi:[1,0]
	v_pk_mul_f32 v[56:57], v[56:57], v[64:65] op_sel_hi:[1,0]
	v_pk_mul_f32 v[58:59], v[58:59], v[64:65] op_sel_hi:[1,0]
	v_pk_mul_f32 v[60:61], v[60:61], v[64:65] op_sel_hi:[1,0]
	v_pk_mul_f32 v[62:63], v[62:63], v[64:65] op_sel_hi:[1,0]
	v_pk_mul_f32 v[48:49], v[48:49], v[48:49]
	v_pk_mul_f32 v[50:51], v[50:51], v[50:51]
	v_pk_mul_f32 v[52:53], v[52:53], v[52:53]
	v_pk_mul_f32 v[54:55], v[54:55], v[54:55]
	v_pk_mul_f32 v[56:57], v[56:57], v[56:57]
	v_pk_mul_f32 v[58:59], v[58:59], v[58:59]
	v_pk_mul_f32 v[60:61], v[60:61], v[60:61]
	v_pk_mul_f32 v[62:63], v[62:63], v[62:63]
	v_cvt_pk_bf16_f32 v48, v48, v49
	v_cvt_pk_bf16_f32 v49, v52, v53
	v_cvt_pk_bf16_f32 v50, v50, v51
	v_cvt_pk_bf16_f32 v51, v54, v55
	v_cvt_pk_bf16_f32 v52, v56, v57
	v_cvt_pk_bf16_f32 v53, v60, v61
	v_cvt_pk_bf16_f32 v54, v58, v59
	v_cvt_pk_bf16_f32 v55, v62, v63
	global_store_dwordx4 v[66:67], v[48:51], off
	s_nop 0
	global_store_dwordx4 v[66:67], v[52:55], off offset:256
	global_load_dwordx4 v[48:51], v[68:69], off
	s_nop 0
	global_load_dwordx4 v[52:55], v[68:69], off offset:16
	global_load_dwordx4 v[56:59], v[68:69], off offset:32
	global_load_dwordx4 v[60:63], v[68:69], off offset:48
	v_max_f32_e32 v66, v37, v37
	v_max_f32_e32 v67, v33, v33
	v_max_f32_e32 v33, 0, v45
	v_max_f32_e32 v37, 0, v47
	v_max_f32_e32 v45, 0, v39
	v_max_f32_e32 v47, 0, v35
	v_max_f32_e32 v64, v36, v36
	v_max_f32_e32 v65, v32, v32
	v_max_f32_e32 v68, v38, v38
	v_max_f32_e32 v69, v34, v34
	v_max_f32_e32 v32, 0, v44
	v_max_f32_e32 v34, 0, v40
	v_max_f32_e32 v35, 0, v41
	v_max_f32_e32 v36, 0, v46
	v_max_f32_e32 v38, 0, v42
	v_max_f32_e32 v39, 0, v43
	v_max_f32_e32 v40, 0, v64
	v_max_f32_e32 v42, 0, v65
	v_max_f32_e32 v41, 0, v66
	v_max_f32_e32 v43, 0, v67
	v_max_f32_e32 v44, 0, v68
	v_max_f32_e32 v46, 0, v69
	v_add_u32_e32 v64, 0xa0, v144
	v_lshlrev_b64 v[66:67], 13, v[80:81]
	v_ashrrev_i32_e32 v65, 31, v64
	v_lshlrev_b64 v[68:69], 6, v[64:65]
	s_waitcnt vmcnt(0) lgkmcnt(0)
; DI u32x4 pack_v8(f32x4 v0, f32x4 v1) { u32x4 w; w.x = pk2(v0[0], v0[1]); w.y = pk2(v0[2], v0[3]); w.z = pk2(v1[0], v1[1]); w.w = pk2(v1[2], v1[3]); return w; }
; DI float rstd16(const float* ssq, int row) { const f32x4* p = (const f32x4*)(ssq + (size_t)row * 16); const f32x4 a = p[0], b = p[1], c = p[2], d = p[3];
;   return __builtin_amdgcn_rsqf((((a[0] + a[1]) + (a[2] + a[3])) + ((b[0] + b[1]) + (b[2] + b[3])) + ((c[0] + c[1]) + (c[2] + c[3])) + ((d[0] + d[1]) + (d[2] + d[3]))) * (1.0f / 1024.0f) + EPS); }
;   DI void operator()(AccRef acc, const Unit& u, int wr, int wc, int fr, int fq) const {
;     ...
;       for (int m = 0; m < 4; ++m) { const int row = rowb + ai * 128 + m * 16; const float rs = rstd16(SSQH, row);
; #pragma unroll
;         for (int bj = 0; bj < 2; ++bj) { f32x4 v0 = acc[ai][bj][m][0], v1 = acc[ai][bj][m][1];
; #pragma unroll
;           for (int j = 0; j < 4; ++j) { const float a = fmaxf(v0[j], 0.f) * rs, b = fmaxf(v1[j], 0.f) * rs; v0[j] = a * a; v1[j] = b * b; }
;           *(u32x4*)(A2 + (size_t)row * DFF + cb + bj * 128) = pack_v8(v0, v1); } }
	v_mov_b32_e32 v70, v49
	v_mov_b32_e32 v71, v50
	v_mov_b32_e32 v49, v51
	v_mov_b32_e32 v50, v53
	v_mov_b32_e32 v51, v54
	v_mov_b32_e32 v53, v55
	v_pk_add_f32 v[48:49], v[70:71], v[48:49]
	v_pk_add_f32 v[50:51], v[50:51], v[52:53]
	v_pk_add_f32 v[48:49], v[48:49], v[48:49] op_sel:[0,1] op_sel_hi:[1,0]
	v_pk_add_f32 v[50:51], v[50:51], v[50:51] op_sel:[0,1] op_sel_hi:[1,0]
	v_add_f32_e32 v54, v56, v57
	v_add_f32_e32 v56, v58, v59
	v_mov_b32_e32 v55, v62
	v_mov_b32_e32 v57, v63
	v_mov_b32_e32 v49, v60
	v_mov_b32_e32 v51, v61
	v_pk_add_f32 v[52:53], v[54:55], v[56:57]
	v_pk_add_f32 v[48:49], v[48:49], v[50:51]
	v_lshl_add_u64 v[50:51], s[54:55], 0, v[66:67]
	v_pk_add_f32 v[48:49], v[48:49], v[52:53]
	v_lshl_add_u64 v[50:51], v[50:51], 0, v[112:113]
	v_add_f32_e32 v48, v48, v49
	v_fmamk_f32 v48, v48, 0x3a800000, v150
	v_rsq_f32_e32 v48, v48
	v_lshl_add_u64 v[52:53], s[58:59], 0, v[68:69]
	v_pk_mul_f32 v[32:33], v[32:33], v[48:49] op_sel_hi:[1,0]
	v_pk_mul_f32 v[34:35], v[34:35], v[48:49] op_sel_hi:[1,0]
	v_pk_mul_f32 v[36:37], v[36:37], v[48:49] op_sel_hi:[1,0]
	v_pk_mul_f32 v[38:39], v[38:39], v[48:49] op_sel_hi:[1,0]
	v_pk_mul_f32 v[40:41], v[40:41], v[48:49] op_sel_hi:[1,0]
	v_pk_mul_f32 v[42:43], v[42:43], v[48:49] op_sel_hi:[1,0]
	v_pk_mul_f32 v[44:45], v[44:45], v[48:49] op_sel_hi:[1,0]
	v_pk_mul_f32 v[46:47], v[46:47], v[48:49] op_sel_hi:[1,0]
	v_pk_mul_f32 v[32:33], v[32:33], v[32:33]
	v_pk_mul_f32 v[34:35], v[34:35], v[34:35]
	v_pk_mul_f32 v[36:37], v[36:37], v[36:37]
	v_pk_mul_f32 v[38:39], v[38:39], v[38:39]
	v_pk_mul_f32 v[40:41], v[40:41], v[40:41]
	v_pk_mul_f32 v[42:43], v[42:43], v[42:43]
	v_pk_mul_f32 v[44:45], v[44:45], v[44:45]
	v_pk_mul_f32 v[46:47], v[46:47], v[46:47]
	v_cvt_pk_bf16_f32 v32, v32, v33
	v_cvt_pk_bf16_f32 v33, v36, v37
	v_cvt_pk_bf16_f32 v34, v34, v35
	v_cvt_pk_bf16_f32 v35, v38, v39
	v_cvt_pk_bf16_f32 v36, v40, v41
	v_cvt_pk_bf16_f32 v37, v44, v45
	v_cvt_pk_bf16_f32 v38, v42, v43
	v_cvt_pk_bf16_f32 v39, v46, v47
	global_store_dwordx4 v[50:51], v[32:35], off
	s_nop 0
	global_store_dwordx4 v[50:51], v[36:39], off offset:256
	global_load_dwordx4 v[32:35], v[52:53], off
	s_nop 0
	global_load_dwordx4 v[36:39], v[52:53], off offset:16
	global_load_dwordx4 v[40:43], v[52:53], off offset:32
	global_load_dwordx4 v[44:47], v[52:53], off offset:48
	v_max_f32_e32 v50, v21, v21
	v_max_f32_e32 v51, v17, v17
	v_max_f32_e32 v17, 0, v29
	v_max_f32_e32 v21, 0, v31
	v_max_f32_e32 v29, 0, v23
	v_max_f32_e32 v31, 0, v19
	v_max_f32_e32 v48, v20, v20
	v_max_f32_e32 v49, v16, v16
	v_max_f32_e32 v52, v22, v22
	v_max_f32_e32 v53, v18, v18
	v_max_f32_e32 v16, 0, v28
	v_max_f32_e32 v18, 0, v24
	v_max_f32_e32 v19, 0, v25
	v_max_f32_e32 v20, 0, v30
	v_max_f32_e32 v22, 0, v26
	v_max_f32_e32 v23, 0, v27
	v_max_f32_e32 v24, 0, v48
	v_max_f32_e32 v26, 0, v49
	v_max_f32_e32 v25, 0, v50
	v_max_f32_e32 v27, 0, v51
	v_max_f32_e32 v28, 0, v52
	v_max_f32_e32 v30, 0, v53
	v_add_u32_e32 v48, 0xb0, v144
	v_lshlrev_b64 v[50:51], 13, v[64:65]
	v_ashrrev_i32_e32 v49, 31, v48
	v_lshlrev_b64 v[52:53], 6, v[48:49]
	s_waitcnt vmcnt(0) lgkmcnt(0)
; DI float ozero() { float z = 0.f; asm volatile("" : "+v"(z)); return z; }
; DI int otid() { int t = threadIdx.x; asm volatile("" : "+v"(t)); return t; }
; #define PG8_BAR __builtin_amdgcn_s_barrier()
; DI u32x4 pack_v8(f32x4 v0, f32x4 v1) { u32x4 w; w.x = pk2(v0[0], v0[1]); w.y = pk2(v0[2], v0[3]); w.z = pk2(v1[0], v1[1]); w.w = pk2(v1[2], v1[3]); return w; }
; template <class Epi, class Sched>
; DI void gemm_phase(LAS unsigned char* lds, const Gemm g, const Sched& S, const Epi& E) {
;     ...
;     if (wr == 0) PG8_BAR;
;     { const int l2 = otid() & 63; E(acc, cur, wr, wc, l2 & 15, l2 >> 4); }
;     if (!has_next) break;
;     { const float z0 = ozero();
; #pragma unroll
;     for (int a = 0; a < 2; ++a)
; #pragma unroll
;       for (int b = 0; b < 2; ++b)
; #pragma unroll
;         for (int m = 0; m < 4; ++m)
; #pragma unroll
;           for (int n = 0; n < 2; ++n) acc[a][b][m][n] = (f32x4){z0, z0, z0, z0}; }
;     cur = nxt; cA = nA; cB = nB; ++ui;
;     if (wr == 1) PG8_BAR;
;   DI void operator()(AccRef acc, const Unit& u, int wr, int wc, int fr, int fq) const {
;     ...
;       for (int m = 0; m < 4; ++m) { const int row = rowb + ai * 128 + m * 16; const float rs = rstd16(SSQH, row);
; #pragma unroll
;         for (int bj = 0; bj < 2; ++bj) { f32x4 v0 = acc[ai][bj][m][0], v1 = acc[ai][bj][m][1];
; #pragma unroll
;           for (int j = 0; j < 4; ++j) { const float a = fmaxf(v0[j], 0.f) * rs, b = fmaxf(v1[j], 0.f) * rs; v0[j] = a * a; v1[j] = b * b; }
;           *(u32x4*)(A2 + (size_t)row * DFF + cb + bj * 128) = pack_v8(v0, v1); } }
	v_mov_b32_e32 v54, v33
	v_mov_b32_e32 v55, v34
	v_mov_b32_e32 v33, v35
	v_mov_b32_e32 v34, v37
	v_mov_b32_e32 v35, v38
	v_mov_b32_e32 v37, v39
	v_pk_add_f32 v[32:33], v[54:55], v[32:33]
	v_pk_add_f32 v[34:35], v[34:35], v[36:37]
	v_pk_add_f32 v[32:33], v[32:33], v[32:33] op_sel:[0,1] op_sel_hi:[1,0]
	v_pk_add_f32 v[34:35], v[34:35], v[34:35] op_sel:[0,1] op_sel_hi:[1,0]
	v_add_f32_e32 v38, v40, v41
	v_add_f32_e32 v40, v42, v43
	v_mov_b32_e32 v39, v46
	v_mov_b32_e32 v41, v47
	v_mov_b32_e32 v33, v44
	v_mov_b32_e32 v35, v45
	v_pk_add_f32 v[36:37], v[38:39], v[40:41]
	v_pk_add_f32 v[32:33], v[32:33], v[34:35]
	v_lshl_add_u64 v[34:35], s[54:55], 0, v[50:51]
	v_pk_add_f32 v[32:33], v[32:33], v[36:37]
	v_lshl_add_u64 v[34:35], v[34:35], 0, v[112:113]
	v_add_f32_e32 v32, v32, v33
	v_fmamk_f32 v32, v32, 0x3a800000, v150
	v_rsq_f32_e32 v32, v32
	v_lshl_add_u64 v[36:37], s[58:59], 0, v[52:53]
	v_max_f32_e32 v38, v7, v7
	v_max_f32_e32 v39, v3, v3
	v_pk_mul_f32 v[16:17], v[16:17], v[32:33] op_sel_hi:[1,0]
	v_pk_mul_f32 v[18:19], v[18:19], v[32:33] op_sel_hi:[1,0]
	v_pk_mul_f32 v[20:21], v[20:21], v[32:33] op_sel_hi:[1,0]
	v_pk_mul_f32 v[22:23], v[22:23], v[32:33] op_sel_hi:[1,0]
	v_pk_mul_f32 v[24:25], v[24:25], v[32:33] op_sel_hi:[1,0]
	v_pk_mul_f32 v[26:27], v[26:27], v[32:33] op_sel_hi:[1,0]
	v_pk_mul_f32 v[28:29], v[28:29], v[32:33] op_sel_hi:[1,0]
	v_pk_mul_f32 v[30:31], v[30:31], v[32:33] op_sel_hi:[1,0]
	v_pk_mul_f32 v[16:17], v[16:17], v[16:17]
	v_pk_mul_f32 v[18:19], v[18:19], v[18:19]
	v_pk_mul_f32 v[20:21], v[20:21], v[20:21]
	v_pk_mul_f32 v[22:23], v[22:23], v[22:23]
	v_pk_mul_f32 v[24:25], v[24:25], v[24:25]
	v_pk_mul_f32 v[26:27], v[26:27], v[26:27]
	v_pk_mul_f32 v[28:29], v[28:29], v[28:29]
	v_pk_mul_f32 v[30:31], v[30:31], v[30:31]
	v_cvt_pk_bf16_f32 v16, v16, v17
	v_cvt_pk_bf16_f32 v17, v20, v21
	v_cvt_pk_bf16_f32 v18, v18, v19
	v_cvt_pk_bf16_f32 v19, v22, v23
	v_cvt_pk_bf16_f32 v20, v24, v25
	v_cvt_pk_bf16_f32 v21, v28, v29
	v_cvt_pk_bf16_f32 v22, v26, v27
	v_cvt_pk_bf16_f32 v23, v30, v31
	global_store_dwordx4 v[34:35], v[16:19], off
	s_nop 0
	global_store_dwordx4 v[34:35], v[20:23], off offset:256
	global_load_dwordx4 v[16:19], v[36:37], off
	s_nop 0
	global_load_dwordx4 v[20:23], v[36:37], off offset:16
	global_load_dwordx4 v[24:27], v[36:37], off offset:32
	global_load_dwordx4 v[28:31], v[36:37], off offset:48
	v_max_f32_e32 v36, v6, v6
	v_max_f32_e32 v37, v2, v2
	v_max_f32_e32 v2, 0, v8
	v_max_f32_e32 v6, 0, v10
	v_max_f32_e32 v8, 0, v4
	v_max_f32_e32 v10, 0, v0
	v_max_f32_e32 v34, v5, v5
	v_max_f32_e32 v35, v1, v1
	v_max_f32_e32 v0, 0, v12
	v_max_f32_e32 v1, 0, v13
	v_max_f32_e32 v3, 0, v9
	v_max_f32_e32 v4, 0, v14
	v_max_f32_e32 v5, 0, v15
	v_max_f32_e32 v7, 0, v11
	v_max_f32_e32 v9, 0, v34
	v_max_f32_e32 v11, 0, v35
	v_max_f32_e32 v12, 0, v36
	v_max_f32_e32 v14, 0, v37
	v_max_f32_e32 v13, 0, v38
	v_max_f32_e32 v15, 0, v39
	s_waitcnt vmcnt(0) lgkmcnt(0)
	v_mov_b32_e32 v32, v17
	v_mov_b32_e32 v33, v18
	v_mov_b32_e32 v17, v19
	v_mov_b32_e32 v18, v21
	v_mov_b32_e32 v19, v22
	v_mov_b32_e32 v21, v23
	v_pk_add_f32 v[16:17], v[32:33], v[16:17]
	v_pk_add_f32 v[18:19], v[18:19], v[20:21]
	v_pk_add_f32 v[16:17], v[16:17], v[16:17] op_sel:[0,1] op_sel_hi:[1,0]
	v_pk_add_f32 v[18:19], v[18:19], v[18:19] op_sel:[0,1] op_sel_hi:[1,0]
	v_add_f32_e32 v22, v24, v25
	v_add_f32_e32 v24, v26, v27
	v_mov_b32_e32 v23, v30
	v_mov_b32_e32 v25, v31
	v_mov_b32_e32 v17, v28
	v_mov_b32_e32 v19, v29
	v_pk_add_f32 v[20:21], v[22:23], v[24:25]
	v_pk_add_f32 v[16:17], v[16:17], v[18:19]
	v_lshlrev_b64 v[18:19], 13, v[48:49]
	v_pk_add_f32 v[16:17], v[16:17], v[20:21]
	v_lshl_add_u64 v[18:19], s[54:55], 0, v[18:19]
	v_add_f32_e32 v16, v16, v17
	v_fmamk_f32 v16, v16, 0x3a800000, v150
	v_rsq_f32_e32 v16, v16
	v_lshl_add_u64 v[18:19], v[18:19], 0, v[112:113]
	v_pk_mul_f32 v[0:1], v[0:1], v[16:17] op_sel_hi:[1,0]
	v_pk_mul_f32 v[2:3], v[2:3], v[16:17] op_sel_hi:[1,0]
	v_pk_mul_f32 v[4:5], v[4:5], v[16:17] op_sel_hi:[1,0]
	v_pk_mul_f32 v[6:7], v[6:7], v[16:17] op_sel_hi:[1,0]
	v_pk_mul_f32 v[8:9], v[8:9], v[16:17] op_sel_hi:[1,0]
	v_pk_mul_f32 v[10:11], v[10:11], v[16:17] op_sel_hi:[1,0]
	v_pk_mul_f32 v[12:13], v[12:13], v[16:17] op_sel_hi:[1,0]
	v_pk_mul_f32 v[14:15], v[14:15], v[16:17] op_sel_hi:[1,0]
	v_pk_mul_f32 v[0:1], v[0:1], v[0:1]
	v_pk_mul_f32 v[2:3], v[2:3], v[2:3]
	v_pk_mul_f32 v[4:5], v[4:5], v[4:5]
	v_pk_mul_f32 v[6:7], v[6:7], v[6:7]
	v_pk_mul_f32 v[8:9], v[8:9], v[8:9]
	v_pk_mul_f32 v[10:11], v[10:11], v[10:11]
	v_pk_mul_f32 v[12:13], v[12:13], v[12:13]
	v_pk_mul_f32 v[14:15], v[14:15], v[14:15]
	v_cvt_pk_bf16_f32 v0, v0, v1
	v_cvt_pk_bf16_f32 v1, v4, v5
	v_cvt_pk_bf16_f32 v2, v2, v3
	v_cvt_pk_bf16_f32 v3, v6, v7
	v_cvt_pk_bf16_f32 v4, v8, v9
	v_cvt_pk_bf16_f32 v5, v12, v13
	v_cvt_pk_bf16_f32 v6, v10, v11
	v_cvt_pk_bf16_f32 v7, v14, v15
	global_store_dwordx4 v[18:19], v[0:3], off
	global_store_dwordx4 v[18:19], v[4:7], off offset:256
	s_cbranch_vccnz .LBB0_1676
	v_mov_b32_e32 v0, 0
	s_andn2_b64 vcc, exec, s[6:7]
	s_cbranch_vccnz .LBB0_1675
	s_barrier
	s_branch .LBB0_1675

; DI u32x4 pack_v8(f32x4 v0, f32x4 v1) { u32x4 w; w.x = pk2(v0[0], v0[1]); w.y = pk2(v0[2], v0[3]); w.z = pk2(v1[0], v1[1]); w.w = pk2(v1[2], v1[3]); return w; }
; DI float rstd16(const float* ssq, int row) { const f32x4* p = (const f32x4*)(ssq + (size_t)row * 16); const f32x4 a = p[0], b = p[1], c = p[2], d = p[3];
;   return __builtin_amdgcn_rsqf((((a[0] + a[1]) + (a[2] + a[3])) + ((b[0] + b[1]) + (b[2] + b[3])) + ((c[0] + c[1]) + (c[2] + c[3])) + ((d[0] + d[1]) + (d[2] + d[3]))) * (1.0f / 1024.0f) + EPS); }
;   DI void operator()(AccRef acc, const Unit& u, int wr, int wc, int fr, int fq) const {
;     const int rowb = u.pm * 256 + wr * 64 + fr; const int cb = u.pn * 256 + wc * 32 + 8 * fq;
; #pragma unroll
;     for (int ai = 0; ai < 2; ++ai)
; #pragma unroll
;       for (int m = 0; m < 4; ++m) { const int row = rowb + ai * 128 + m * 16; const float rs = rstd16(SSQH, row);
; #pragma unroll
;         for (int bj = 0; bj < 2; ++bj) { f32x4 v0 = acc[ai][bj][m][0], v1 = acc[ai][bj][m][1];
; #pragma unroll
;           for (int j = 0; j < 4; ++j) { const float a = fmaxf(v0[j], 0.f) * rs, b = fmaxf(v1[j], 0.f) * rs; v0[j] = a * a; v1[j] = b * b; }
;           *(u32x4*)(A2 + (size_t)row * DFF + cb + bj * 128) = pack_v8(v0, v1); } }
.LBB0_3006:
	s_lshl_b32 s0, s24, 8
	v_mov_b32_e32 v151, v224
	s_add_i32 s0, s0, s42
	v_and_or_b32 v144, v151, 15, s0
	v_ashrrev_i32_e32 v145, 31, v144
	v_lshlrev_b64 v[152:153], 6, v[144:145]
	v_lshl_add_u64 v[164:165], s[56:57], 0, v[152:153]
	global_load_dwordx4 v[152:155], v[164:165], off
	global_load_dwordx4 v[156:159], v[164:165], off offset:16
	global_load_dwordx4 v[160:163], v[164:165], off offset:32
	s_nop 0
	global_load_dwordx4 v[164:167], v[164:165], off offset:48
	v_max_f32_e32 v169, v117, v117
	v_max_f32_e32 v172, v119, v119
	v_max_f32_e32 v117, 0, v121
	v_max_f32_e32 v119, 0, v127
	v_max_f32_e32 v121, 0, v123
	v_max_f32_e32 v123, 0, v169
	v_max_f32_e32 v127, 0, v172
	v_max_f32_e32 v169, 0, v115
	v_lshlrev_b64 v[172:173], 13, v[144:145]
	s_lshl_b32 s0, s64, 8
	v_max_f32_e32 v171, v114, v114
	v_max_f32_e32 v114, 0, v124
	v_max_f32_e32 v124, 0, v112
	v_lshrrev_b32_e32 v112, 1, v151
	v_and_or_b32 v112, v112, 24, s0
	v_max_f32_e32 v168, v116, v116
	v_max_f32_e32 v170, v118, v118
	v_max_f32_e32 v116, 0, v120
	v_max_f32_e32 v115, 0, v125
	v_max_f32_e32 v118, 0, v126
	v_max_f32_e32 v120, 0, v122
	v_or_b32_e32 v112, s43, v112
	v_max_f32_e32 v122, 0, v168
	v_max_f32_e32 v125, 0, v113
	v_max_f32_e32 v126, 0, v170
	v_max_f32_e32 v168, 0, v171
	v_ashrrev_i32_e32 v113, 31, v112
	v_or_b32_e32 v170, 16, v144
	v_lshlrev_b64 v[112:113], 1, v[112:113]
	v_ashrrev_i32_e32 v171, 31, v170
	v_max_f32_e32 v151, v97, v97
	v_max_f32_e32 v97, 0, v109
	s_waitcnt vmcnt(0) lgkmcnt(0)
	v_mov_b32_e32 v174, v153
	v_mov_b32_e32 v175, v154
	v_mov_b32_e32 v153, v155
	v_mov_b32_e32 v154, v157
	v_mov_b32_e32 v155, v158
	v_mov_b32_e32 v157, v159
	v_pk_add_f32 v[152:153], v[174:175], v[152:153]
	v_pk_add_f32 v[154:155], v[154:155], v[156:157]
	v_pk_add_f32 v[152:153], v[152:153], v[152:153] op_sel:[0,1] op_sel_hi:[1,0]
	v_pk_add_f32 v[154:155], v[154:155], v[154:155] op_sel:[0,1] op_sel_hi:[1,0]
	v_add_f32_e32 v158, v160, v161
	v_add_f32_e32 v160, v162, v163
	v_mov_b32_e32 v159, v166
	v_mov_b32_e32 v161, v167
	v_mov_b32_e32 v153, v164
	v_mov_b32_e32 v155, v165
	v_pk_add_f32 v[156:157], v[158:159], v[160:161]
	v_pk_add_f32 v[152:153], v[152:153], v[154:155]
	v_lshl_add_u64 v[154:155], s[54:55], 0, v[172:173]
	v_pk_add_f32 v[152:153], v[152:153], v[156:157]
	v_lshl_add_u64 v[154:155], v[154:155], 0, v[112:113]
	v_add_f32_e32 v145, v152, v153
	v_fmamk_f32 v145, v145, 0x3a800000, v150
	v_rsq_f32_e32 v152, v145
	v_max_f32_e32 v145, v101, v101
	v_max_f32_e32 v156, v102, v102
	v_max_f32_e32 v157, v98, v98
	v_pk_mul_f32 v[114:115], v[114:115], v[152:153] op_sel_hi:[1,0]
	v_pk_mul_f32 v[116:117], v[116:117], v[152:153] op_sel_hi:[1,0]
	v_pk_mul_f32 v[118:119], v[118:119], v[152:153] op_sel_hi:[1,0]
	v_pk_mul_f32 v[120:121], v[120:121], v[152:153] op_sel_hi:[1,0]
	v_pk_mul_f32 v[122:123], v[122:123], v[152:153] op_sel_hi:[1,0]
	v_pk_mul_f32 v[124:125], v[124:125], v[152:153] op_sel_hi:[1,0]
	v_pk_mul_f32 v[126:127], v[126:127], v[152:153] op_sel_hi:[1,0]
	v_pk_mul_f32 v[152:153], v[168:169], v[152:153] op_sel_hi:[1,0]
	v_pk_mul_f32 v[114:115], v[114:115], v[114:115]
	v_pk_mul_f32 v[116:117], v[116:117], v[116:117]
	v_pk_mul_f32 v[118:119], v[118:119], v[118:119]
	v_pk_mul_f32 v[120:121], v[120:121], v[120:121]
	v_pk_mul_f32 v[122:123], v[122:123], v[122:123]
	v_pk_mul_f32 v[124:125], v[124:125], v[124:125]
	v_pk_mul_f32 v[126:127], v[126:127], v[126:127]
	v_pk_mul_f32 v[152:153], v[152:153], v[152:153]
	v_cvt_pk_bf16_f32 v114, v114, v115
	v_cvt_pk_bf16_f32 v115, v118, v119
	v_cvt_pk_bf16_f32 v116, v116, v117
	v_cvt_pk_bf16_f32 v117, v120, v121
	v_cvt_pk_bf16_f32 v118, v122, v123
	v_cvt_pk_bf16_f32 v119, v126, v127
	v_cvt_pk_bf16_f32 v120, v124, v125
	v_cvt_pk_bf16_f32 v121, v152, v153
	global_store_dwordx4 v[154:155], v[114:117], off
	global_store_dwordx4 v[154:155], v[118:121], off offset:256
	v_max_f32_e32 v158, v103, v103
	v_lshlrev_b64 v[114:115], 6, v[170:171]
	v_lshl_add_u64 v[126:127], s[56:57], 0, v[114:115]
	global_load_dwordx4 v[114:117], v[126:127], off
	global_load_dwordx4 v[118:121], v[126:127], off offset:16
	global_load_dwordx4 v[122:125], v[126:127], off offset:32
	global_load_dwordx4 v[152:155], v[126:127], off offset:48
	v_max_f32_e32 v126, v100, v100
	v_max_f32_e32 v127, v96, v96
	v_max_f32_e32 v159, v99, v99
	v_max_f32_e32 v96, 0, v108
	v_max_f32_e32 v98, 0, v104
	v_max_f32_e32 v99, 0, v105
	v_max_f32_e32 v100, 0, v110
	v_max_f32_e32 v102, 0, v106
	v_max_f32_e32 v101, 0, v111
	v_max_f32_e32 v103, 0, v107
	v_max_f32_e32 v104, 0, v126
	v_max_f32_e32 v106, 0, v127
	v_max_f32_e32 v105, 0, v145
	v_max_f32_e32 v107, 0, v151
	v_max_f32_e32 v108, 0, v156
	v_max_f32_e32 v110, 0, v157
	v_max_f32_e32 v109, 0, v158
	v_max_f32_e32 v111, 0, v159
	v_or_b32_e32 v126, 32, v144
	v_lshlrev_b64 v[156:157], 13, v[170:171]
	v_ashrrev_i32_e32 v127, 31, v126
	v_lshlrev_b64 v[158:159], 6, v[126:127]
	s_andn2_b64 vcc, exec, s[4:5]
	s_mov_b64 s[4:5], -1
	s_waitcnt vmcnt(0) lgkmcnt(0)
; DI u32x4 pack_v8(f32x4 v0, f32x4 v1) { u32x4 w; w.x = pk2(v0[0], v0[1]); w.y = pk2(v0[2], v0[3]); w.z = pk2(v1[0], v1[1]); w.w = pk2(v1[2], v1[3]); return w; }
; DI float rstd16(const float* ssq, int row) { const f32x4* p = (const f32x4*)(ssq + (size_t)row * 16); const f32x4 a = p[0], b = p[1], c = p[2], d = p[3];
;   return __builtin_amdgcn_rsqf((((a[0] + a[1]) + (a[2] + a[3])) + ((b[0] + b[1]) + (b[2] + b[3])) + ((c[0] + c[1]) + (c[2] + c[3])) + ((d[0] + d[1]) + (d[2] + d[3]))) * (1.0f / 1024.0f) + EPS); }
;   DI void operator()(AccRef acc, const Unit& u, int wr, int wc, int fr, int fq) const {
;     ...
;       for (int m = 0; m < 4; ++m) { const int row = rowb + ai * 128 + m * 16; const float rs = rstd16(SSQH, row);
; #pragma unroll
;         for (int bj = 0; bj < 2; ++bj) { f32x4 v0 = acc[ai][bj][m][0], v1 = acc[ai][bj][m][1];
; #pragma unroll
;           for (int j = 0; j < 4; ++j) { const float a = fmaxf(v0[j], 0.f) * rs, b = fmaxf(v1[j], 0.f) * rs; v0[j] = a * a; v1[j] = b * b; }
;           *(u32x4*)(A2 + (size_t)row * DFF + cb + bj * 128) = pack_v8(v0, v1); } }
	v_mov_b32_e32 v160, v115
	v_mov_b32_e32 v161, v116
	v_mov_b32_e32 v115, v117
	v_mov_b32_e32 v116, v119
	v_mov_b32_e32 v117, v120
	v_mov_b32_e32 v119, v121
	v_pk_add_f32 v[114:115], v[160:161], v[114:115]
	v_pk_add_f32 v[116:117], v[116:117], v[118:119]
	v_pk_add_f32 v[114:115], v[114:115], v[114:115] op_sel:[0,1] op_sel_hi:[1,0]
	v_pk_add_f32 v[116:117], v[116:117], v[116:117] op_sel:[0,1] op_sel_hi:[1,0]
	v_add_f32_e32 v120, v122, v123
	v_add_f32_e32 v122, v124, v125
	v_mov_b32_e32 v121, v154
	v_mov_b32_e32 v123, v155
	v_mov_b32_e32 v115, v152
	v_mov_b32_e32 v117, v153
	v_pk_add_f32 v[118:119], v[120:121], v[122:123]
	v_pk_add_f32 v[114:115], v[114:115], v[116:117]
	v_lshl_add_u64 v[116:117], s[54:55], 0, v[156:157]
	v_pk_add_f32 v[114:115], v[114:115], v[118:119]
	v_lshl_add_u64 v[116:117], v[116:117], 0, v[112:113]
	v_add_f32_e32 v114, v114, v115
	v_fmamk_f32 v114, v114, 0x3a800000, v150
	v_rsq_f32_e32 v114, v114
	v_lshl_add_u64 v[118:119], s[56:57], 0, v[158:159]
	v_pk_mul_f32 v[96:97], v[96:97], v[114:115] op_sel_hi:[1,0]
	v_pk_mul_f32 v[98:99], v[98:99], v[114:115] op_sel_hi:[1,0]
	v_pk_mul_f32 v[100:101], v[100:101], v[114:115] op_sel_hi:[1,0]
	v_pk_mul_f32 v[102:103], v[102:103], v[114:115] op_sel_hi:[1,0]
	v_pk_mul_f32 v[104:105], v[104:105], v[114:115] op_sel_hi:[1,0]
	v_pk_mul_f32 v[106:107], v[106:107], v[114:115] op_sel_hi:[1,0]
	v_pk_mul_f32 v[108:109], v[108:109], v[114:115] op_sel_hi:[1,0]
	v_pk_mul_f32 v[110:111], v[110:111], v[114:115] op_sel_hi:[1,0]
	v_pk_mul_f32 v[96:97], v[96:97], v[96:97]
	v_pk_mul_f32 v[98:99], v[98:99], v[98:99]
	v_pk_mul_f32 v[100:101], v[100:101], v[100:101]
	v_pk_mul_f32 v[102:103], v[102:103], v[102:103]
	v_pk_mul_f32 v[104:105], v[104:105], v[104:105]
	v_pk_mul_f32 v[106:107], v[106:107], v[106:107]
	v_pk_mul_f32 v[108:109], v[108:109], v[108:109]
	v_pk_mul_f32 v[110:111], v[110:111], v[110:111]
	v_cvt_pk_bf16_f32 v96, v96, v97
	v_cvt_pk_bf16_f32 v97, v100, v101
	v_cvt_pk_bf16_f32 v98, v98, v99
	v_cvt_pk_bf16_f32 v99, v102, v103
	v_cvt_pk_bf16_f32 v100, v104, v105
	v_cvt_pk_bf16_f32 v101, v108, v109
	v_cvt_pk_bf16_f32 v102, v106, v107
	v_cvt_pk_bf16_f32 v103, v110, v111
	global_store_dwordx4 v[116:117], v[96:99], off
	s_nop 0
	global_store_dwordx4 v[116:117], v[100:103], off offset:256
	global_load_dwordx4 v[96:99], v[118:119], off
	s_nop 0
	global_load_dwordx4 v[100:103], v[118:119], off offset:16
	global_load_dwordx4 v[104:107], v[118:119], off offset:32
	global_load_dwordx4 v[108:111], v[118:119], off offset:48
	v_max_f32_e32 v116, v85, v85
	v_max_f32_e32 v117, v81, v81
	v_max_f32_e32 v81, 0, v93
	v_max_f32_e32 v85, 0, v95
	v_max_f32_e32 v93, 0, v87
	v_max_f32_e32 v95, 0, v83
	v_max_f32_e32 v114, v84, v84
	v_max_f32_e32 v115, v80, v80
	v_max_f32_e32 v118, v86, v86
	v_max_f32_e32 v119, v82, v82
	v_max_f32_e32 v80, 0, v92
	v_max_f32_e32 v82, 0, v88
	v_max_f32_e32 v83, 0, v89
	v_max_f32_e32 v84, 0, v94
	v_max_f32_e32 v86, 0, v90
	v_max_f32_e32 v87, 0, v91
	v_max_f32_e32 v88, 0, v114
	v_max_f32_e32 v90, 0, v115
	v_max_f32_e32 v89, 0, v116
	v_max_f32_e32 v91, 0, v117
	v_max_f32_e32 v92, 0, v118
	v_max_f32_e32 v94, 0, v119
	v_or_b32_e32 v114, 48, v144
	v_lshlrev_b64 v[116:117], 13, v[126:127]
	v_ashrrev_i32_e32 v115, 31, v114
	v_lshlrev_b64 v[118:119], 6, v[114:115]
	s_waitcnt vmcnt(0) lgkmcnt(0)
	v_mov_b32_e32 v120, v97
	v_mov_b32_e32 v121, v98
	v_mov_b32_e32 v97, v99
	v_mov_b32_e32 v98, v101
	v_mov_b32_e32 v99, v102
	v_mov_b32_e32 v101, v103
	v_pk_add_f32 v[96:97], v[120:121], v[96:97]
	v_pk_add_f32 v[98:99], v[98:99], v[100:101]
	v_pk_add_f32 v[96:97], v[96:97], v[96:97] op_sel:[0,1] op_sel_hi:[1,0]
	v_pk_add_f32 v[98:99], v[98:99], v[98:99] op_sel:[0,1] op_sel_hi:[1,0]
	v_add_f32_e32 v102, v104, v105
	v_add_f32_e32 v104, v106, v107
	v_mov_b32_e32 v103, v110
	v_mov_b32_e32 v105, v111
	v_mov_b32_e32 v97, v108
	v_mov_b32_e32 v99, v109
	v_pk_add_f32 v[100:101], v[102:103], v[104:105]
	v_pk_add_f32 v[96:97], v[96:97], v[98:99]
	v_lshl_add_u64 v[98:99], s[54:55], 0, v[116:117]
	v_pk_add_f32 v[96:97], v[96:97], v[100:101]
	v_lshl_add_u64 v[98:99], v[98:99], 0, v[112:113]
	v_add_f32_e32 v96, v96, v97
	v_fmamk_f32 v96, v96, 0x3a800000, v150
	v_rsq_f32_e32 v96, v96
	v_lshl_add_u64 v[100:101], s[56:57], 0, v[118:119]
	v_pk_mul_f32 v[80:81], v[80:81], v[96:97] op_sel_hi:[1,0]
	v_pk_mul_f32 v[82:83], v[82:83], v[96:97] op_sel_hi:[1,0]
	v_pk_mul_f32 v[84:85], v[84:85], v[96:97] op_sel_hi:[1,0]
	v_pk_mul_f32 v[86:87], v[86:87], v[96:97] op_sel_hi:[1,0]
	v_pk_mul_f32 v[88:89], v[88:89], v[96:97] op_sel_hi:[1,0]
	v_pk_mul_f32 v[90:91], v[90:91], v[96:97] op_sel_hi:[1,0]
	v_pk_mul_f32 v[92:93], v[92:93], v[96:97] op_sel_hi:[1,0]
	v_pk_mul_f32 v[94:95], v[94:95], v[96:97] op_sel_hi:[1,0]
	v_pk_mul_f32 v[80:81], v[80:81], v[80:81]
	v_pk_mul_f32 v[82:83], v[82:83], v[82:83]
	v_pk_mul_f32 v[84:85], v[84:85], v[84:85]
	v_pk_mul_f32 v[86:87], v[86:87], v[86:87]
	v_pk_mul_f32 v[88:89], v[88:89], v[88:89]
	v_pk_mul_f32 v[90:91], v[90:91], v[90:91]
	v_pk_mul_f32 v[92:93], v[92:93], v[92:93]
	v_pk_mul_f32 v[94:95], v[94:95], v[94:95]
	v_cvt_pk_bf16_f32 v80, v80, v81
	v_cvt_pk_bf16_f32 v81, v84, v85
	v_cvt_pk_bf16_f32 v82, v82, v83
	v_cvt_pk_bf16_f32 v83, v86, v87
	v_cvt_pk_bf16_f32 v84, v88, v89
	v_cvt_pk_bf16_f32 v85, v92, v93
	v_cvt_pk_bf16_f32 v86, v90, v91
	v_cvt_pk_bf16_f32 v87, v94, v95
	global_store_dwordx4 v[98:99], v[80:83], off
	s_nop 0
	global_store_dwordx4 v[98:99], v[84:87], off offset:256
	global_load_dwordx4 v[80:83], v[100:101], off
	s_nop 0
	global_load_dwordx4 v[84:87], v[100:101], off offset:16
	global_load_dwordx4 v[88:91], v[100:101], off offset:32
	global_load_dwordx4 v[92:95], v[100:101], off offset:48
	v_max_f32_e32 v98, v69, v69
	v_max_f32_e32 v99, v65, v65
	v_max_f32_e32 v65, 0, v77
	v_max_f32_e32 v69, 0, v79
	v_max_f32_e32 v77, 0, v71
	v_max_f32_e32 v79, 0, v67
	v_max_f32_e32 v96, v68, v68
	v_max_f32_e32 v97, v64, v64
	v_max_f32_e32 v100, v70, v70
	v_max_f32_e32 v101, v66, v66
	v_max_f32_e32 v64, 0, v76
	v_max_f32_e32 v66, 0, v72
	v_max_f32_e32 v67, 0, v73
	v_max_f32_e32 v68, 0, v78
	v_max_f32_e32 v70, 0, v74
	v_max_f32_e32 v71, 0, v75
	v_max_f32_e32 v72, 0, v96
	v_max_f32_e32 v74, 0, v97
	v_max_f32_e32 v73, 0, v98
	v_max_f32_e32 v75, 0, v99
	v_max_f32_e32 v76, 0, v100
	v_max_f32_e32 v78, 0, v101
	v_add_u32_e32 v96, 0x80, v144
	v_lshlrev_b64 v[98:99], 13, v[114:115]
	v_ashrrev_i32_e32 v97, 31, v96
	v_lshlrev_b64 v[100:101], 6, v[96:97]
	s_waitcnt vmcnt(0) lgkmcnt(0)
; DI u32x4 pack_v8(f32x4 v0, f32x4 v1) { u32x4 w; w.x = pk2(v0[0], v0[1]); w.y = pk2(v0[2], v0[3]); w.z = pk2(v1[0], v1[1]); w.w = pk2(v1[2], v1[3]); return w; }
; DI float rstd16(const float* ssq, int row) { const f32x4* p = (const f32x4*)(ssq + (size_t)row * 16); const f32x4 a = p[0], b = p[1], c = p[2], d = p[3];
;   return __builtin_amdgcn_rsqf((((a[0] + a[1]) + (a[2] + a[3])) + ((b[0] + b[1]) + (b[2] + b[3])) + ((c[0] + c[1]) + (c[2] + c[3])) + ((d[0] + d[1]) + (d[2] + d[3]))) * (1.0f / 1024.0f) + EPS); }
;   DI void operator()(AccRef acc, const Unit& u, int wr, int wc, int fr, int fq) const {
;     ...
;       for (int m = 0; m < 4; ++m) { const int row = rowb + ai * 128 + m * 16; const float rs = rstd16(SSQH, row);
; #pragma unroll
;         for (int bj = 0; bj < 2; ++bj) { f32x4 v0 = acc[ai][bj][m][0], v1 = acc[ai][bj][m][1];
; #pragma unroll
;           for (int j = 0; j < 4; ++j) { const float a = fmaxf(v0[j], 0.f) * rs, b = fmaxf(v1[j], 0.f) * rs; v0[j] = a * a; v1[j] = b * b; }
;           *(u32x4*)(A2 + (size_t)row * DFF + cb + bj * 128) = pack_v8(v0, v1); } }
	v_mov_b32_e32 v102, v81
	v_mov_b32_e32 v103, v82
	v_mov_b32_e32 v81, v83
	v_mov_b32_e32 v82, v85
	v_mov_b32_e32 v83, v86
	v_mov_b32_e32 v85, v87
	v_pk_add_f32 v[80:81], v[102:103], v[80:81]
	v_pk_add_f32 v[82:83], v[82:83], v[84:85]
	v_pk_add_f32 v[80:81], v[80:81], v[80:81] op_sel:[0,1] op_sel_hi:[1,0]
	v_pk_add_f32 v[82:83], v[82:83], v[82:83] op_sel:[0,1] op_sel_hi:[1,0]
	v_add_f32_e32 v86, v88, v89
	v_add_f32_e32 v88, v90, v91
	v_mov_b32_e32 v87, v94
	v_mov_b32_e32 v89, v95
	v_mov_b32_e32 v81, v92
	v_mov_b32_e32 v83, v93
	v_pk_add_f32 v[84:85], v[86:87], v[88:89]
	v_pk_add_f32 v[80:81], v[80:81], v[82:83]
	v_lshl_add_u64 v[82:83], s[54:55], 0, v[98:99]
	v_pk_add_f32 v[80:81], v[80:81], v[84:85]
	v_lshl_add_u64 v[82:83], v[82:83], 0, v[112:113]
	v_add_f32_e32 v80, v80, v81
	v_fmamk_f32 v80, v80, 0x3a800000, v150
	v_rsq_f32_e32 v80, v80
	v_lshl_add_u64 v[84:85], s[56:57], 0, v[100:101]
	v_pk_mul_f32 v[64:65], v[64:65], v[80:81] op_sel_hi:[1,0]
	v_pk_mul_f32 v[66:67], v[66:67], v[80:81] op_sel_hi:[1,0]
	v_pk_mul_f32 v[68:69], v[68:69], v[80:81] op_sel_hi:[1,0]
	v_pk_mul_f32 v[70:71], v[70:71], v[80:81] op_sel_hi:[1,0]
	v_pk_mul_f32 v[72:73], v[72:73], v[80:81] op_sel_hi:[1,0]
	v_pk_mul_f32 v[74:75], v[74:75], v[80:81] op_sel_hi:[1,0]
	v_pk_mul_f32 v[76:77], v[76:77], v[80:81] op_sel_hi:[1,0]
	v_pk_mul_f32 v[78:79], v[78:79], v[80:81] op_sel_hi:[1,0]
	v_pk_mul_f32 v[64:65], v[64:65], v[64:65]
	v_pk_mul_f32 v[66:67], v[66:67], v[66:67]
	v_pk_mul_f32 v[68:69], v[68:69], v[68:69]
	v_pk_mul_f32 v[70:71], v[70:71], v[70:71]
	v_pk_mul_f32 v[72:73], v[72:73], v[72:73]
	v_pk_mul_f32 v[74:75], v[74:75], v[74:75]
	v_pk_mul_f32 v[76:77], v[76:77], v[76:77]
	v_pk_mul_f32 v[78:79], v[78:79], v[78:79]
	v_cvt_pk_bf16_f32 v64, v64, v65
	v_cvt_pk_bf16_f32 v65, v68, v69
	v_cvt_pk_bf16_f32 v66, v66, v67
	v_cvt_pk_bf16_f32 v67, v70, v71
	v_cvt_pk_bf16_f32 v68, v72, v73
	v_cvt_pk_bf16_f32 v69, v76, v77
	v_cvt_pk_bf16_f32 v70, v74, v75
	v_cvt_pk_bf16_f32 v71, v78, v79
	global_store_dwordx4 v[82:83], v[64:67], off
	s_nop 0
	global_store_dwordx4 v[82:83], v[68:71], off offset:256
	global_load_dwordx4 v[64:67], v[84:85], off
	s_nop 0
	global_load_dwordx4 v[68:71], v[84:85], off offset:16
	global_load_dwordx4 v[72:75], v[84:85], off offset:32
	global_load_dwordx4 v[76:79], v[84:85], off offset:48
	v_max_f32_e32 v82, v53, v53
	v_max_f32_e32 v83, v49, v49
	v_max_f32_e32 v49, 0, v61
	v_max_f32_e32 v53, 0, v63
	v_max_f32_e32 v61, 0, v55
	v_max_f32_e32 v63, 0, v51
	v_max_f32_e32 v80, v52, v52
	v_max_f32_e32 v81, v48, v48
	v_max_f32_e32 v84, v54, v54
	v_max_f32_e32 v85, v50, v50
	v_max_f32_e32 v48, 0, v60
	v_max_f32_e32 v50, 0, v56
	v_max_f32_e32 v51, 0, v57
	v_max_f32_e32 v52, 0, v62
	v_max_f32_e32 v54, 0, v58
	v_max_f32_e32 v55, 0, v59
	v_max_f32_e32 v56, 0, v80
	v_max_f32_e32 v58, 0, v81
	v_max_f32_e32 v57, 0, v82
	v_max_f32_e32 v59, 0, v83
	v_max_f32_e32 v60, 0, v84
	v_max_f32_e32 v62, 0, v85
	v_add_u32_e32 v80, 0x90, v144
	v_lshlrev_b64 v[82:83], 13, v[96:97]
	v_ashrrev_i32_e32 v81, 31, v80
	v_lshlrev_b64 v[84:85], 6, v[80:81]
	s_waitcnt vmcnt(0) lgkmcnt(0)
	v_mov_b32_e32 v86, v65
	v_mov_b32_e32 v87, v66
	v_mov_b32_e32 v65, v67
	v_mov_b32_e32 v66, v69
	v_mov_b32_e32 v67, v70
	v_mov_b32_e32 v69, v71
	v_pk_add_f32 v[64:65], v[86:87], v[64:65]
	v_pk_add_f32 v[66:67], v[66:67], v[68:69]
	v_pk_add_f32 v[64:65], v[64:65], v[64:65] op_sel:[0,1] op_sel_hi:[1,0]
	v_pk_add_f32 v[66:67], v[66:67], v[66:67] op_sel:[0,1] op_sel_hi:[1,0]
	v_add_f32_e32 v70, v72, v73
	v_add_f32_e32 v72, v74, v75
	v_mov_b32_e32 v71, v78
	v_mov_b32_e32 v73, v79
	v_mov_b32_e32 v65, v76
	v_mov_b32_e32 v67, v77
	v_pk_add_f32 v[68:69], v[70:71], v[72:73]
	v_pk_add_f32 v[64:65], v[64:65], v[66:67]
	v_lshl_add_u64 v[66:67], s[54:55], 0, v[82:83]
	v_pk_add_f32 v[64:65], v[64:65], v[68:69]
	v_lshl_add_u64 v[66:67], v[66:67], 0, v[112:113]
	v_add_f32_e32 v64, v64, v65
	v_fmamk_f32 v64, v64, 0x3a800000, v150
	v_rsq_f32_e32 v64, v64
	v_lshl_add_u64 v[68:69], s[56:57], 0, v[84:85]
	v_pk_mul_f32 v[48:49], v[48:49], v[64:65] op_sel_hi:[1,0]
	v_pk_mul_f32 v[50:51], v[50:51], v[64:65] op_sel_hi:[1,0]
	v_pk_mul_f32 v[52:53], v[52:53], v[64:65] op_sel_hi:[1,0]
	v_pk_mul_f32 v[54:55], v[54:55], v[64:65] op_sel_hi:[1,0]
	v_pk_mul_f32 v[56:57], v[56:57], v[64:65] op_sel_hi:[1,0]
	v_pk_mul_f32 v[58:59], v[58:59], v[64:65] op_sel_hi:[1,0]
	v_pk_mul_f32 v[60:61], v[60:61], v[64:65] op_sel_hi:[1,0]
	v_pk_mul_f32 v[62:63], v[62:63], v[64:65] op_sel_hi:[1,0]
	v_pk_mul_f32 v[48:49], v[48:49], v[48:49]
	v_pk_mul_f32 v[50:51], v[50:51], v[50:51]
	v_pk_mul_f32 v[52:53], v[52:53], v[52:53]
	v_pk_mul_f32 v[54:55], v[54:55], v[54:55]
	v_pk_mul_f32 v[56:57], v[56:57], v[56:57]
	v_pk_mul_f32 v[58:59], v[58:59], v[58:59]
	v_pk_mul_f32 v[60:61], v[60:61], v[60:61]
	v_pk_mul_f32 v[62:63], v[62:63], v[62:63]
	v_cvt_pk_bf16_f32 v48, v48, v49
	v_cvt_pk_bf16_f32 v49, v52, v53
	v_cvt_pk_bf16_f32 v50, v50, v51
	v_cvt_pk_bf16_f32 v51, v54, v55
	v_cvt_pk_bf16_f32 v52, v56, v57
	v_cvt_pk_bf16_f32 v53, v60, v61
	v_cvt_pk_bf16_f32 v54, v58, v59
	v_cvt_pk_bf16_f32 v55, v62, v63
	global_store_dwordx4 v[66:67], v[48:51], off
	s_nop 0
	global_store_dwordx4 v[66:67], v[52:55], off offset:256
	global_load_dwordx4 v[48:51], v[68:69], off
	s_nop 0
	global_load_dwordx4 v[52:55], v[68:69], off offset:16
	global_load_dwordx4 v[56:59], v[68:69], off offset:32
	global_load_dwordx4 v[60:63], v[68:69], off offset:48
	v_max_f32_e32 v66, v37, v37
	v_max_f32_e32 v67, v33, v33
	v_max_f32_e32 v33, 0, v45
	v_max_f32_e32 v37, 0, v47
	v_max_f32_e32 v45, 0, v39
	v_max_f32_e32 v47, 0, v35
	v_max_f32_e32 v64, v36, v36
	v_max_f32_e32 v65, v32, v32
	v_max_f32_e32 v68, v38, v38
	v_max_f32_e32 v69, v34, v34
	v_max_f32_e32 v32, 0, v44
	v_max_f32_e32 v34, 0, v40
	v_max_f32_e32 v35, 0, v41
	v_max_f32_e32 v36, 0, v46
	v_max_f32_e32 v38, 0, v42
	v_max_f32_e32 v39, 0, v43
	v_max_f32_e32 v40, 0, v64
	v_max_f32_e32 v42, 0, v65
	v_max_f32_e32 v41, 0, v66
	v_max_f32_e32 v43, 0, v67
	v_max_f32_e32 v44, 0, v68
	v_max_f32_e32 v46, 0, v69
	v_add_u32_e32 v64, 0xa0, v144
	v_lshlrev_b64 v[66:67], 13, v[80:81]
	v_ashrrev_i32_e32 v65, 31, v64
	v_lshlrev_b64 v[68:69], 6, v[64:65]
	s_waitcnt vmcnt(0) lgkmcnt(0)
; DI u32x4 pack_v8(f32x4 v0, f32x4 v1) { u32x4 w; w.x = pk2(v0[0], v0[1]); w.y = pk2(v0[2], v0[3]); w.z = pk2(v1[0], v1[1]); w.w = pk2(v1[2], v1[3]); return w; }
; DI float rstd16(const float* ssq, int row) { const f32x4* p = (const f32x4*)(ssq + (size_t)row * 16); const f32x4 a = p[0], b = p[1], c = p[2], d = p[3];
;   return __builtin_amdgcn_rsqf((((a[0] + a[1]) + (a[2] + a[3])) + ((b[0] + b[1]) + (b[2] + b[3])) + ((c[0] + c[1]) + (c[2] + c[3])) + ((d[0] + d[1]) + (d[2] + d[3]))) * (1.0f / 1024.0f) + EPS); }
;   DI void operator()(AccRef acc, const Unit& u, int wr, int wc, int fr, int fq) const {
;     ...
;       for (int m = 0; m < 4; ++m) { const int row = rowb + ai * 128 + m * 16; const float rs = rstd16(SSQH, row);
; #pragma unroll
;         for (int bj = 0; bj < 2; ++bj) { f32x4 v0 = acc[ai][bj][m][0], v1 = acc[ai][bj][m][1];
; #pragma unroll
;           for (int j = 0; j < 4; ++j) { const float a = fmaxf(v0[j], 0.f) * rs, b = fmaxf(v1[j], 0.f) * rs; v0[j] = a * a; v1[j] = b * b; }
;           *(u32x4*)(A2 + (size_t)row * DFF + cb + bj * 128) = pack_v8(v0, v1); } }
	v_mov_b32_e32 v70, v49
	v_mov_b32_e32 v71, v50
	v_mov_b32_e32 v49, v51
	v_mov_b32_e32 v50, v53
	v_mov_b32_e32 v51, v54
	v_mov_b32_e32 v53, v55
	v_pk_add_f32 v[48:49], v[70:71], v[48:49]
	v_pk_add_f32 v[50:51], v[50:51], v[52:53]
	v_pk_add_f32 v[48:49], v[48:49], v[48:49] op_sel:[0,1] op_sel_hi:[1,0]
	v_pk_add_f32 v[50:51], v[50:51], v[50:51] op_sel:[0,1] op_sel_hi:[1,0]
	v_add_f32_e32 v54, v56, v57
	v_add_f32_e32 v56, v58, v59
	v_mov_b32_e32 v55, v62
	v_mov_b32_e32 v57, v63
	v_mov_b32_e32 v49, v60
	v_mov_b32_e32 v51, v61
	v_pk_add_f32 v[52:53], v[54:55], v[56:57]
	v_pk_add_f32 v[48:49], v[48:49], v[50:51]
	v_lshl_add_u64 v[50:51], s[54:55], 0, v[66:67]
	v_pk_add_f32 v[48:49], v[48:49], v[52:53]
	v_lshl_add_u64 v[50:51], v[50:51], 0, v[112:113]
	v_add_f32_e32 v48, v48, v49
	v_fmamk_f32 v48, v48, 0x3a800000, v150
	v_rsq_f32_e32 v48, v48
	v_lshl_add_u64 v[52:53], s[56:57], 0, v[68:69]
	v_pk_mul_f32 v[32:33], v[32:33], v[48:49] op_sel_hi:[1,0]
	v_pk_mul_f32 v[34:35], v[34:35], v[48:49] op_sel_hi:[1,0]
	v_pk_mul_f32 v[36:37], v[36:37], v[48:49] op_sel_hi:[1,0]
	v_pk_mul_f32 v[38:39], v[38:39], v[48:49] op_sel_hi:[1,0]
	v_pk_mul_f32 v[40:41], v[40:41], v[48:49] op_sel_hi:[1,0]
	v_pk_mul_f32 v[42:43], v[42:43], v[48:49] op_sel_hi:[1,0]
	v_pk_mul_f32 v[44:45], v[44:45], v[48:49] op_sel_hi:[1,0]
	v_pk_mul_f32 v[46:47], v[46:47], v[48:49] op_sel_hi:[1,0]
	v_pk_mul_f32 v[32:33], v[32:33], v[32:33]
	v_pk_mul_f32 v[34:35], v[34:35], v[34:35]
	v_pk_mul_f32 v[36:37], v[36:37], v[36:37]
	v_pk_mul_f32 v[38:39], v[38:39], v[38:39]
	v_pk_mul_f32 v[40:41], v[40:41], v[40:41]
	v_pk_mul_f32 v[42:43], v[42:43], v[42:43]
	v_pk_mul_f32 v[44:45], v[44:45], v[44:45]
	v_pk_mul_f32 v[46:47], v[46:47], v[46:47]
	v_cvt_pk_bf16_f32 v32, v32, v33
	v_cvt_pk_bf16_f32 v33, v36, v37
	v_cvt_pk_bf16_f32 v34, v34, v35
	v_cvt_pk_bf16_f32 v35, v38, v39
	v_cvt_pk_bf16_f32 v36, v40, v41
	v_cvt_pk_bf16_f32 v37, v44, v45
	v_cvt_pk_bf16_f32 v38, v42, v43
	v_cvt_pk_bf16_f32 v39, v46, v47
	global_store_dwordx4 v[50:51], v[32:35], off
	s_nop 0
	global_store_dwordx4 v[50:51], v[36:39], off offset:256
	global_load_dwordx4 v[32:35], v[52:53], off
	s_nop 0
	global_load_dwordx4 v[36:39], v[52:53], off offset:16
	global_load_dwordx4 v[40:43], v[52:53], off offset:32
	global_load_dwordx4 v[44:47], v[52:53], off offset:48
	v_max_f32_e32 v50, v21, v21
	v_max_f32_e32 v51, v17, v17
	v_max_f32_e32 v17, 0, v29
	v_max_f32_e32 v21, 0, v31
	v_max_f32_e32 v29, 0, v23
	v_max_f32_e32 v31, 0, v19
	v_max_f32_e32 v48, v20, v20
	v_max_f32_e32 v49, v16, v16
	v_max_f32_e32 v52, v22, v22
	v_max_f32_e32 v53, v18, v18
	v_max_f32_e32 v16, 0, v28
	v_max_f32_e32 v18, 0, v24
	v_max_f32_e32 v19, 0, v25
	v_max_f32_e32 v20, 0, v30
	v_max_f32_e32 v22, 0, v26
	v_max_f32_e32 v23, 0, v27
	v_max_f32_e32 v24, 0, v48
	v_max_f32_e32 v26, 0, v49
	v_max_f32_e32 v25, 0, v50
	v_max_f32_e32 v27, 0, v51
	v_max_f32_e32 v28, 0, v52
	v_max_f32_e32 v30, 0, v53
	v_add_u32_e32 v48, 0xb0, v144
	v_lshlrev_b64 v[50:51], 13, v[64:65]
	v_ashrrev_i32_e32 v49, 31, v48
	v_lshlrev_b64 v[52:53], 6, v[48:49]
	s_waitcnt vmcnt(0) lgkmcnt(0)
; DI float ozero() { float z = 0.f; asm volatile("" : "+v"(z)); return z; }
; DI int otid() { int t = threadIdx.x; asm volatile("" : "+v"(t)); return t; }
; #define PG8_BAR __builtin_amdgcn_s_barrier()
; DI u32x4 pack_v8(f32x4 v0, f32x4 v1) { u32x4 w; w.x = pk2(v0[0], v0[1]); w.y = pk2(v0[2], v0[3]); w.z = pk2(v1[0], v1[1]); w.w = pk2(v1[2], v1[3]); return w; }
; template <class Epi, class Sched>
; DI void gemm_phase(LAS unsigned char* lds, const Gemm g, const Sched& S, const Epi& E) {
;     ...
;     if (wr == 0) PG8_BAR;
;     { const int l2 = otid() & 63; E(acc, cur, wr, wc, l2 & 15, l2 >> 4); }
;     if (!has_next) break;
;     { const float z0 = ozero();
; #pragma unroll
;     for (int a = 0; a < 2; ++a)
; #pragma unroll
;       for (int b = 0; b < 2; ++b)
; #pragma unroll
;         for (int m = 0; m < 4; ++m)
; #pragma unroll
;           for (int n = 0; n < 2; ++n) acc[a][b][m][n] = (f32x4){z0, z0, z0, z0}; }
;     cur = nxt; cA = nA; cB = nB; ++ui;
;     if (wr == 1) PG8_BAR;
;   DI void operator()(AccRef acc, const Unit& u, int wr, int wc, int fr, int fq) const {
;     ...
;       for (int m = 0; m < 4; ++m) { const int row = rowb + ai * 128 + m * 16; const float rs = rstd16(SSQH, row);
; #pragma unroll
;         for (int bj = 0; bj < 2; ++bj) { f32x4 v0 = acc[ai][bj][m][0], v1 = acc[ai][bj][m][1];
; #pragma unroll
;           for (int j = 0; j < 4; ++j) { const float a = fmaxf(v0[j], 0.f) * rs, b = fmaxf(v1[j], 0.f) * rs; v0[j] = a * a; v1[j] = b * b; }
;           *(u32x4*)(A2 + (size_t)row * DFF + cb + bj * 128) = pack_v8(v0, v1); } }
	v_mov_b32_e32 v54, v33
	v_mov_b32_e32 v55, v34
	v_mov_b32_e32 v33, v35
	v_mov_b32_e32 v34, v37
	v_mov_b32_e32 v35, v38
	v_mov_b32_e32 v37, v39
	v_pk_add_f32 v[32:33], v[54:55], v[32:33]
	v_pk_add_f32 v[34:35], v[34:35], v[36:37]
	v_pk_add_f32 v[32:33], v[32:33], v[32:33] op_sel:[0,1] op_sel_hi:[1,0]
	v_pk_add_f32 v[34:35], v[34:35], v[34:35] op_sel:[0,1] op_sel_hi:[1,0]
	v_add_f32_e32 v38, v40, v41
	v_add_f32_e32 v40, v42, v43
	v_mov_b32_e32 v39, v46
	v_mov_b32_e32 v41, v47
	v_mov_b32_e32 v33, v44
	v_mov_b32_e32 v35, v45
	v_pk_add_f32 v[36:37], v[38:39], v[40:41]
	v_pk_add_f32 v[32:33], v[32:33], v[34:35]
	v_lshl_add_u64 v[34:35], s[54:55], 0, v[50:51]
	v_pk_add_f32 v[32:33], v[32:33], v[36:37]
	v_lshl_add_u64 v[34:35], v[34:35], 0, v[112:113]
	v_add_f32_e32 v32, v32, v33
	v_fmamk_f32 v32, v32, 0x3a800000, v150
	v_rsq_f32_e32 v32, v32
	v_lshl_add_u64 v[36:37], s[56:57], 0, v[52:53]
	v_max_f32_e32 v38, v7, v7
	v_max_f32_e32 v39, v3, v3
	v_pk_mul_f32 v[16:17], v[16:17], v[32:33] op_sel_hi:[1,0]
	v_pk_mul_f32 v[18:19], v[18:19], v[32:33] op_sel_hi:[1,0]
	v_pk_mul_f32 v[20:21], v[20:21], v[32:33] op_sel_hi:[1,0]
	v_pk_mul_f32 v[22:23], v[22:23], v[32:33] op_sel_hi:[1,0]
	v_pk_mul_f32 v[24:25], v[24:25], v[32:33] op_sel_hi:[1,0]
	v_pk_mul_f32 v[26:27], v[26:27], v[32:33] op_sel_hi:[1,0]
	v_pk_mul_f32 v[28:29], v[28:29], v[32:33] op_sel_hi:[1,0]
	v_pk_mul_f32 v[30:31], v[30:31], v[32:33] op_sel_hi:[1,0]
	v_pk_mul_f32 v[16:17], v[16:17], v[16:17]
	v_pk_mul_f32 v[18:19], v[18:19], v[18:19]
	v_pk_mul_f32 v[20:21], v[20:21], v[20:21]
	v_pk_mul_f32 v[22:23], v[22:23], v[22:23]
	v_pk_mul_f32 v[24:25], v[24:25], v[24:25]
	v_pk_mul_f32 v[26:27], v[26:27], v[26:27]
	v_pk_mul_f32 v[28:29], v[28:29], v[28:29]
	v_pk_mul_f32 v[30:31], v[30:31], v[30:31]
	v_cvt_pk_bf16_f32 v16, v16, v17
	v_cvt_pk_bf16_f32 v17, v20, v21
	v_cvt_pk_bf16_f32 v18, v18, v19
	v_cvt_pk_bf16_f32 v19, v22, v23
	v_cvt_pk_bf16_f32 v20, v24, v25
	v_cvt_pk_bf16_f32 v21, v28, v29
	v_cvt_pk_bf16_f32 v22, v26, v27
	v_cvt_pk_bf16_f32 v23, v30, v31
	global_store_dwordx4 v[34:35], v[16:19], off
	s_nop 0
	global_store_dwordx4 v[34:35], v[20:23], off offset:256
	global_load_dwordx4 v[16:19], v[36:37], off
	s_nop 0
	global_load_dwordx4 v[20:23], v[36:37], off offset:16
	global_load_dwordx4 v[24:27], v[36:37], off offset:32
	global_load_dwordx4 v[28:31], v[36:37], off offset:48
	v_max_f32_e32 v36, v6, v6
	v_max_f32_e32 v37, v2, v2
	v_max_f32_e32 v2, 0, v8
	v_max_f32_e32 v6, 0, v10
	v_max_f32_e32 v8, 0, v4
	v_max_f32_e32 v10, 0, v0
	v_max_f32_e32 v34, v5, v5
	v_max_f32_e32 v35, v1, v1
	v_max_f32_e32 v0, 0, v12
	v_max_f32_e32 v1, 0, v13
	v_max_f32_e32 v3, 0, v9
	v_max_f32_e32 v4, 0, v14
	v_max_f32_e32 v5, 0, v15
	v_max_f32_e32 v7, 0, v11
	v_max_f32_e32 v9, 0, v34
	v_max_f32_e32 v11, 0, v35
	v_max_f32_e32 v12, 0, v36
	v_max_f32_e32 v14, 0, v37
	v_max_f32_e32 v13, 0, v38
	v_max_f32_e32 v15, 0, v39
	s_waitcnt vmcnt(0) lgkmcnt(0)
	v_mov_b32_e32 v32, v17
	v_mov_b32_e32 v33, v18
	v_mov_b32_e32 v17, v19
	v_mov_b32_e32 v18, v21
	v_mov_b32_e32 v19, v22
	v_mov_b32_e32 v21, v23
	v_pk_add_f32 v[16:17], v[32:33], v[16:17]
	v_pk_add_f32 v[18:19], v[18:19], v[20:21]
	v_pk_add_f32 v[16:17], v[16:17], v[16:17] op_sel:[0,1] op_sel_hi:[1,0]
	v_pk_add_f32 v[18:19], v[18:19], v[18:19] op_sel:[0,1] op_sel_hi:[1,0]
	v_add_f32_e32 v22, v24, v25
	v_add_f32_e32 v24, v26, v27
	v_mov_b32_e32 v23, v30
	v_mov_b32_e32 v25, v31
	v_mov_b32_e32 v17, v28
	v_mov_b32_e32 v19, v29
	v_pk_add_f32 v[20:21], v[22:23], v[24:25]
	v_pk_add_f32 v[16:17], v[16:17], v[18:19]
	v_lshlrev_b64 v[18:19], 13, v[48:49]
	v_pk_add_f32 v[16:17], v[16:17], v[20:21]
	v_lshl_add_u64 v[18:19], s[54:55], 0, v[18:19]
	v_add_f32_e32 v16, v16, v17
	v_fmamk_f32 v16, v16, 0x3a800000, v150
	v_rsq_f32_e32 v16, v16
	v_lshl_add_u64 v[18:19], v[18:19], 0, v[112:113]
	v_pk_mul_f32 v[0:1], v[0:1], v[16:17] op_sel_hi:[1,0]
	v_pk_mul_f32 v[2:3], v[2:3], v[16:17] op_sel_hi:[1,0]
	v_pk_mul_f32 v[4:5], v[4:5], v[16:17] op_sel_hi:[1,0]
	v_pk_mul_f32 v[6:7], v[6:7], v[16:17] op_sel_hi:[1,0]
	v_pk_mul_f32 v[8:9], v[8:9], v[16:17] op_sel_hi:[1,0]
	v_pk_mul_f32 v[10:11], v[10:11], v[16:17] op_sel_hi:[1,0]
	v_pk_mul_f32 v[12:13], v[12:13], v[16:17] op_sel_hi:[1,0]
	v_pk_mul_f32 v[14:15], v[14:15], v[16:17] op_sel_hi:[1,0]
	v_pk_mul_f32 v[0:1], v[0:1], v[0:1]
	v_pk_mul_f32 v[2:3], v[2:3], v[2:3]
	v_pk_mul_f32 v[4:5], v[4:5], v[4:5]
	v_pk_mul_f32 v[6:7], v[6:7], v[6:7]
	v_pk_mul_f32 v[8:9], v[8:9], v[8:9]
	v_pk_mul_f32 v[10:11], v[10:11], v[10:11]
	v_pk_mul_f32 v[12:13], v[12:13], v[12:13]
	v_pk_mul_f32 v[14:15], v[14:15], v[14:15]
	v_cvt_pk_bf16_f32 v0, v0, v1
	v_cvt_pk_bf16_f32 v1, v4, v5
	v_cvt_pk_bf16_f32 v2, v2, v3
	v_cvt_pk_bf16_f32 v3, v6, v7
	v_cvt_pk_bf16_f32 v4, v8, v9
	v_cvt_pk_bf16_f32 v5, v12, v13
	v_cvt_pk_bf16_f32 v6, v10, v11
	v_cvt_pk_bf16_f32 v7, v14, v15
	global_store_dwordx4 v[18:19], v[0:3], off
	global_store_dwordx4 v[18:19], v[4:7], off offset:256
	s_cbranch_vccnz .LBB0_2999
	v_mov_b32_e32 v0, 0
	s_andn2_b64 vcc, exec, s[6:7]
	s_cbranch_vccnz .LBB0_2998
	s_barrier
	s_branch .LBB0_2998

; DI u32x4 pack_v8(f32x4 v0, f32x4 v1) { u32x4 w; w.x = pk2(v0[0], v0[1]); w.y = pk2(v0[2], v0[3]); w.z = pk2(v1[0], v1[1]); w.w = pk2(v1[2], v1[3]); return w; }
; DI float rstd16(const float* ssq, int row) { const f32x4* p = (const f32x4*)(ssq + (size_t)row * 16); const f32x4 a = p[0], b = p[1], c = p[2], d = p[3];
;   return __builtin_amdgcn_rsqf((((a[0] + a[1]) + (a[2] + a[3])) + ((b[0] + b[1]) + (b[2] + b[3])) + ((c[0] + c[1]) + (c[2] + c[3])) + ((d[0] + d[1]) + (d[2] + d[3]))) * (1.0f / 1024.0f) + EPS); }
;   DI void operator()(AccRef acc, const Unit& u, int wr, int wc, int fr, int fq) const {
;     const int rowb = u.pm * 256 + wr * 64 + fr; const int cb = u.pn * 256 + wc * 32 + 8 * fq;
; #pragma unroll
;     for (int ai = 0; ai < 2; ++ai)
; #pragma unroll
;       for (int m = 0; m < 4; ++m) { const int row = rowb + ai * 128 + m * 16; const float rs = rstd16(SSQH, row);
; #pragma unroll
;         for (int bj = 0; bj < 2; ++bj) { f32x4 v0 = acc[ai][bj][m][0], v1 = acc[ai][bj][m][1];
; #pragma unroll
;           for (int j = 0; j < 4; ++j) { const float a = fmaxf(v0[j], 0.f) * rs, b = fmaxf(v1[j], 0.f) * rs; v0[j] = a * a; v1[j] = b * b; }
;           *(u32x4*)(A2 + (size_t)row * DFF + cb + bj * 128) = pack_v8(v0, v1); } }
.LBB0_3782:
	s_lshl_b32 s0, s22, 8
	v_mov_b32_e32 v151, v224
	s_add_i32 s0, s0, s36
	v_and_or_b32 v144, v151, 15, s0
	v_ashrrev_i32_e32 v145, 31, v144
	v_lshlrev_b64 v[152:153], 6, v[144:145]
	v_lshl_add_u64 v[164:165], s[58:59], 0, v[152:153]
	global_load_dwordx4 v[152:155], v[164:165], off
	global_load_dwordx4 v[156:159], v[164:165], off offset:16
	global_load_dwordx4 v[160:163], v[164:165], off offset:32
	s_nop 0
	global_load_dwordx4 v[164:167], v[164:165], off offset:48
	v_max_f32_e32 v169, v117, v117
	v_max_f32_e32 v172, v119, v119
	v_max_f32_e32 v117, 0, v121
	v_max_f32_e32 v119, 0, v127
	v_max_f32_e32 v121, 0, v123
	v_max_f32_e32 v123, 0, v169
	v_max_f32_e32 v127, 0, v172
	v_max_f32_e32 v169, 0, v115
	v_lshlrev_b64 v[172:173], 13, v[144:145]
	s_lshl_b32 s0, s57, 8
	v_max_f32_e32 v171, v114, v114
	v_max_f32_e32 v114, 0, v124
	v_max_f32_e32 v124, 0, v112
	v_lshrrev_b32_e32 v112, 1, v151
	v_and_or_b32 v112, v112, 24, s0
	v_max_f32_e32 v168, v116, v116
	v_max_f32_e32 v170, v118, v118
	v_max_f32_e32 v116, 0, v120
	v_max_f32_e32 v115, 0, v125
	v_max_f32_e32 v118, 0, v126
	v_max_f32_e32 v120, 0, v122
	v_or_b32_e32 v112, s37, v112
	v_max_f32_e32 v122, 0, v168
	v_max_f32_e32 v125, 0, v113
	v_max_f32_e32 v126, 0, v170
	v_max_f32_e32 v168, 0, v171
	v_ashrrev_i32_e32 v113, 31, v112
	v_or_b32_e32 v170, 16, v144
	v_lshlrev_b64 v[112:113], 1, v[112:113]
	v_ashrrev_i32_e32 v171, 31, v170
	v_max_f32_e32 v151, v97, v97
	v_max_f32_e32 v97, 0, v109
	s_waitcnt vmcnt(0) lgkmcnt(0)
	v_mov_b32_e32 v174, v153
	v_mov_b32_e32 v175, v154
	v_mov_b32_e32 v153, v155
	v_mov_b32_e32 v154, v157
	v_mov_b32_e32 v155, v158
	v_mov_b32_e32 v157, v159
	v_pk_add_f32 v[152:153], v[174:175], v[152:153]
	v_pk_add_f32 v[154:155], v[154:155], v[156:157]
	v_pk_add_f32 v[152:153], v[152:153], v[152:153] op_sel:[0,1] op_sel_hi:[1,0]
	v_pk_add_f32 v[154:155], v[154:155], v[154:155] op_sel:[0,1] op_sel_hi:[1,0]
	v_add_f32_e32 v158, v160, v161
	v_add_f32_e32 v160, v162, v163
	v_mov_b32_e32 v159, v166
	v_mov_b32_e32 v161, v167
	v_mov_b32_e32 v153, v164
	v_mov_b32_e32 v155, v165
	v_pk_add_f32 v[156:157], v[158:159], v[160:161]
	v_pk_add_f32 v[152:153], v[152:153], v[154:155]
	v_lshl_add_u64 v[154:155], s[50:51], 0, v[172:173]
	v_pk_add_f32 v[152:153], v[152:153], v[156:157]
	v_lshl_add_u64 v[154:155], v[154:155], 0, v[112:113]
	v_add_f32_e32 v145, v152, v153
	v_fmamk_f32 v145, v145, 0x3a800000, v150
	v_rsq_f32_e32 v152, v145
	v_max_f32_e32 v145, v101, v101
	v_max_f32_e32 v156, v102, v102
	v_max_f32_e32 v157, v98, v98
	v_pk_mul_f32 v[114:115], v[114:115], v[152:153] op_sel_hi:[1,0]
	v_pk_mul_f32 v[116:117], v[116:117], v[152:153] op_sel_hi:[1,0]
	v_pk_mul_f32 v[118:119], v[118:119], v[152:153] op_sel_hi:[1,0]
	v_pk_mul_f32 v[120:121], v[120:121], v[152:153] op_sel_hi:[1,0]
	v_pk_mul_f32 v[122:123], v[122:123], v[152:153] op_sel_hi:[1,0]
	v_pk_mul_f32 v[124:125], v[124:125], v[152:153] op_sel_hi:[1,0]
	v_pk_mul_f32 v[126:127], v[126:127], v[152:153] op_sel_hi:[1,0]
	v_pk_mul_f32 v[152:153], v[168:169], v[152:153] op_sel_hi:[1,0]
	v_pk_mul_f32 v[114:115], v[114:115], v[114:115]
	v_pk_mul_f32 v[116:117], v[116:117], v[116:117]
	v_pk_mul_f32 v[118:119], v[118:119], v[118:119]
	v_pk_mul_f32 v[120:121], v[120:121], v[120:121]
	v_pk_mul_f32 v[122:123], v[122:123], v[122:123]
	v_pk_mul_f32 v[124:125], v[124:125], v[124:125]
	v_pk_mul_f32 v[126:127], v[126:127], v[126:127]
	v_pk_mul_f32 v[152:153], v[152:153], v[152:153]
	v_cvt_pk_bf16_f32 v114, v114, v115
	v_cvt_pk_bf16_f32 v115, v118, v119
	v_cvt_pk_bf16_f32 v116, v116, v117
	v_cvt_pk_bf16_f32 v117, v120, v121
	v_cvt_pk_bf16_f32 v118, v122, v123
	v_cvt_pk_bf16_f32 v119, v126, v127
	v_cvt_pk_bf16_f32 v120, v124, v125
	v_cvt_pk_bf16_f32 v121, v152, v153
	global_store_dwordx4 v[154:155], v[114:117], off
	global_store_dwordx4 v[154:155], v[118:121], off offset:256
	v_max_f32_e32 v158, v103, v103
	v_lshlrev_b64 v[114:115], 6, v[170:171]
	v_lshl_add_u64 v[126:127], s[58:59], 0, v[114:115]
	global_load_dwordx4 v[114:117], v[126:127], off
	global_load_dwordx4 v[118:121], v[126:127], off offset:16
	global_load_dwordx4 v[122:125], v[126:127], off offset:32
	global_load_dwordx4 v[152:155], v[126:127], off offset:48
	v_max_f32_e32 v126, v100, v100
	v_max_f32_e32 v127, v96, v96
	v_max_f32_e32 v159, v99, v99
	v_max_f32_e32 v96, 0, v108
	v_max_f32_e32 v98, 0, v104
	v_max_f32_e32 v99, 0, v105
	v_max_f32_e32 v100, 0, v110
	v_max_f32_e32 v102, 0, v106
	v_max_f32_e32 v101, 0, v111
	v_max_f32_e32 v103, 0, v107
	v_max_f32_e32 v104, 0, v126
	v_max_f32_e32 v106, 0, v127
	v_max_f32_e32 v105, 0, v145
	v_max_f32_e32 v107, 0, v151
	v_max_f32_e32 v108, 0, v156
	v_max_f32_e32 v110, 0, v157
	v_max_f32_e32 v109, 0, v158
	v_max_f32_e32 v111, 0, v159
	v_or_b32_e32 v126, 32, v144
	v_lshlrev_b64 v[156:157], 13, v[170:171]
	v_ashrrev_i32_e32 v127, 31, v126
	v_lshlrev_b64 v[158:159], 6, v[126:127]
	s_andn2_b64 vcc, exec, s[4:5]
	s_mov_b64 s[4:5], -1
	s_waitcnt vmcnt(0) lgkmcnt(0)
; DI u32x4 pack_v8(f32x4 v0, f32x4 v1) { u32x4 w; w.x = pk2(v0[0], v0[1]); w.y = pk2(v0[2], v0[3]); w.z = pk2(v1[0], v1[1]); w.w = pk2(v1[2], v1[3]); return w; }
; DI float rstd16(const float* ssq, int row) { const f32x4* p = (const f32x4*)(ssq + (size_t)row * 16); const f32x4 a = p[0], b = p[1], c = p[2], d = p[3];
;   return __builtin_amdgcn_rsqf((((a[0] + a[1]) + (a[2] + a[3])) + ((b[0] + b[1]) + (b[2] + b[3])) + ((c[0] + c[1]) + (c[2] + c[3])) + ((d[0] + d[1]) + (d[2] + d[3]))) * (1.0f / 1024.0f) + EPS); }
;   DI void operator()(AccRef acc, const Unit& u, int wr, int wc, int fr, int fq) const {
;     ...
;       for (int m = 0; m < 4; ++m) { const int row = rowb + ai * 128 + m * 16; const float rs = rstd16(SSQH, row);
; #pragma unroll
;         for (int bj = 0; bj < 2; ++bj) { f32x4 v0 = acc[ai][bj][m][0], v1 = acc[ai][bj][m][1];
; #pragma unroll
;           for (int j = 0; j < 4; ++j) { const float a = fmaxf(v0[j], 0.f) * rs, b = fmaxf(v1[j], 0.f) * rs; v0[j] = a * a; v1[j] = b * b; }
;           *(u32x4*)(A2 + (size_t)row * DFF + cb + bj * 128) = pack_v8(v0, v1); } }
	v_mov_b32_e32 v160, v115
	v_mov_b32_e32 v161, v116
	v_mov_b32_e32 v115, v117
	v_mov_b32_e32 v116, v119
	v_mov_b32_e32 v117, v120
	v_mov_b32_e32 v119, v121
	v_pk_add_f32 v[114:115], v[160:161], v[114:115]
	v_pk_add_f32 v[116:117], v[116:117], v[118:119]
	v_pk_add_f32 v[114:115], v[114:115], v[114:115] op_sel:[0,1] op_sel_hi:[1,0]
	v_pk_add_f32 v[116:117], v[116:117], v[116:117] op_sel:[0,1] op_sel_hi:[1,0]
	v_add_f32_e32 v120, v122, v123
	v_add_f32_e32 v122, v124, v125
	v_mov_b32_e32 v121, v154
	v_mov_b32_e32 v123, v155
	v_mov_b32_e32 v115, v152
	v_mov_b32_e32 v117, v153
	v_pk_add_f32 v[118:119], v[120:121], v[122:123]
	v_pk_add_f32 v[114:115], v[114:115], v[116:117]
	v_lshl_add_u64 v[116:117], s[50:51], 0, v[156:157]
	v_pk_add_f32 v[114:115], v[114:115], v[118:119]
	v_lshl_add_u64 v[116:117], v[116:117], 0, v[112:113]
	v_add_f32_e32 v114, v114, v115
	v_fmamk_f32 v114, v114, 0x3a800000, v150
	v_rsq_f32_e32 v114, v114
	v_lshl_add_u64 v[118:119], s[58:59], 0, v[158:159]
	v_pk_mul_f32 v[96:97], v[96:97], v[114:115] op_sel_hi:[1,0]
	v_pk_mul_f32 v[98:99], v[98:99], v[114:115] op_sel_hi:[1,0]
	v_pk_mul_f32 v[100:101], v[100:101], v[114:115] op_sel_hi:[1,0]
	v_pk_mul_f32 v[102:103], v[102:103], v[114:115] op_sel_hi:[1,0]
	v_pk_mul_f32 v[104:105], v[104:105], v[114:115] op_sel_hi:[1,0]
	v_pk_mul_f32 v[106:107], v[106:107], v[114:115] op_sel_hi:[1,0]
	v_pk_mul_f32 v[108:109], v[108:109], v[114:115] op_sel_hi:[1,0]
	v_pk_mul_f32 v[110:111], v[110:111], v[114:115] op_sel_hi:[1,0]
	v_pk_mul_f32 v[96:97], v[96:97], v[96:97]
	v_pk_mul_f32 v[98:99], v[98:99], v[98:99]
	v_pk_mul_f32 v[100:101], v[100:101], v[100:101]
	v_pk_mul_f32 v[102:103], v[102:103], v[102:103]
	v_pk_mul_f32 v[104:105], v[104:105], v[104:105]
	v_pk_mul_f32 v[106:107], v[106:107], v[106:107]
	v_pk_mul_f32 v[108:109], v[108:109], v[108:109]
	v_pk_mul_f32 v[110:111], v[110:111], v[110:111]
	v_cvt_pk_bf16_f32 v96, v96, v97
	v_cvt_pk_bf16_f32 v97, v100, v101
	v_cvt_pk_bf16_f32 v98, v98, v99
	v_cvt_pk_bf16_f32 v99, v102, v103
	v_cvt_pk_bf16_f32 v100, v104, v105
	v_cvt_pk_bf16_f32 v101, v108, v109
	v_cvt_pk_bf16_f32 v102, v106, v107
	v_cvt_pk_bf16_f32 v103, v110, v111
	global_store_dwordx4 v[116:117], v[96:99], off
	s_nop 0
	global_store_dwordx4 v[116:117], v[100:103], off offset:256
	global_load_dwordx4 v[96:99], v[118:119], off
	s_nop 0
	global_load_dwordx4 v[100:103], v[118:119], off offset:16
	global_load_dwordx4 v[104:107], v[118:119], off offset:32
	global_load_dwordx4 v[108:111], v[118:119], off offset:48
	v_max_f32_e32 v116, v85, v85
	v_max_f32_e32 v117, v81, v81
	v_max_f32_e32 v81, 0, v93
	v_max_f32_e32 v85, 0, v95
	v_max_f32_e32 v93, 0, v87
	v_max_f32_e32 v95, 0, v83
	v_max_f32_e32 v114, v84, v84
	v_max_f32_e32 v115, v80, v80
	v_max_f32_e32 v118, v86, v86
	v_max_f32_e32 v119, v82, v82
	v_max_f32_e32 v80, 0, v92
	v_max_f32_e32 v82, 0, v88
	v_max_f32_e32 v83, 0, v89
	v_max_f32_e32 v84, 0, v94
	v_max_f32_e32 v86, 0, v90
	v_max_f32_e32 v87, 0, v91
	v_max_f32_e32 v88, 0, v114
	v_max_f32_e32 v90, 0, v115
	v_max_f32_e32 v89, 0, v116
	v_max_f32_e32 v91, 0, v117
	v_max_f32_e32 v92, 0, v118
	v_max_f32_e32 v94, 0, v119
	v_or_b32_e32 v114, 48, v144
	v_lshlrev_b64 v[116:117], 13, v[126:127]
	v_ashrrev_i32_e32 v115, 31, v114
	v_lshlrev_b64 v[118:119], 6, v[114:115]
	s_waitcnt vmcnt(0) lgkmcnt(0)
	v_mov_b32_e32 v120, v97
	v_mov_b32_e32 v121, v98
	v_mov_b32_e32 v97, v99
	v_mov_b32_e32 v98, v101
	v_mov_b32_e32 v99, v102
	v_mov_b32_e32 v101, v103
	v_pk_add_f32 v[96:97], v[120:121], v[96:97]
	v_pk_add_f32 v[98:99], v[98:99], v[100:101]
	v_pk_add_f32 v[96:97], v[96:97], v[96:97] op_sel:[0,1] op_sel_hi:[1,0]
	v_pk_add_f32 v[98:99], v[98:99], v[98:99] op_sel:[0,1] op_sel_hi:[1,0]
	v_add_f32_e32 v102, v104, v105
	v_add_f32_e32 v104, v106, v107
	v_mov_b32_e32 v103, v110
	v_mov_b32_e32 v105, v111
	v_mov_b32_e32 v97, v108
	v_mov_b32_e32 v99, v109
	v_pk_add_f32 v[100:101], v[102:103], v[104:105]
	v_pk_add_f32 v[96:97], v[96:97], v[98:99]
	v_lshl_add_u64 v[98:99], s[50:51], 0, v[116:117]
	v_pk_add_f32 v[96:97], v[96:97], v[100:101]
	v_lshl_add_u64 v[98:99], v[98:99], 0, v[112:113]
	v_add_f32_e32 v96, v96, v97
	v_fmamk_f32 v96, v96, 0x3a800000, v150
	v_rsq_f32_e32 v96, v96
	v_lshl_add_u64 v[100:101], s[58:59], 0, v[118:119]
	v_pk_mul_f32 v[80:81], v[80:81], v[96:97] op_sel_hi:[1,0]
	v_pk_mul_f32 v[82:83], v[82:83], v[96:97] op_sel_hi:[1,0]
	v_pk_mul_f32 v[84:85], v[84:85], v[96:97] op_sel_hi:[1,0]
	v_pk_mul_f32 v[86:87], v[86:87], v[96:97] op_sel_hi:[1,0]
	v_pk_mul_f32 v[88:89], v[88:89], v[96:97] op_sel_hi:[1,0]
	v_pk_mul_f32 v[90:91], v[90:91], v[96:97] op_sel_hi:[1,0]
	v_pk_mul_f32 v[92:93], v[92:93], v[96:97] op_sel_hi:[1,0]
	v_pk_mul_f32 v[94:95], v[94:95], v[96:97] op_sel_hi:[1,0]
	v_pk_mul_f32 v[80:81], v[80:81], v[80:81]
	v_pk_mul_f32 v[82:83], v[82:83], v[82:83]
	v_pk_mul_f32 v[84:85], v[84:85], v[84:85]
	v_pk_mul_f32 v[86:87], v[86:87], v[86:87]
	v_pk_mul_f32 v[88:89], v[88:89], v[88:89]
	v_pk_mul_f32 v[90:91], v[90:91], v[90:91]
	v_pk_mul_f32 v[92:93], v[92:93], v[92:93]
	v_pk_mul_f32 v[94:95], v[94:95], v[94:95]
	v_cvt_pk_bf16_f32 v80, v80, v81
	v_cvt_pk_bf16_f32 v81, v84, v85
	v_cvt_pk_bf16_f32 v82, v82, v83
	v_cvt_pk_bf16_f32 v83, v86, v87
	v_cvt_pk_bf16_f32 v84, v88, v89
	v_cvt_pk_bf16_f32 v85, v92, v93
	v_cvt_pk_bf16_f32 v86, v90, v91
	v_cvt_pk_bf16_f32 v87, v94, v95
	global_store_dwordx4 v[98:99], v[80:83], off
	s_nop 0
	global_store_dwordx4 v[98:99], v[84:87], off offset:256
	global_load_dwordx4 v[80:83], v[100:101], off
	s_nop 0
	global_load_dwordx4 v[84:87], v[100:101], off offset:16
	global_load_dwordx4 v[88:91], v[100:101], off offset:32
	global_load_dwordx4 v[92:95], v[100:101], off offset:48
	v_max_f32_e32 v98, v69, v69
	v_max_f32_e32 v99, v65, v65
	v_max_f32_e32 v65, 0, v77
	v_max_f32_e32 v69, 0, v79
	v_max_f32_e32 v77, 0, v71
	v_max_f32_e32 v79, 0, v67
	v_max_f32_e32 v96, v68, v68
	v_max_f32_e32 v97, v64, v64
	v_max_f32_e32 v100, v70, v70
	v_max_f32_e32 v101, v66, v66
	v_max_f32_e32 v64, 0, v76
	v_max_f32_e32 v66, 0, v72
	v_max_f32_e32 v67, 0, v73
	v_max_f32_e32 v68, 0, v78
	v_max_f32_e32 v70, 0, v74
	v_max_f32_e32 v71, 0, v75
	v_max_f32_e32 v72, 0, v96
	v_max_f32_e32 v74, 0, v97
	v_max_f32_e32 v73, 0, v98
	v_max_f32_e32 v75, 0, v99
	v_max_f32_e32 v76, 0, v100
	v_max_f32_e32 v78, 0, v101
	v_add_u32_e32 v96, 0x80, v144
	v_lshlrev_b64 v[98:99], 13, v[114:115]
	v_ashrrev_i32_e32 v97, 31, v96
	v_lshlrev_b64 v[100:101], 6, v[96:97]
	s_waitcnt vmcnt(0) lgkmcnt(0)
; DI u32x4 pack_v8(f32x4 v0, f32x4 v1) { u32x4 w; w.x = pk2(v0[0], v0[1]); w.y = pk2(v0[2], v0[3]); w.z = pk2(v1[0], v1[1]); w.w = pk2(v1[2], v1[3]); return w; }
; DI float rstd16(const float* ssq, int row) { const f32x4* p = (const f32x4*)(ssq + (size_t)row * 16); const f32x4 a = p[0], b = p[1], c = p[2], d = p[3];
;   return __builtin_amdgcn_rsqf((((a[0] + a[1]) + (a[2] + a[3])) + ((b[0] + b[1]) + (b[2] + b[3])) + ((c[0] + c[1]) + (c[2] + c[3])) + ((d[0] + d[1]) + (d[2] + d[3]))) * (1.0f / 1024.0f) + EPS); }
;   DI void operator()(AccRef acc, const Unit& u, int wr, int wc, int fr, int fq) const {
;     ...
;       for (int m = 0; m < 4; ++m) { const int row = rowb + ai * 128 + m * 16; const float rs = rstd16(SSQH, row);
; #pragma unroll
;         for (int bj = 0; bj < 2; ++bj) { f32x4 v0 = acc[ai][bj][m][0], v1 = acc[ai][bj][m][1];
; #pragma unroll
;           for (int j = 0; j < 4; ++j) { const float a = fmaxf(v0[j], 0.f) * rs, b = fmaxf(v1[j], 0.f) * rs; v0[j] = a * a; v1[j] = b * b; }
;           *(u32x4*)(A2 + (size_t)row * DFF + cb + bj * 128) = pack_v8(v0, v1); } }
	v_mov_b32_e32 v102, v81
	v_mov_b32_e32 v103, v82
	v_mov_b32_e32 v81, v83
	v_mov_b32_e32 v82, v85
	v_mov_b32_e32 v83, v86
	v_mov_b32_e32 v85, v87
	v_pk_add_f32 v[80:81], v[102:103], v[80:81]
	v_pk_add_f32 v[82:83], v[82:83], v[84:85]
	v_pk_add_f32 v[80:81], v[80:81], v[80:81] op_sel:[0,1] op_sel_hi:[1,0]
	v_pk_add_f32 v[82:83], v[82:83], v[82:83] op_sel:[0,1] op_sel_hi:[1,0]
	v_add_f32_e32 v86, v88, v89
	v_add_f32_e32 v88, v90, v91
	v_mov_b32_e32 v87, v94
	v_mov_b32_e32 v89, v95
	v_mov_b32_e32 v81, v92
	v_mov_b32_e32 v83, v93
	v_pk_add_f32 v[84:85], v[86:87], v[88:89]
	v_pk_add_f32 v[80:81], v[80:81], v[82:83]
	v_lshl_add_u64 v[82:83], s[50:51], 0, v[98:99]
	v_pk_add_f32 v[80:81], v[80:81], v[84:85]
	v_lshl_add_u64 v[82:83], v[82:83], 0, v[112:113]
	v_add_f32_e32 v80, v80, v81
	v_fmamk_f32 v80, v80, 0x3a800000, v150
	v_rsq_f32_e32 v80, v80
	v_lshl_add_u64 v[84:85], s[58:59], 0, v[100:101]
	v_pk_mul_f32 v[64:65], v[64:65], v[80:81] op_sel_hi:[1,0]
	v_pk_mul_f32 v[66:67], v[66:67], v[80:81] op_sel_hi:[1,0]
	v_pk_mul_f32 v[68:69], v[68:69], v[80:81] op_sel_hi:[1,0]
	v_pk_mul_f32 v[70:71], v[70:71], v[80:81] op_sel_hi:[1,0]
	v_pk_mul_f32 v[72:73], v[72:73], v[80:81] op_sel_hi:[1,0]
	v_pk_mul_f32 v[74:75], v[74:75], v[80:81] op_sel_hi:[1,0]
	v_pk_mul_f32 v[76:77], v[76:77], v[80:81] op_sel_hi:[1,0]
	v_pk_mul_f32 v[78:79], v[78:79], v[80:81] op_sel_hi:[1,0]
	v_pk_mul_f32 v[64:65], v[64:65], v[64:65]
	v_pk_mul_f32 v[66:67], v[66:67], v[66:67]
	v_pk_mul_f32 v[68:69], v[68:69], v[68:69]
	v_pk_mul_f32 v[70:71], v[70:71], v[70:71]
	v_pk_mul_f32 v[72:73], v[72:73], v[72:73]
	v_pk_mul_f32 v[74:75], v[74:75], v[74:75]
	v_pk_mul_f32 v[76:77], v[76:77], v[76:77]
	v_pk_mul_f32 v[78:79], v[78:79], v[78:79]
	v_cvt_pk_bf16_f32 v64, v64, v65
	v_cvt_pk_bf16_f32 v65, v68, v69
	v_cvt_pk_bf16_f32 v66, v66, v67
	v_cvt_pk_bf16_f32 v67, v70, v71
	v_cvt_pk_bf16_f32 v68, v72, v73
	v_cvt_pk_bf16_f32 v69, v76, v77
	v_cvt_pk_bf16_f32 v70, v74, v75
	v_cvt_pk_bf16_f32 v71, v78, v79
	global_store_dwordx4 v[82:83], v[64:67], off
	s_nop 0
	global_store_dwordx4 v[82:83], v[68:71], off offset:256
	global_load_dwordx4 v[64:67], v[84:85], off
	s_nop 0
	global_load_dwordx4 v[68:71], v[84:85], off offset:16
	global_load_dwordx4 v[72:75], v[84:85], off offset:32
	global_load_dwordx4 v[76:79], v[84:85], off offset:48
	v_max_f32_e32 v82, v53, v53
	v_max_f32_e32 v83, v49, v49
	v_max_f32_e32 v49, 0, v61
	v_max_f32_e32 v53, 0, v63
	v_max_f32_e32 v61, 0, v55
	v_max_f32_e32 v63, 0, v51
	v_max_f32_e32 v80, v52, v52
	v_max_f32_e32 v81, v48, v48
	v_max_f32_e32 v84, v54, v54
	v_max_f32_e32 v85, v50, v50
	v_max_f32_e32 v48, 0, v60
	v_max_f32_e32 v50, 0, v56
	v_max_f32_e32 v51, 0, v57
	v_max_f32_e32 v52, 0, v62
	v_max_f32_e32 v54, 0, v58
	v_max_f32_e32 v55, 0, v59
	v_max_f32_e32 v56, 0, v80
	v_max_f32_e32 v58, 0, v81
	v_max_f32_e32 v57, 0, v82
	v_max_f32_e32 v59, 0, v83
	v_max_f32_e32 v60, 0, v84
	v_max_f32_e32 v62, 0, v85
	v_add_u32_e32 v80, 0x90, v144
	v_lshlrev_b64 v[82:83], 13, v[96:97]
	v_ashrrev_i32_e32 v81, 31, v80
	v_lshlrev_b64 v[84:85], 6, v[80:81]
	s_waitcnt vmcnt(0) lgkmcnt(0)
	v_mov_b32_e32 v86, v65
	v_mov_b32_e32 v87, v66
	v_mov_b32_e32 v65, v67
	v_mov_b32_e32 v66, v69
	v_mov_b32_e32 v67, v70
	v_mov_b32_e32 v69, v71
	v_pk_add_f32 v[64:65], v[86:87], v[64:65]
	v_pk_add_f32 v[66:67], v[66:67], v[68:69]
	v_pk_add_f32 v[64:65], v[64:65], v[64:65] op_sel:[0,1] op_sel_hi:[1,0]
	v_pk_add_f32 v[66:67], v[66:67], v[66:67] op_sel:[0,1] op_sel_hi:[1,0]
	v_add_f32_e32 v70, v72, v73
	v_add_f32_e32 v72, v74, v75
	v_mov_b32_e32 v71, v78
	v_mov_b32_e32 v73, v79
	v_mov_b32_e32 v65, v76
	v_mov_b32_e32 v67, v77
	v_pk_add_f32 v[68:69], v[70:71], v[72:73]
	v_pk_add_f32 v[64:65], v[64:65], v[66:67]
	v_lshl_add_u64 v[66:67], s[50:51], 0, v[82:83]
	v_pk_add_f32 v[64:65], v[64:65], v[68:69]
	v_lshl_add_u64 v[66:67], v[66:67], 0, v[112:113]
	v_add_f32_e32 v64, v64, v65
	v_fmamk_f32 v64, v64, 0x3a800000, v150
	v_rsq_f32_e32 v64, v64
	v_lshl_add_u64 v[68:69], s[58:59], 0, v[84:85]
	v_pk_mul_f32 v[48:49], v[48:49], v[64:65] op_sel_hi:[1,0]
	v_pk_mul_f32 v[50:51], v[50:51], v[64:65] op_sel_hi:[1,0]
	v_pk_mul_f32 v[52:53], v[52:53], v[64:65] op_sel_hi:[1,0]
	v_pk_mul_f32 v[54:55], v[54:55], v[64:65] op_sel_hi:[1,0]
	v_pk_mul_f32 v[56:57], v[56:57], v[64:65] op_sel_hi:[1,0]
	v_pk_mul_f32 v[58:59], v[58:59], v[64:65] op_sel_hi:[1,0]
	v_pk_mul_f32 v[60:61], v[60:61], v[64:65] op_sel_hi:[1,0]
	v_pk_mul_f32 v[62:63], v[62:63], v[64:65] op_sel_hi:[1,0]
	v_pk_mul_f32 v[48:49], v[48:49], v[48:49]
	v_pk_mul_f32 v[50:51], v[50:51], v[50:51]
	v_pk_mul_f32 v[52:53], v[52:53], v[52:53]
	v_pk_mul_f32 v[54:55], v[54:55], v[54:55]
	v_pk_mul_f32 v[56:57], v[56:57], v[56:57]
	v_pk_mul_f32 v[58:59], v[58:59], v[58:59]
	v_pk_mul_f32 v[60:61], v[60:61], v[60:61]
	v_pk_mul_f32 v[62:63], v[62:63], v[62:63]
	v_cvt_pk_bf16_f32 v48, v48, v49
	v_cvt_pk_bf16_f32 v49, v52, v53
	v_cvt_pk_bf16_f32 v50, v50, v51
	v_cvt_pk_bf16_f32 v51, v54, v55
	v_cvt_pk_bf16_f32 v52, v56, v57
	v_cvt_pk_bf16_f32 v53, v60, v61
	v_cvt_pk_bf16_f32 v54, v58, v59
	v_cvt_pk_bf16_f32 v55, v62, v63
	global_store_dwordx4 v[66:67], v[48:51], off
	s_nop 0
	global_store_dwordx4 v[66:67], v[52:55], off offset:256
	global_load_dwordx4 v[48:51], v[68:69], off
	s_nop 0
	global_load_dwordx4 v[52:55], v[68:69], off offset:16
	global_load_dwordx4 v[56:59], v[68:69], off offset:32
	global_load_dwordx4 v[60:63], v[68:69], off offset:48
	v_max_f32_e32 v66, v37, v37
	v_max_f32_e32 v67, v33, v33
	v_max_f32_e32 v33, 0, v45
	v_max_f32_e32 v37, 0, v47
	v_max_f32_e32 v45, 0, v39
	v_max_f32_e32 v47, 0, v35
	v_max_f32_e32 v64, v36, v36
	v_max_f32_e32 v65, v32, v32
	v_max_f32_e32 v68, v38, v38
	v_max_f32_e32 v69, v34, v34
	v_max_f32_e32 v32, 0, v44
	v_max_f32_e32 v34, 0, v40
	v_max_f32_e32 v35, 0, v41
	v_max_f32_e32 v36, 0, v46
	v_max_f32_e32 v38, 0, v42
	v_max_f32_e32 v39, 0, v43
	v_max_f32_e32 v40, 0, v64
	v_max_f32_e32 v42, 0, v65
	v_max_f32_e32 v41, 0, v66
	v_max_f32_e32 v43, 0, v67
	v_max_f32_e32 v44, 0, v68
	v_max_f32_e32 v46, 0, v69
	v_add_u32_e32 v64, 0xa0, v144
	v_lshlrev_b64 v[66:67], 13, v[80:81]
	v_ashrrev_i32_e32 v65, 31, v64
	v_lshlrev_b64 v[68:69], 6, v[64:65]
	s_waitcnt vmcnt(0) lgkmcnt(0)
; DI u32x4 pack_v8(f32x4 v0, f32x4 v1) { u32x4 w; w.x = pk2(v0[0], v0[1]); w.y = pk2(v0[2], v0[3]); w.z = pk2(v1[0], v1[1]); w.w = pk2(v1[2], v1[3]); return w; }
; DI float rstd16(const float* ssq, int row) { const f32x4* p = (const f32x4*)(ssq + (size_t)row * 16); const f32x4 a = p[0], b = p[1], c = p[2], d = p[3];
;   return __builtin_amdgcn_rsqf((((a[0] + a[1]) + (a[2] + a[3])) + ((b[0] + b[1]) + (b[2] + b[3])) + ((c[0] + c[1]) + (c[2] + c[3])) + ((d[0] + d[1]) + (d[2] + d[3]))) * (1.0f / 1024.0f) + EPS); }
;   DI void operator()(AccRef acc, const Unit& u, int wr, int wc, int fr, int fq) const {
;     ...
;       for (int m = 0; m < 4; ++m) { const int row = rowb + ai * 128 + m * 16; const float rs = rstd16(SSQH, row);
; #pragma unroll
;         for (int bj = 0; bj < 2; ++bj) { f32x4 v0 = acc[ai][bj][m][0], v1 = acc[ai][bj][m][1];
; #pragma unroll
;           for (int j = 0; j < 4; ++j) { const float a = fmaxf(v0[j], 0.f) * rs, b = fmaxf(v1[j], 0.f) * rs; v0[j] = a * a; v1[j] = b * b; }
;           *(u32x4*)(A2 + (size_t)row * DFF + cb + bj * 128) = pack_v8(v0, v1); } }
	v_mov_b32_e32 v70, v49
	v_mov_b32_e32 v71, v50
	v_mov_b32_e32 v49, v51
	v_mov_b32_e32 v50, v53
	v_mov_b32_e32 v51, v54
	v_mov_b32_e32 v53, v55
	v_pk_add_f32 v[48:49], v[70:71], v[48:49]
	v_pk_add_f32 v[50:51], v[50:51], v[52:53]
	v_pk_add_f32 v[48:49], v[48:49], v[48:49] op_sel:[0,1] op_sel_hi:[1,0]
	v_pk_add_f32 v[50:51], v[50:51], v[50:51] op_sel:[0,1] op_sel_hi:[1,0]
	v_add_f32_e32 v54, v56, v57
	v_add_f32_e32 v56, v58, v59
	v_mov_b32_e32 v55, v62
	v_mov_b32_e32 v57, v63
	v_mov_b32_e32 v49, v60
	v_mov_b32_e32 v51, v61
	v_pk_add_f32 v[52:53], v[54:55], v[56:57]
	v_pk_add_f32 v[48:49], v[48:49], v[50:51]
	v_lshl_add_u64 v[50:51], s[50:51], 0, v[66:67]
	v_pk_add_f32 v[48:49], v[48:49], v[52:53]
	v_lshl_add_u64 v[50:51], v[50:51], 0, v[112:113]
	v_add_f32_e32 v48, v48, v49
	v_fmamk_f32 v48, v48, 0x3a800000, v150
	v_rsq_f32_e32 v48, v48
	v_lshl_add_u64 v[52:53], s[58:59], 0, v[68:69]
	v_pk_mul_f32 v[32:33], v[32:33], v[48:49] op_sel_hi:[1,0]
	v_pk_mul_f32 v[34:35], v[34:35], v[48:49] op_sel_hi:[1,0]
	v_pk_mul_f32 v[36:37], v[36:37], v[48:49] op_sel_hi:[1,0]
	v_pk_mul_f32 v[38:39], v[38:39], v[48:49] op_sel_hi:[1,0]
	v_pk_mul_f32 v[40:41], v[40:41], v[48:49] op_sel_hi:[1,0]
	v_pk_mul_f32 v[42:43], v[42:43], v[48:49] op_sel_hi:[1,0]
	v_pk_mul_f32 v[44:45], v[44:45], v[48:49] op_sel_hi:[1,0]
	v_pk_mul_f32 v[46:47], v[46:47], v[48:49] op_sel_hi:[1,0]
	v_pk_mul_f32 v[32:33], v[32:33], v[32:33]
	v_pk_mul_f32 v[34:35], v[34:35], v[34:35]
	v_pk_mul_f32 v[36:37], v[36:37], v[36:37]
	v_pk_mul_f32 v[38:39], v[38:39], v[38:39]
	v_pk_mul_f32 v[40:41], v[40:41], v[40:41]
	v_pk_mul_f32 v[42:43], v[42:43], v[42:43]
	v_pk_mul_f32 v[44:45], v[44:45], v[44:45]
	v_pk_mul_f32 v[46:47], v[46:47], v[46:47]
	v_cvt_pk_bf16_f32 v32, v32, v33
	v_cvt_pk_bf16_f32 v33, v36, v37
	v_cvt_pk_bf16_f32 v34, v34, v35
	v_cvt_pk_bf16_f32 v35, v38, v39
	v_cvt_pk_bf16_f32 v36, v40, v41
	v_cvt_pk_bf16_f32 v37, v44, v45
	v_cvt_pk_bf16_f32 v38, v42, v43
	v_cvt_pk_bf16_f32 v39, v46, v47
	global_store_dwordx4 v[50:51], v[32:35], off
	s_nop 0
	global_store_dwordx4 v[50:51], v[36:39], off offset:256
	global_load_dwordx4 v[32:35], v[52:53], off
	s_nop 0
	global_load_dwordx4 v[36:39], v[52:53], off offset:16
	global_load_dwordx4 v[40:43], v[52:53], off offset:32
	global_load_dwordx4 v[44:47], v[52:53], off offset:48
	v_max_f32_e32 v50, v21, v21
	v_max_f32_e32 v51, v17, v17
	v_max_f32_e32 v17, 0, v29
	v_max_f32_e32 v21, 0, v31
	v_max_f32_e32 v29, 0, v23
	v_max_f32_e32 v31, 0, v19
	v_max_f32_e32 v48, v20, v20
	v_max_f32_e32 v49, v16, v16
	v_max_f32_e32 v52, v22, v22
	v_max_f32_e32 v53, v18, v18
	v_max_f32_e32 v16, 0, v28
	v_max_f32_e32 v18, 0, v24
	v_max_f32_e32 v19, 0, v25
	v_max_f32_e32 v20, 0, v30
	v_max_f32_e32 v22, 0, v26
	v_max_f32_e32 v23, 0, v27
	v_max_f32_e32 v24, 0, v48
	v_max_f32_e32 v26, 0, v49
	v_max_f32_e32 v25, 0, v50
	v_max_f32_e32 v27, 0, v51
	v_max_f32_e32 v28, 0, v52
	v_max_f32_e32 v30, 0, v53
	v_add_u32_e32 v48, 0xb0, v144
	v_lshlrev_b64 v[50:51], 13, v[64:65]
	v_ashrrev_i32_e32 v49, 31, v48
	v_lshlrev_b64 v[52:53], 6, v[48:49]
	s_waitcnt vmcnt(0) lgkmcnt(0)
; DI float ozero() { float z = 0.f; asm volatile("" : "+v"(z)); return z; }
; DI int otid() { int t = threadIdx.x; asm volatile("" : "+v"(t)); return t; }
; #define PG8_BAR __builtin_amdgcn_s_barrier()
; DI u32x4 pack_v8(f32x4 v0, f32x4 v1) { u32x4 w; w.x = pk2(v0[0], v0[1]); w.y = pk2(v0[2], v0[3]); w.z = pk2(v1[0], v1[1]); w.w = pk2(v1[2], v1[3]); return w; }
; template <class Epi, class Sched>
; DI void gemm_phase(LAS unsigned char* lds, const Gemm g, const Sched& S, const Epi& E) {
;     ...
;     if (wr == 0) PG8_BAR;
;     { const int l2 = otid() & 63; E(acc, cur, wr, wc, l2 & 15, l2 >> 4); }
;     if (!has_next) break;
;     { const float z0 = ozero();
; #pragma unroll
;     for (int a = 0; a < 2; ++a)
; #pragma unroll
;       for (int b = 0; b < 2; ++b)
; #pragma unroll
;         for (int m = 0; m < 4; ++m)
; #pragma unroll
;           for (int n = 0; n < 2; ++n) acc[a][b][m][n] = (f32x4){z0, z0, z0, z0}; }
;     cur = nxt; cA = nA; cB = nB; ++ui;
;     if (wr == 1) PG8_BAR;
;   DI void operator()(AccRef acc, const Unit& u, int wr, int wc, int fr, int fq) const {
;     ...
;       for (int m = 0; m < 4; ++m) { const int row = rowb + ai * 128 + m * 16; const float rs = rstd16(SSQH, row);
; #pragma unroll
;         for (int bj = 0; bj < 2; ++bj) { f32x4 v0 = acc[ai][bj][m][0], v1 = acc[ai][bj][m][1];
; #pragma unroll
;           for (int j = 0; j < 4; ++j) { const float a = fmaxf(v0[j], 0.f) * rs, b = fmaxf(v1[j], 0.f) * rs; v0[j] = a * a; v1[j] = b * b; }
;           *(u32x4*)(A2 + (size_t)row * DFF + cb + bj * 128) = pack_v8(v0, v1); } }
	v_mov_b32_e32 v54, v33
	v_mov_b32_e32 v55, v34
	v_mov_b32_e32 v33, v35
	v_mov_b32_e32 v34, v37
	v_mov_b32_e32 v35, v38
	v_mov_b32_e32 v37, v39
	v_pk_add_f32 v[32:33], v[54:55], v[32:33]
	v_pk_add_f32 v[34:35], v[34:35], v[36:37]
	v_pk_add_f32 v[32:33], v[32:33], v[32:33] op_sel:[0,1] op_sel_hi:[1,0]
	v_pk_add_f32 v[34:35], v[34:35], v[34:35] op_sel:[0,1] op_sel_hi:[1,0]
	v_add_f32_e32 v38, v40, v41
	v_add_f32_e32 v40, v42, v43
	v_mov_b32_e32 v39, v46
	v_mov_b32_e32 v41, v47
	v_mov_b32_e32 v33, v44
	v_mov_b32_e32 v35, v45
	v_pk_add_f32 v[36:37], v[38:39], v[40:41]
	v_pk_add_f32 v[32:33], v[32:33], v[34:35]
	v_lshl_add_u64 v[34:35], s[50:51], 0, v[50:51]
	v_pk_add_f32 v[32:33], v[32:33], v[36:37]
	v_lshl_add_u64 v[34:35], v[34:35], 0, v[112:113]
	v_add_f32_e32 v32, v32, v33
	v_fmamk_f32 v32, v32, 0x3a800000, v150
	v_rsq_f32_e32 v32, v32
	v_lshl_add_u64 v[36:37], s[58:59], 0, v[52:53]
	v_max_f32_e32 v38, v7, v7
	v_max_f32_e32 v39, v3, v3
	v_pk_mul_f32 v[16:17], v[16:17], v[32:33] op_sel_hi:[1,0]
	v_pk_mul_f32 v[18:19], v[18:19], v[32:33] op_sel_hi:[1,0]
	v_pk_mul_f32 v[20:21], v[20:21], v[32:33] op_sel_hi:[1,0]
	v_pk_mul_f32 v[22:23], v[22:23], v[32:33] op_sel_hi:[1,0]
	v_pk_mul_f32 v[24:25], v[24:25], v[32:33] op_sel_hi:[1,0]
	v_pk_mul_f32 v[26:27], v[26:27], v[32:33] op_sel_hi:[1,0]
	v_pk_mul_f32 v[28:29], v[28:29], v[32:33] op_sel_hi:[1,0]
	v_pk_mul_f32 v[30:31], v[30:31], v[32:33] op_sel_hi:[1,0]
	v_pk_mul_f32 v[16:17], v[16:17], v[16:17]
	v_pk_mul_f32 v[18:19], v[18:19], v[18:19]
	v_pk_mul_f32 v[20:21], v[20:21], v[20:21]
	v_pk_mul_f32 v[22:23], v[22:23], v[22:23]
	v_pk_mul_f32 v[24:25], v[24:25], v[24:25]
	v_pk_mul_f32 v[26:27], v[26:27], v[26:27]
	v_pk_mul_f32 v[28:29], v[28:29], v[28:29]
	v_pk_mul_f32 v[30:31], v[30:31], v[30:31]
	v_cvt_pk_bf16_f32 v16, v16, v17
	v_cvt_pk_bf16_f32 v17, v20, v21
	v_cvt_pk_bf16_f32 v18, v18, v19
	v_cvt_pk_bf16_f32 v19, v22, v23
	v_cvt_pk_bf16_f32 v20, v24, v25
	v_cvt_pk_bf16_f32 v21, v28, v29
	v_cvt_pk_bf16_f32 v22, v26, v27
	v_cvt_pk_bf16_f32 v23, v30, v31
	global_store_dwordx4 v[34:35], v[16:19], off
	s_nop 0
	global_store_dwordx4 v[34:35], v[20:23], off offset:256
	global_load_dwordx4 v[16:19], v[36:37], off
	s_nop 0
	global_load_dwordx4 v[20:23], v[36:37], off offset:16
	global_load_dwordx4 v[24:27], v[36:37], off offset:32
	global_load_dwordx4 v[28:31], v[36:37], off offset:48
	v_max_f32_e32 v36, v6, v6
	v_max_f32_e32 v37, v2, v2
	v_max_f32_e32 v2, 0, v8
	v_max_f32_e32 v6, 0, v10
	v_max_f32_e32 v8, 0, v4
	v_max_f32_e32 v10, 0, v0
	v_max_f32_e32 v34, v5, v5
	v_max_f32_e32 v35, v1, v1
	v_max_f32_e32 v0, 0, v12
	v_max_f32_e32 v1, 0, v13
	v_max_f32_e32 v3, 0, v9
	v_max_f32_e32 v4, 0, v14
	v_max_f32_e32 v5, 0, v15
	v_max_f32_e32 v7, 0, v11
	v_max_f32_e32 v9, 0, v34
	v_max_f32_e32 v11, 0, v35
	v_max_f32_e32 v12, 0, v36
	v_max_f32_e32 v14, 0, v37
	v_max_f32_e32 v13, 0, v38
	v_max_f32_e32 v15, 0, v39
	s_waitcnt vmcnt(0) lgkmcnt(0)
	v_mov_b32_e32 v32, v17
	v_mov_b32_e32 v33, v18
	v_mov_b32_e32 v17, v19
	v_mov_b32_e32 v18, v21
	v_mov_b32_e32 v19, v22
	v_mov_b32_e32 v21, v23
	v_pk_add_f32 v[16:17], v[32:33], v[16:17]
	v_pk_add_f32 v[18:19], v[18:19], v[20:21]
	v_pk_add_f32 v[16:17], v[16:17], v[16:17] op_sel:[0,1] op_sel_hi:[1,0]
	v_pk_add_f32 v[18:19], v[18:19], v[18:19] op_sel:[0,1] op_sel_hi:[1,0]
	v_add_f32_e32 v22, v24, v25
	v_add_f32_e32 v24, v26, v27
	v_mov_b32_e32 v23, v30
	v_mov_b32_e32 v25, v31
	v_mov_b32_e32 v17, v28
	v_mov_b32_e32 v19, v29
	v_pk_add_f32 v[20:21], v[22:23], v[24:25]
	v_pk_add_f32 v[16:17], v[16:17], v[18:19]
	v_lshlrev_b64 v[18:19], 13, v[48:49]
	v_pk_add_f32 v[16:17], v[16:17], v[20:21]
	v_lshl_add_u64 v[18:19], s[50:51], 0, v[18:19]
	v_add_f32_e32 v16, v16, v17
	v_fmamk_f32 v16, v16, 0x3a800000, v150
	v_rsq_f32_e32 v16, v16
	v_lshl_add_u64 v[18:19], v[18:19], 0, v[112:113]
	v_pk_mul_f32 v[0:1], v[0:1], v[16:17] op_sel_hi:[1,0]
	v_pk_mul_f32 v[2:3], v[2:3], v[16:17] op_sel_hi:[1,0]
	v_pk_mul_f32 v[4:5], v[4:5], v[16:17] op_sel_hi:[1,0]
	v_pk_mul_f32 v[6:7], v[6:7], v[16:17] op_sel_hi:[1,0]
	v_pk_mul_f32 v[8:9], v[8:9], v[16:17] op_sel_hi:[1,0]
	v_pk_mul_f32 v[10:11], v[10:11], v[16:17] op_sel_hi:[1,0]
	v_pk_mul_f32 v[12:13], v[12:13], v[16:17] op_sel_hi:[1,0]
	v_pk_mul_f32 v[14:15], v[14:15], v[16:17] op_sel_hi:[1,0]
	v_pk_mul_f32 v[0:1], v[0:1], v[0:1]
	v_pk_mul_f32 v[2:3], v[2:3], v[2:3]
	v_pk_mul_f32 v[4:5], v[4:5], v[4:5]
	v_pk_mul_f32 v[6:7], v[6:7], v[6:7]
	v_pk_mul_f32 v[8:9], v[8:9], v[8:9]
	v_pk_mul_f32 v[10:11], v[10:11], v[10:11]
	v_pk_mul_f32 v[12:13], v[12:13], v[12:13]
	v_pk_mul_f32 v[14:15], v[14:15], v[14:15]
	v_cvt_pk_bf16_f32 v0, v0, v1
	v_cvt_pk_bf16_f32 v1, v4, v5
	v_cvt_pk_bf16_f32 v2, v2, v3
	v_cvt_pk_bf16_f32 v3, v6, v7
	v_cvt_pk_bf16_f32 v4, v8, v9
	v_cvt_pk_bf16_f32 v5, v12, v13
	v_cvt_pk_bf16_f32 v6, v10, v11
	v_cvt_pk_bf16_f32 v7, v14, v15
	global_store_dwordx4 v[18:19], v[0:3], off
	global_store_dwordx4 v[18:19], v[4:7], off offset:256
	s_cbranch_vccnz .LBB0_3775
	v_mov_b32_e32 v0, 0
	s_andn2_b64 vcc, exec, s[6:7]
	s_cbranch_vccnz .LBB0_3774
	s_barrier
	s_branch .LBB0_3774
